# phase9 quad epilogue: hoist the 16 final-norm gain loads, one wait, 16 mul+store without per-step vmcnt(0)
# speedup vs baseline: 1.0279x; 1.0279x over previous
.LBB0_1753:
	v_add_u32_e32 v229, v232, v206
	ds_read_b32 v96, v229 offset:64
	ds_read_b128 v[98:101], v232 offset:96
	s_waitcnt vmcnt(23)
	v_dot8_u32_u4 v106, v12, v214, 0
	v_dot8_u32_u4 v107, v13, v215, 0
	v_dot8_u32_u4 v12, v12, v132, 0
	s_waitcnt lgkmcnt(1)
	v_ashrrev_i32_e32 v97, 31, v96
	v_lshlrev_b64 v[96:97], 2, v[96:97]
	v_dot8_u32_u4 v13, v13, v216, 0
	v_dot8_u32_u4 v106, v14, v217, v106
	v_lshl_add_u64 v[102:103], s[38:39], 0, v[96:97]
	v_dot8_u32_u4 v107, v15, v218, v107
	v_dot8_u32_u4 v12, v14, v219, v12
	v_dot8_u32_u4 v13, v15, v220, v13
	s_waitcnt vmcnt(22)
	v_dot8_u32_u4 v14, v0, v221, v106
	v_lshl_add_u64 v[104:105], s[42:43], 0, v[96:97]
	v_lshl_add_u64 v[96:97], s[44:45], 0, v[96:97]
	v_dot8_u32_u4 v126, v1, v222, v107
	v_dot8_u32_u4 v0, v0, v223, v12
	v_dot8_u32_u4 v1, v1, v224, v13
	v_dot8_u32_u4 v127, v2, v225, v14
	s_waitcnt lgkmcnt(0)
	v_lshl_or_b32 v98, v98, 9, v203
	global_load_dword v136, v[102:103], off
	global_load_dword v231, v[104:105], off
	global_load_dword v230, v[96:97], off
	global_load_dwordx4 v[12:15], v98, s[36:37]
	v_lshl_or_b32 v102, v99, 9, v203
	v_lshl_or_b32 v100, v100, 9, v203
	v_lshl_or_b32 v101, v101, 9, v203
	global_load_dwordx4 v[112:115], v98, s[36:37] offset:256
	s_nop 0
	global_load_dwordx4 v[96:99], v102, s[36:37]
	global_load_dwordx4 v[116:119], v102, s[36:37] offset:256
	global_load_dwordx4 v[104:107], v100, s[36:37]
	global_load_dwordx4 v[120:123], v100, s[36:37] offset:256
	global_load_dwordx4 v[108:111], v101, s[36:37]
	s_nop 0
	global_load_dwordx4 v[100:103], v101, s[36:37] offset:256
	v_dot8_u32_u4 v126, v3, v226, v126
	v_dot8_u32_u4 v0, v2, v227, v0
	v_dot8_u32_u4 v1, v3, v228, v1
	s_waitcnt vmcnt(32)
	v_dot8_u32_u4 v3, v4, v132, 0
	v_add_lshl_u32 v2, v126, v127, 4
	v_dot8_u32_u4 v3, v6, v219, v3
	v_add3_u32 v0, v1, v0, v2
	v_dot8_u32_u4 v1, v4, v214, 0
	v_dot8_u32_u4 v2, v5, v215, 0
	v_dot8_u32_u4 v4, v5, v216, 0
	v_dot8_u32_u4 v1, v6, v217, v1
	v_dot8_u32_u4 v2, v7, v218, v2
	v_dot8_u32_u4 v4, v7, v220, v4
	s_waitcnt vmcnt(31)
	v_dot8_u32_u4 v1, v8, v221, v1
	v_dot8_u32_u4 v2, v9, v222, v2
	v_dot8_u32_u4 v3, v8, v223, v3
	v_dot8_u32_u4 v4, v9, v224, v4
	v_dot8_u32_u4 v1, v10, v225, v1
	v_dot8_u32_u4 v2, v11, v226, v2
	v_dot8_u32_u4 v3, v10, v227, v3
	v_dot8_u32_u4 v4, v11, v228, v4
	v_add_u32_dpp v0, v0, v0 quad_perm:[1,0,3,2] row_mask:0xf bank_mask:0xf bound_ctrl:1
	v_add_lshl_u32 v1, v2, v1, 4
	s_waitcnt vmcnt(30)
	v_dot8_u32_u4 v2, v17, v215, 0
	v_add3_u32 v1, v4, v3, v1
	v_add_u32_dpp v0, v0, v0 quad_perm:[2,3,0,1] row_mask:0xf bank_mask:0xf bound_ctrl:1
	v_dot8_u32_u4 v3, v16, v132, 0
	v_add_u32_dpp v1, v1, v1 quad_perm:[1,0,3,2] row_mask:0xf bank_mask:0xf bound_ctrl:1
	v_add_u32_dpp v0, v0, v0 row_half_mirror row_mask:0xf bank_mask:0xf bound_ctrl:1
	v_dot8_u32_u4 v4, v17, v216, 0
	v_add_u32_dpp v1, v1, v1 quad_perm:[2,3,0,1] row_mask:0xf bank_mask:0xf bound_ctrl:1
	v_add_u32_dpp v0, v0, v0 row_mirror row_mask:0xf bank_mask:0xf bound_ctrl:1
	v_cndmask_b32_e64 v0, v233, v0, s[0:1]
	v_add_u32_dpp v1, v1, v1 row_half_mirror row_mask:0xf bank_mask:0xf bound_ctrl:1
	v_dot8_u32_u4 v2, v19, v218, v2
	v_dot8_u32_u4 v3, v18, v219, v3
	v_add_u32_dpp v1, v1, v1 row_mirror row_mask:0xf bank_mask:0xf bound_ctrl:1
	v_cndmask_b32_e64 v0, v0, v1, s[2:3]
	v_dot8_u32_u4 v1, v16, v214, 0
	v_dot8_u32_u4 v4, v19, v220, v4
	v_dot8_u32_u4 v1, v18, v217, v1
	s_waitcnt vmcnt(29)
	v_dot8_u32_u4 v2, v21, v222, v2
	v_dot8_u32_u4 v1, v20, v221, v1
	v_dot8_u32_u4 v3, v20, v223, v3
	v_dot8_u32_u4 v4, v21, v224, v4
	v_dot8_u32_u4 v1, v22, v225, v1
	v_dot8_u32_u4 v2, v23, v226, v2
	v_dot8_u32_u4 v3, v22, v227, v3
	v_dot8_u32_u4 v4, v23, v228, v4
	s_add_i32 s65, s65, 4
	v_add_lshl_u32 v1, v2, v1, 4
	s_waitcnt vmcnt(28)
	v_dot8_u32_u4 v2, v25, v215, 0
	v_add3_u32 v1, v4, v3, v1
	v_dot8_u32_u4 v3, v24, v132, 0
	v_dot8_u32_u4 v4, v25, v216, 0
	v_add_u32_dpp v1, v1, v1 quad_perm:[1,0,3,2] row_mask:0xf bank_mask:0xf bound_ctrl:1
	v_dot8_u32_u4 v2, v27, v218, v2
	v_dot8_u32_u4 v3, v26, v219, v3
	v_add_u32_dpp v1, v1, v1 quad_perm:[2,3,0,1] row_mask:0xf bank_mask:0xf bound_ctrl:1
	v_dot8_u32_u4 v4, v27, v220, v4
	s_waitcnt vmcnt(27)
	v_dot8_u32_u4 v2, v29, v222, v2
	v_add_u32_dpp v1, v1, v1 row_half_mirror row_mask:0xf bank_mask:0xf bound_ctrl:1
	v_dot8_u32_u4 v3, v28, v223, v3
	v_dot8_u32_u4 v4, v29, v224, v4
	v_add_u32_dpp v1, v1, v1 row_mirror row_mask:0xf bank_mask:0xf bound_ctrl:1
	v_cndmask_b32_e64 v0, v0, v1, s[4:5]
	v_dot8_u32_u4 v1, v24, v214, 0
	v_dot8_u32_u4 v2, v31, v226, v2
	v_dot8_u32_u4 v1, v26, v217, v1
	v_dot8_u32_u4 v3, v30, v227, v3
	v_dot8_u32_u4 v1, v28, v221, v1
	v_dot8_u32_u4 v4, v31, v228, v4
	v_dot8_u32_u4 v1, v30, v225, v1
	s_nop 2
	v_add_lshl_u32 v1, v2, v1, 4
	v_add3_u32 v1, v4, v3, v1
	s_nop 1
	v_add_u32_dpp v1, v1, v1 quad_perm:[1,0,3,2] row_mask:0xf bank_mask:0xf bound_ctrl:1
	s_nop 1
	v_add_u32_dpp v1, v1, v1 quad_perm:[2,3,0,1] row_mask:0xf bank_mask:0xf bound_ctrl:1
	s_nop 1
	v_add_u32_dpp v1, v1, v1 row_half_mirror row_mask:0xf bank_mask:0xf bound_ctrl:1
	s_nop 1
	v_add_u32_dpp v1, v1, v1 row_mirror row_mask:0xf bank_mask:0xf bound_ctrl:1
	v_cndmask_b32_e64 v198, v0, v1, s[6:7]
	ds_read_b128 v[0:3], v232 offset:16
	ds_read_b128 v[126:129], v232 offset:4096
	s_waitcnt vmcnt(18)
	v_cvt_scalef32_pk_f32_fp4 v[8:9], v92, 1.0
	s_waitcnt lgkmcnt(1)
	v_lshl_or_b32 v0, v0, 9, v203
	global_load_dwordx4 v[24:27], v0, s[46:47]
	global_load_dwordx4 v[4:7], v0, s[46:47] offset:256
	s_waitcnt lgkmcnt(0)
	v_pk_fma_f32 v[16:17], v[8:9], v[126:127], v[124:125] op_sel_hi:[1,0,1]
	v_cvt_scalef32_pk_f32_fp4 v[8:9], v92, 1.0 op_sel:[1,0,0]
	v_pk_fma_f32 v[18:19], v[8:9], v[126:127], v[130:131] op_sel_hi:[1,0,1]
	v_cvt_scalef32_pk_f32_fp4 v[8:9], v92, 1.0 op_sel:[0,1,0]
	v_pk_fma_f32 v[20:21], v[8:9], v[126:127], v[138:139] op_sel_hi:[1,0,1]
	v_cvt_scalef32_pk_f32_fp4 v[8:9], v92, 1.0 op_sel:[1,1,0]
	v_pk_fma_f32 v[22:23], v[8:9], v[126:127], v[140:141] op_sel_hi:[1,0,1]
	v_cvt_scalef32_pk_f32_fp4 v[8:9], v93, 1.0
	v_pk_fma_f32 v[124:125], v[8:9], v[126:127], v[142:143] op_sel_hi:[1,0,1]
	v_cvt_scalef32_pk_f32_fp4 v[8:9], v93, 1.0 op_sel:[1,0,0]
	v_pk_fma_f32 v[130:131], v[8:9], v[126:127], v[144:145] op_sel_hi:[1,0,1]
	v_cvt_scalef32_pk_f32_fp4 v[8:9], v93, 1.0 op_sel:[0,1,0]
	v_pk_fma_f32 v[138:139], v[8:9], v[126:127], v[146:147] op_sel_hi:[1,0,1]
	v_cvt_scalef32_pk_f32_fp4 v[8:9], v93, 1.0 op_sel:[1,1,0]
	v_pk_fma_f32 v[92:93], v[8:9], v[126:127], v[148:149] op_sel_hi:[1,0,1]
	v_cvt_scalef32_pk_f32_fp4 v[8:9], v94, 1.0
	v_pk_fma_f32 v[140:141], v[8:9], v[126:127], v[150:151] op_sel_hi:[1,0,1]
	v_cvt_scalef32_pk_f32_fp4 v[8:9], v94, 1.0 op_sel:[1,0,0]
	v_pk_fma_f32 v[142:143], v[8:9], v[126:127], v[152:153] op_sel_hi:[1,0,1]
	v_cvt_scalef32_pk_f32_fp4 v[8:9], v94, 1.0 op_sel:[0,1,0]
	v_pk_fma_f32 v[144:145], v[8:9], v[126:127], v[154:155] op_sel_hi:[1,0,1]
	v_cvt_scalef32_pk_f32_fp4 v[8:9], v94, 1.0 op_sel:[1,1,0]
	v_pk_fma_f32 v[146:147], v[8:9], v[126:127], v[156:157] op_sel_hi:[1,0,1]
	v_cvt_scalef32_pk_f32_fp4 v[8:9], v95, 1.0
	v_pk_fma_f32 v[148:149], v[8:9], v[126:127], v[158:159] op_sel_hi:[1,0,1]
	v_cvt_scalef32_pk_f32_fp4 v[8:9], v95, 1.0 op_sel:[1,0,0]
	v_pk_fma_f32 v[150:151], v[8:9], v[126:127], v[160:161] op_sel_hi:[1,0,1]
	v_cvt_scalef32_pk_f32_fp4 v[8:9], v95, 1.0 op_sel:[0,1,0]
	v_pk_fma_f32 v[152:153], v[8:9], v[126:127], v[162:163] op_sel_hi:[1,0,1]
	v_cvt_scalef32_pk_f32_fp4 v[8:9], v95, 1.0 op_sel:[1,1,0]
	v_pk_fma_f32 v[94:95], v[8:9], v[126:127], v[164:165] op_sel_hi:[1,0,1]
	s_waitcnt vmcnt(19)
	v_cvt_scalef32_pk_f32_fp4 v[8:9], v88, 1.0
	v_pk_fma_f32 v[154:155], v[8:9], v[126:127], v[166:167] op_sel_hi:[1,0,1]
	v_cvt_scalef32_pk_f32_fp4 v[8:9], v88, 1.0 op_sel:[1,0,0]
	v_pk_fma_f32 v[156:157], v[8:9], v[126:127], v[168:169] op_sel_hi:[1,0,1]
	v_cvt_scalef32_pk_f32_fp4 v[8:9], v88, 1.0 op_sel:[0,1,0]
	v_pk_fma_f32 v[158:159], v[8:9], v[126:127], v[170:171] op_sel_hi:[1,0,1]
	v_cvt_scalef32_pk_f32_fp4 v[8:9], v88, 1.0 op_sel:[1,1,0]
	v_pk_fma_f32 v[160:161], v[8:9], v[126:127], v[172:173] op_sel_hi:[1,0,1]
	v_cvt_scalef32_pk_f32_fp4 v[8:9], v89, 1.0
	v_pk_fma_f32 v[162:163], v[8:9], v[126:127], v[174:175] op_sel_hi:[1,0,1]
	v_cvt_scalef32_pk_f32_fp4 v[8:9], v89, 1.0 op_sel:[1,0,0]
	v_pk_fma_f32 v[164:165], v[8:9], v[126:127], v[176:177] op_sel_hi:[1,0,1]
	v_cvt_scalef32_pk_f32_fp4 v[8:9], v89, 1.0 op_sel:[0,1,0]
	v_pk_fma_f32 v[166:167], v[8:9], v[126:127], v[178:179] op_sel_hi:[1,0,1]
	v_cvt_scalef32_pk_f32_fp4 v[8:9], v89, 1.0 op_sel:[1,1,0]
	v_pk_fma_f32 v[88:89], v[8:9], v[126:127], v[180:181] op_sel_hi:[1,0,1]
	v_cvt_scalef32_pk_f32_fp4 v[8:9], v90, 1.0
	v_pk_fma_f32 v[168:169], v[8:9], v[126:127], v[182:183] op_sel_hi:[1,0,1]
	v_cvt_scalef32_pk_f32_fp4 v[8:9], v90, 1.0 op_sel:[1,0,0]
	v_pk_fma_f32 v[170:171], v[8:9], v[126:127], v[184:185] op_sel_hi:[1,0,1]
	v_cvt_scalef32_pk_f32_fp4 v[8:9], v90, 1.0 op_sel:[0,1,0]
	v_pk_fma_f32 v[172:173], v[8:9], v[126:127], v[186:187] op_sel_hi:[1,0,1]
	v_cvt_scalef32_pk_f32_fp4 v[8:9], v90, 1.0 op_sel:[1,1,0]
	v_pk_fma_f32 v[174:175], v[8:9], v[126:127], v[188:189] op_sel_hi:[1,0,1]
	v_cvt_scalef32_pk_f32_fp4 v[8:9], v91, 1.0
	v_pk_fma_f32 v[176:177], v[8:9], v[126:127], v[190:191] op_sel_hi:[1,0,1]
	v_cvt_scalef32_pk_f32_fp4 v[8:9], v91, 1.0 op_sel:[1,0,0]
	v_pk_fma_f32 v[178:179], v[8:9], v[126:127], v[192:193] op_sel_hi:[1,0,1]
	v_cvt_scalef32_pk_f32_fp4 v[8:9], v91, 1.0 op_sel:[0,1,0]
	v_pk_fma_f32 v[180:181], v[8:9], v[126:127], v[194:195] op_sel_hi:[1,0,1]
	v_cvt_scalef32_pk_f32_fp4 v[8:9], v91, 1.0 op_sel:[1,1,0]
	v_pk_fma_f32 v[90:91], v[8:9], v[126:127], v[196:197] op_sel_hi:[1,0,1]
	v_lshl_or_b32 v0, v1, 9, v203
	global_load_dwordx4 v[28:31], v0, s[46:47]
	global_load_dwordx4 v[8:11], v0, s[46:47] offset:256
	s_waitcnt vmcnt(20)
	v_cvt_scalef32_pk_f32_fp4 v[0:1], v84, 1.0
	v_pk_fma_f32 v[0:1], v[0:1], v[126:127], v[16:17] op_sel:[0,1,0]
	v_cvt_scalef32_pk_f32_fp4 v[16:17], v84, 1.0 op_sel:[1,0,0]
	v_pk_fma_f32 v[182:183], v[16:17], v[126:127], v[18:19] op_sel:[0,1,0]
	v_cvt_scalef32_pk_f32_fp4 v[16:17], v84, 1.0 op_sel:[0,1,0]
	v_pk_fma_f32 v[20:21], v[16:17], v[126:127], v[20:21] op_sel:[0,1,0]
	v_cvt_scalef32_pk_f32_fp4 v[16:17], v84, 1.0 op_sel:[1,1,0]
	v_pk_fma_f32 v[22:23], v[16:17], v[126:127], v[22:23] op_sel:[0,1,0]
	v_cvt_scalef32_pk_f32_fp4 v[16:17], v85, 1.0
	v_pk_fma_f32 v[184:185], v[16:17], v[126:127], v[124:125] op_sel:[0,1,0]
	v_cvt_scalef32_pk_f32_fp4 v[16:17], v85, 1.0 op_sel:[1,0,0]
	v_pk_fma_f32 v[130:131], v[16:17], v[126:127], v[130:131] op_sel:[0,1,0]
	v_cvt_scalef32_pk_f32_fp4 v[16:17], v85, 1.0 op_sel:[0,1,0]
	v_pk_fma_f32 v[138:139], v[16:17], v[126:127], v[138:139] op_sel:[0,1,0]
	v_cvt_scalef32_pk_f32_fp4 v[16:17], v85, 1.0 op_sel:[1,1,0]
	v_pk_fma_f32 v[84:85], v[16:17], v[126:127], v[92:93] op_sel:[0,1,0]
	v_cvt_scalef32_pk_f32_fp4 v[16:17], v86, 1.0
	v_pk_fma_f32 v[92:93], v[16:17], v[126:127], v[140:141] op_sel:[0,1,0]
	v_cvt_scalef32_pk_f32_fp4 v[16:17], v86, 1.0 op_sel:[1,0,0]
	v_pk_fma_f32 v[140:141], v[16:17], v[126:127], v[142:143] op_sel:[0,1,0]
	v_cvt_scalef32_pk_f32_fp4 v[16:17], v86, 1.0 op_sel:[0,1,0]
	v_pk_fma_f32 v[142:143], v[16:17], v[126:127], v[144:145] op_sel:[0,1,0]
	v_cvt_scalef32_pk_f32_fp4 v[16:17], v86, 1.0 op_sel:[1,1,0]
	v_pk_fma_f32 v[144:145], v[16:17], v[126:127], v[146:147] op_sel:[0,1,0]
	v_cvt_scalef32_pk_f32_fp4 v[16:17], v87, 1.0
	v_pk_fma_f32 v[146:147], v[16:17], v[126:127], v[148:149] op_sel:[0,1,0]
	v_cvt_scalef32_pk_f32_fp4 v[16:17], v87, 1.0 op_sel:[1,0,0]
	v_pk_fma_f32 v[148:149], v[16:17], v[126:127], v[150:151] op_sel:[0,1,0]
	v_cvt_scalef32_pk_f32_fp4 v[16:17], v87, 1.0 op_sel:[0,1,0]
	v_pk_fma_f32 v[150:151], v[16:17], v[126:127], v[152:153] op_sel:[0,1,0]
	v_cvt_scalef32_pk_f32_fp4 v[16:17], v87, 1.0 op_sel:[1,1,0]
	v_pk_fma_f32 v[86:87], v[16:17], v[126:127], v[94:95] op_sel:[0,1,0]
	s_waitcnt vmcnt(19)
	v_cvt_scalef32_pk_f32_fp4 v[16:17], v80, 1.0
	v_pk_fma_f32 v[94:95], v[16:17], v[126:127], v[154:155] op_sel:[0,1,0]
	v_cvt_scalef32_pk_f32_fp4 v[16:17], v80, 1.0 op_sel:[1,0,0]
	v_pk_fma_f32 v[152:153], v[16:17], v[126:127], v[156:157] op_sel:[0,1,0]
	v_cvt_scalef32_pk_f32_fp4 v[16:17], v80, 1.0 op_sel:[0,1,0]
	v_pk_fma_f32 v[154:155], v[16:17], v[126:127], v[158:159] op_sel:[0,1,0]
	v_cvt_scalef32_pk_f32_fp4 v[16:17], v80, 1.0 op_sel:[1,1,0]
	v_pk_fma_f32 v[156:157], v[16:17], v[126:127], v[160:161] op_sel:[0,1,0]
	v_cvt_scalef32_pk_f32_fp4 v[16:17], v81, 1.0
	v_pk_fma_f32 v[158:159], v[16:17], v[126:127], v[162:163] op_sel:[0,1,0]
	v_cvt_scalef32_pk_f32_fp4 v[16:17], v81, 1.0 op_sel:[1,0,0]
	v_pk_fma_f32 v[160:161], v[16:17], v[126:127], v[164:165] op_sel:[0,1,0]
	v_cvt_scalef32_pk_f32_fp4 v[16:17], v81, 1.0 op_sel:[0,1,0]
	v_pk_fma_f32 v[162:163], v[16:17], v[126:127], v[166:167] op_sel:[0,1,0]
	v_cvt_scalef32_pk_f32_fp4 v[16:17], v81, 1.0 op_sel:[1,1,0]
	v_pk_fma_f32 v[80:81], v[16:17], v[126:127], v[88:89] op_sel:[0,1,0]
	v_cvt_scalef32_pk_f32_fp4 v[16:17], v82, 1.0
	v_pk_fma_f32 v[88:89], v[16:17], v[126:127], v[168:169] op_sel:[0,1,0]
	v_cvt_scalef32_pk_f32_fp4 v[16:17], v82, 1.0 op_sel:[1,0,0]
	v_pk_fma_f32 v[164:165], v[16:17], v[126:127], v[170:171] op_sel:[0,1,0]
	v_cvt_scalef32_pk_f32_fp4 v[16:17], v82, 1.0 op_sel:[0,1,0]
	v_pk_fma_f32 v[166:167], v[16:17], v[126:127], v[172:173] op_sel:[0,1,0]
	v_cvt_scalef32_pk_f32_fp4 v[16:17], v82, 1.0 op_sel:[1,1,0]
	v_pk_fma_f32 v[168:169], v[16:17], v[126:127], v[174:175] op_sel:[0,1,0]
	v_cvt_scalef32_pk_f32_fp4 v[16:17], v83, 1.0
	v_pk_fma_f32 v[170:171], v[16:17], v[126:127], v[176:177] op_sel:[0,1,0]
	v_cvt_scalef32_pk_f32_fp4 v[16:17], v83, 1.0 op_sel:[1,0,0]
	v_pk_fma_f32 v[172:173], v[16:17], v[126:127], v[178:179] op_sel:[0,1,0]
	v_cvt_scalef32_pk_f32_fp4 v[16:17], v83, 1.0 op_sel:[0,1,0]
	v_pk_fma_f32 v[174:175], v[16:17], v[126:127], v[180:181] op_sel:[0,1,0]
	v_cvt_scalef32_pk_f32_fp4 v[16:17], v83, 1.0 op_sel:[1,1,0]
	v_pk_fma_f32 v[82:83], v[16:17], v[126:127], v[90:91] op_sel:[0,1,0]
	v_lshl_or_b32 v2, v2, 9, v203
	global_load_dwordx4 v[124:127], v2, s[46:47]
	global_load_dwordx4 v[16:19], v2, s[46:47] offset:256
	s_waitcnt vmcnt(20)
	v_cvt_scalef32_pk_f32_fp4 v[90:91], v76, 1.0
	v_pk_fma_f32 v[90:91], v[90:91], v[128:129], v[0:1] op_sel_hi:[1,0,1]
	v_cvt_scalef32_pk_f32_fp4 v[0:1], v76, 1.0 op_sel:[1,0,0]
	v_pk_fma_f32 v[176:177], v[0:1], v[128:129], v[182:183] op_sel_hi:[1,0,1]
	v_cvt_scalef32_pk_f32_fp4 v[0:1], v76, 1.0 op_sel:[0,1,0]
	v_pk_fma_f32 v[178:179], v[0:1], v[128:129], v[20:21] op_sel_hi:[1,0,1]
	v_cvt_scalef32_pk_f32_fp4 v[0:1], v76, 1.0 op_sel:[1,1,0]
	v_pk_fma_f32 v[180:181], v[0:1], v[128:129], v[22:23] op_sel_hi:[1,0,1]
	v_cvt_scalef32_pk_f32_fp4 v[0:1], v77, 1.0
	v_pk_fma_f32 v[182:183], v[0:1], v[128:129], v[184:185] op_sel_hi:[1,0,1]
	v_cvt_scalef32_pk_f32_fp4 v[0:1], v77, 1.0 op_sel:[1,0,0]
	v_pk_fma_f32 v[130:131], v[0:1], v[128:129], v[130:131] op_sel_hi:[1,0,1]
	v_cvt_scalef32_pk_f32_fp4 v[0:1], v77, 1.0 op_sel:[0,1,0]
	v_pk_fma_f32 v[184:185], v[0:1], v[128:129], v[138:139] op_sel_hi:[1,0,1]
	v_cvt_scalef32_pk_f32_fp4 v[0:1], v77, 1.0 op_sel:[1,1,0]
	v_pk_fma_f32 v[76:77], v[0:1], v[128:129], v[84:85] op_sel_hi:[1,0,1]
	v_cvt_scalef32_pk_f32_fp4 v[0:1], v78, 1.0
	v_pk_fma_f32 v[84:85], v[0:1], v[128:129], v[92:93] op_sel_hi:[1,0,1]
	v_cvt_scalef32_pk_f32_fp4 v[0:1], v78, 1.0 op_sel:[1,0,0]
	v_pk_fma_f32 v[186:187], v[0:1], v[128:129], v[140:141] op_sel_hi:[1,0,1]
	v_cvt_scalef32_pk_f32_fp4 v[0:1], v78, 1.0 op_sel:[0,1,0]
	v_pk_fma_f32 v[188:189], v[0:1], v[128:129], v[142:143] op_sel_hi:[1,0,1]
	v_cvt_scalef32_pk_f32_fp4 v[0:1], v78, 1.0 op_sel:[1,1,0]
	v_pk_fma_f32 v[190:191], v[0:1], v[128:129], v[144:145] op_sel_hi:[1,0,1]
	v_cvt_scalef32_pk_f32_fp4 v[0:1], v79, 1.0
	v_pk_fma_f32 v[192:193], v[0:1], v[128:129], v[146:147] op_sel_hi:[1,0,1]
	v_cvt_scalef32_pk_f32_fp4 v[0:1], v79, 1.0 op_sel:[1,0,0]
	v_pk_fma_f32 v[194:195], v[0:1], v[128:129], v[148:149] op_sel_hi:[1,0,1]
	v_cvt_scalef32_pk_f32_fp4 v[0:1], v79, 1.0 op_sel:[0,1,0]
	v_pk_fma_f32 v[196:197], v[0:1], v[128:129], v[150:151] op_sel_hi:[1,0,1]
	v_cvt_scalef32_pk_f32_fp4 v[0:1], v79, 1.0 op_sel:[1,1,0]
	v_pk_fma_f32 v[78:79], v[0:1], v[128:129], v[86:87] op_sel_hi:[1,0,1]
	s_waitcnt vmcnt(19)
	v_cvt_scalef32_pk_f32_fp4 v[0:1], v72, 1.0
	v_pk_fma_f32 v[86:87], v[0:1], v[128:129], v[94:95] op_sel_hi:[1,0,1]
	v_cvt_scalef32_pk_f32_fp4 v[0:1], v72, 1.0 op_sel:[1,0,0]
	v_pk_fma_f32 v[200:201], v[0:1], v[128:129], v[152:153] op_sel_hi:[1,0,1]
	v_cvt_scalef32_pk_f32_fp4 v[0:1], v72, 1.0 op_sel:[0,1,0]
	v_pk_fma_f32 v[234:235], v[0:1], v[128:129], v[154:155] op_sel_hi:[1,0,1]
	v_cvt_scalef32_pk_f32_fp4 v[0:1], v72, 1.0 op_sel:[1,1,0]
	v_pk_fma_f32 v[236:237], v[0:1], v[128:129], v[156:157] op_sel_hi:[1,0,1]
	v_cvt_scalef32_pk_f32_fp4 v[0:1], v73, 1.0
	v_pk_fma_f32 v[238:239], v[0:1], v[128:129], v[158:159] op_sel_hi:[1,0,1]
	v_cvt_scalef32_pk_f32_fp4 v[0:1], v73, 1.0 op_sel:[1,0,0]
	v_pk_fma_f32 v[240:241], v[0:1], v[128:129], v[160:161] op_sel_hi:[1,0,1]
	v_cvt_scalef32_pk_f32_fp4 v[0:1], v73, 1.0 op_sel:[0,1,0]
	v_pk_fma_f32 v[242:243], v[0:1], v[128:129], v[162:163] op_sel_hi:[1,0,1]
	v_cvt_scalef32_pk_f32_fp4 v[0:1], v73, 1.0 op_sel:[1,1,0]
	v_pk_fma_f32 v[72:73], v[0:1], v[128:129], v[80:81] op_sel_hi:[1,0,1]
	v_cvt_scalef32_pk_f32_fp4 v[0:1], v74, 1.0
	v_pk_fma_f32 v[80:81], v[0:1], v[128:129], v[88:89] op_sel_hi:[1,0,1]
	v_cvt_scalef32_pk_f32_fp4 v[0:1], v74, 1.0 op_sel:[1,0,0]
	v_pk_fma_f32 v[88:89], v[0:1], v[128:129], v[164:165] op_sel_hi:[1,0,1]
	v_cvt_scalef32_pk_f32_fp4 v[0:1], v74, 1.0 op_sel:[0,1,0]
	v_pk_fma_f32 v[244:245], v[0:1], v[128:129], v[166:167] op_sel_hi:[1,0,1]
	v_cvt_scalef32_pk_f32_fp4 v[0:1], v74, 1.0 op_sel:[1,1,0]
	v_pk_fma_f32 v[246:247], v[0:1], v[128:129], v[168:169] op_sel_hi:[1,0,1]
	v_cvt_scalef32_pk_f32_fp4 v[0:1], v75, 1.0
	v_pk_fma_f32 v[248:249], v[0:1], v[128:129], v[170:171] op_sel_hi:[1,0,1]
	v_cvt_scalef32_pk_f32_fp4 v[0:1], v75, 1.0 op_sel:[1,0,0]
	v_pk_fma_f32 v[250:251], v[0:1], v[128:129], v[172:173] op_sel_hi:[1,0,1]
	v_cvt_scalef32_pk_f32_fp4 v[0:1], v75, 1.0 op_sel:[0,1,0]
	v_pk_fma_f32 v[252:253], v[0:1], v[128:129], v[174:175] op_sel_hi:[1,0,1]
	v_cvt_scalef32_pk_f32_fp4 v[0:1], v75, 1.0 op_sel:[1,1,0]
	v_pk_fma_f32 v[74:75], v[0:1], v[128:129], v[82:83] op_sel_hi:[1,0,1]
	v_lshl_or_b32 v0, v3, 9, v203
	global_load_dwordx4 v[20:23], v0, s[46:47]
	s_nop 0
	global_load_dwordx4 v[0:3], v0, s[46:47] offset:256
	v_mov_b32_e32 v82, v129
	s_waitcnt vmcnt(20)
	v_cvt_scalef32_pk_f32_fp4 v[92:93], v68, 1.0
	v_pk_fma_f32 v[92:93], v[92:93], v[82:83], v[90:91] op_sel_hi:[1,0,1]
	v_cvt_scalef32_pk_f32_fp4 v[90:91], v68, 1.0 op_sel:[1,0,0]
	v_pk_fma_f32 v[94:95], v[90:91], v[82:83], v[176:177] op_sel_hi:[1,0,1]
	v_cvt_scalef32_pk_f32_fp4 v[90:91], v68, 1.0 op_sel:[0,1,0]
	v_pk_fma_f32 v[138:139], v[90:91], v[82:83], v[178:179] op_sel_hi:[1,0,1]
	v_cvt_scalef32_pk_f32_fp4 v[90:91], v68, 1.0 op_sel:[1,1,0]
	v_pk_fma_f32 v[140:141], v[90:91], v[82:83], v[180:181] op_sel_hi:[1,0,1]
	v_cvt_scalef32_pk_f32_fp4 v[90:91], v69, 1.0
	v_pk_fma_f32 v[142:143], v[90:91], v[82:83], v[182:183] op_sel_hi:[1,0,1]
	v_cvt_scalef32_pk_f32_fp4 v[90:91], v69, 1.0 op_sel:[1,0,0]
	v_pk_fma_f32 v[144:145], v[90:91], v[82:83], v[130:131] op_sel_hi:[1,0,1]
	v_cvt_scalef32_pk_f32_fp4 v[90:91], v69, 1.0 op_sel:[0,1,0]
	v_cvt_scalef32_pk_f32_fp4 v[68:69], v69, 1.0 op_sel:[1,1,0]
	v_pk_fma_f32 v[148:149], v[68:69], v[82:83], v[76:77] op_sel_hi:[1,0,1]
	v_cvt_scalef32_pk_f32_fp4 v[68:69], v70, 1.0
	v_pk_fma_f32 v[150:151], v[68:69], v[82:83], v[84:85] op_sel_hi:[1,0,1]
	v_cvt_scalef32_pk_f32_fp4 v[68:69], v70, 1.0 op_sel:[1,0,0]
	v_pk_fma_f32 v[152:153], v[68:69], v[82:83], v[186:187] op_sel_hi:[1,0,1]
	v_cvt_scalef32_pk_f32_fp4 v[68:69], v70, 1.0 op_sel:[0,1,0]
	v_pk_fma_f32 v[154:155], v[68:69], v[82:83], v[188:189] op_sel_hi:[1,0,1]
	v_cvt_scalef32_pk_f32_fp4 v[68:69], v70, 1.0 op_sel:[1,1,0]
	v_pk_fma_f32 v[156:157], v[68:69], v[82:83], v[190:191] op_sel_hi:[1,0,1]
	v_cvt_scalef32_pk_f32_fp4 v[68:69], v71, 1.0
	v_pk_fma_f32 v[158:159], v[68:69], v[82:83], v[192:193] op_sel_hi:[1,0,1]
	v_cvt_scalef32_pk_f32_fp4 v[68:69], v71, 1.0 op_sel:[1,0,0]
	v_pk_fma_f32 v[160:161], v[68:69], v[82:83], v[194:195] op_sel_hi:[1,0,1]
	v_cvt_scalef32_pk_f32_fp4 v[68:69], v71, 1.0 op_sel:[0,1,0]
	v_pk_fma_f32 v[162:163], v[68:69], v[82:83], v[196:197] op_sel_hi:[1,0,1]
	v_cvt_scalef32_pk_f32_fp4 v[68:69], v71, 1.0 op_sel:[1,1,0]
	v_pk_fma_f32 v[164:165], v[68:69], v[82:83], v[78:79] op_sel_hi:[1,0,1]
	s_waitcnt vmcnt(19)
	v_cvt_scalef32_pk_f32_fp4 v[68:69], v64, 1.0
	v_pk_fma_f32 v[166:167], v[68:69], v[82:83], v[86:87] op_sel_hi:[1,0,1]
	v_cvt_scalef32_pk_f32_fp4 v[68:69], v64, 1.0 op_sel:[1,0,0]
	v_pk_fma_f32 v[168:169], v[68:69], v[82:83], v[200:201] op_sel_hi:[1,0,1]
	v_cvt_scalef32_pk_f32_fp4 v[68:69], v64, 1.0 op_sel:[0,1,0]
	v_pk_fma_f32 v[170:171], v[68:69], v[82:83], v[234:235] op_sel_hi:[1,0,1]
	v_cvt_scalef32_pk_f32_fp4 v[68:69], v64, 1.0 op_sel:[1,1,0]
	v_pk_fma_f32 v[172:173], v[68:69], v[82:83], v[236:237] op_sel_hi:[1,0,1]
	v_cvt_scalef32_pk_f32_fp4 v[68:69], v65, 1.0
	v_pk_fma_f32 v[174:175], v[68:69], v[82:83], v[238:239] op_sel_hi:[1,0,1]
	v_cvt_scalef32_pk_f32_fp4 v[68:69], v65, 1.0 op_sel:[1,0,0]
	v_pk_fma_f32 v[176:177], v[68:69], v[82:83], v[240:241] op_sel_hi:[1,0,1]
	v_cvt_scalef32_pk_f32_fp4 v[68:69], v65, 1.0 op_sel:[0,1,0]
	v_cvt_scalef32_pk_f32_fp4 v[64:65], v65, 1.0 op_sel:[1,1,0]
	v_pk_fma_f32 v[180:181], v[64:65], v[82:83], v[72:73] op_sel_hi:[1,0,1]
	v_cvt_scalef32_pk_f32_fp4 v[64:65], v66, 1.0
	v_pk_fma_f32 v[182:183], v[64:65], v[82:83], v[80:81] op_sel_hi:[1,0,1]
	v_cvt_scalef32_pk_f32_fp4 v[64:65], v66, 1.0 op_sel:[1,0,0]
	v_pk_fma_f32 v[146:147], v[90:91], v[82:83], v[184:185] op_sel_hi:[1,0,1]
	v_pk_fma_f32 v[184:185], v[64:65], v[82:83], v[88:89] op_sel_hi:[1,0,1]
	v_cvt_scalef32_pk_f32_fp4 v[64:65], v66, 1.0 op_sel:[0,1,0]
	v_pk_fma_f32 v[186:187], v[64:65], v[82:83], v[244:245] op_sel_hi:[1,0,1]
	v_cvt_scalef32_pk_f32_fp4 v[64:65], v66, 1.0 op_sel:[1,1,0]
	v_pk_fma_f32 v[188:189], v[64:65], v[82:83], v[246:247] op_sel_hi:[1,0,1]
	v_cvt_scalef32_pk_f32_fp4 v[64:65], v67, 1.0
	v_pk_fma_f32 v[190:191], v[64:65], v[82:83], v[248:249] op_sel_hi:[1,0,1]
	v_cvt_scalef32_pk_f32_fp4 v[64:65], v67, 1.0 op_sel:[1,0,0]
	v_pk_fma_f32 v[192:193], v[64:65], v[82:83], v[250:251] op_sel_hi:[1,0,1]
	v_cvt_scalef32_pk_f32_fp4 v[64:65], v67, 1.0 op_sel:[0,1,0]
	v_pk_fma_f32 v[194:195], v[64:65], v[82:83], v[252:253] op_sel_hi:[1,0,1]
	v_cvt_scalef32_pk_f32_fp4 v[64:65], v67, 1.0 op_sel:[1,1,0]
	v_pk_fma_f32 v[178:179], v[68:69], v[82:83], v[242:243] op_sel_hi:[1,0,1]
	v_pk_fma_f32 v[196:197], v[64:65], v[82:83], v[74:75] op_sel_hi:[1,0,1]
	ds_read_b128 v[74:77], v232 offset:112
	s_waitcnt vmcnt(26)
	v_dot8_u32_u4 v64, v44, v214, 0
	v_dot8_u32_u4 v65, v45, v215, 0
	v_dot8_u32_u4 v44, v44, v132, 0
	v_dot8_u32_u4 v45, v45, v216, 0
	v_dot8_u32_u4 v64, v46, v217, v64
	v_dot8_u32_u4 v65, v47, v218, v65
	v_dot8_u32_u4 v44, v46, v219, v44
	v_dot8_u32_u4 v45, v47, v220, v45
	s_waitcnt vmcnt(25)
	v_dot8_u32_u4 v46, v32, v221, v64
	s_waitcnt lgkmcnt(0)
	v_lshl_or_b32 v64, v74, 9, v203
	v_lshl_or_b32 v68, v75, 9, v203
	v_lshl_or_b32 v72, v76, 9, v203
	v_lshl_or_b32 v76, v77, 9, v203
	v_dot8_u32_u4 v128, v33, v222, v65
	v_dot8_u32_u4 v32, v32, v223, v44
	v_dot8_u32_u4 v33, v33, v224, v45
	v_dot8_u32_u4 v129, v34, v225, v46
	global_load_dwordx4 v[44:47], v64, s[36:37]
	s_nop 0
	global_load_dwordx4 v[64:67], v64, s[36:37] offset:256
	s_nop 0
	global_load_dwordx4 v[80:83], v68, s[36:37]
	s_nop 0
	global_load_dwordx4 v[68:71], v68, s[36:37] offset:256
	s_nop 0
	global_load_dwordx4 v[84:87], v72, s[36:37]
	s_nop 0
	global_load_dwordx4 v[72:75], v72, s[36:37] offset:256
	s_nop 0
	global_load_dwordx4 v[88:91], v76, s[36:37]
	s_nop 0
	global_load_dwordx4 v[76:79], v76, s[36:37] offset:256
	v_dot8_u32_u4 v128, v35, v226, v128
	v_dot8_u32_u4 v32, v34, v227, v32
	v_dot8_u32_u4 v33, v35, v228, v33
	s_waitcnt vmcnt(32)
	v_dot8_u32_u4 v35, v36, v132, 0
	v_add_lshl_u32 v34, v128, v129, 4
	v_dot8_u32_u4 v35, v38, v219, v35
	v_add3_u32 v32, v33, v32, v34
	v_dot8_u32_u4 v33, v36, v214, 0
	v_dot8_u32_u4 v34, v37, v215, 0
	v_dot8_u32_u4 v36, v37, v216, 0
	v_dot8_u32_u4 v33, v38, v217, v33
	v_dot8_u32_u4 v34, v39, v218, v34
	v_dot8_u32_u4 v36, v39, v220, v36
	s_waitcnt vmcnt(31)
	v_dot8_u32_u4 v33, v40, v221, v33
	v_dot8_u32_u4 v34, v41, v222, v34
	v_dot8_u32_u4 v35, v40, v223, v35
	v_dot8_u32_u4 v36, v41, v224, v36
	v_dot8_u32_u4 v33, v42, v225, v33
	v_dot8_u32_u4 v34, v43, v226, v34
	v_dot8_u32_u4 v35, v42, v227, v35
	v_dot8_u32_u4 v36, v43, v228, v36
	v_add_u32_dpp v32, v32, v32 quad_perm:[1,0,3,2] row_mask:0xf bank_mask:0xf bound_ctrl:1
	v_add_lshl_u32 v33, v34, v33, 4
	s_waitcnt vmcnt(30)
	v_dot8_u32_u4 v34, v49, v215, 0
	v_add3_u32 v33, v36, v35, v33
	v_add_u32_dpp v32, v32, v32 quad_perm:[2,3,0,1] row_mask:0xf bank_mask:0xf bound_ctrl:1
	v_dot8_u32_u4 v35, v48, v132, 0
	v_add_u32_dpp v33, v33, v33 quad_perm:[1,0,3,2] row_mask:0xf bank_mask:0xf bound_ctrl:1
	v_add_u32_dpp v32, v32, v32 row_half_mirror row_mask:0xf bank_mask:0xf bound_ctrl:1
	v_dot8_u32_u4 v36, v49, v216, 0
	v_add_u32_dpp v33, v33, v33 quad_perm:[2,3,0,1] row_mask:0xf bank_mask:0xf bound_ctrl:1
	v_add_u32_dpp v32, v32, v32 row_mirror row_mask:0xf bank_mask:0xf bound_ctrl:1
	v_cndmask_b32_e64 v32, v198, v32, s[8:9]
	v_add_u32_dpp v33, v33, v33 row_half_mirror row_mask:0xf bank_mask:0xf bound_ctrl:1
	v_dot8_u32_u4 v34, v51, v218, v34
	v_dot8_u32_u4 v35, v50, v219, v35
	v_add_u32_dpp v33, v33, v33 row_mirror row_mask:0xf bank_mask:0xf bound_ctrl:1
	v_cndmask_b32_e64 v32, v32, v33, s[10:11]
	v_dot8_u32_u4 v33, v48, v214, 0
	v_dot8_u32_u4 v36, v51, v220, v36
	v_dot8_u32_u4 v33, v50, v217, v33
	s_waitcnt vmcnt(29)
	v_dot8_u32_u4 v34, v53, v222, v34
	v_dot8_u32_u4 v33, v52, v221, v33
	v_dot8_u32_u4 v35, v52, v223, v35
	v_dot8_u32_u4 v36, v53, v224, v36
	v_dot8_u32_u4 v33, v54, v225, v33
	v_dot8_u32_u4 v34, v55, v226, v34
	v_dot8_u32_u4 v35, v54, v227, v35
	v_dot8_u32_u4 v36, v55, v228, v36
	s_nop 0
	v_add_lshl_u32 v33, v34, v33, 4
	s_waitcnt vmcnt(28)
	v_dot8_u32_u4 v34, v57, v215, 0
	v_add3_u32 v33, v36, v35, v33
	v_dot8_u32_u4 v35, v56, v132, 0
	v_dot8_u32_u4 v36, v57, v216, 0
	v_add_u32_dpp v33, v33, v33 quad_perm:[1,0,3,2] row_mask:0xf bank_mask:0xf bound_ctrl:1
	v_dot8_u32_u4 v34, v59, v218, v34
	v_dot8_u32_u4 v35, v58, v219, v35
	v_add_u32_dpp v33, v33, v33 quad_perm:[2,3,0,1] row_mask:0xf bank_mask:0xf bound_ctrl:1
	v_dot8_u32_u4 v36, v59, v220, v36
	s_waitcnt vmcnt(27)
	v_dot8_u32_u4 v34, v61, v222, v34
	v_add_u32_dpp v33, v33, v33 row_half_mirror row_mask:0xf bank_mask:0xf bound_ctrl:1
	v_dot8_u32_u4 v35, v60, v223, v35
	v_dot8_u32_u4 v36, v61, v224, v36
	v_add_u32_dpp v33, v33, v33 row_mirror row_mask:0xf bank_mask:0xf bound_ctrl:1
	v_cndmask_b32_e64 v32, v32, v33, s[12:13]
	v_dot8_u32_u4 v33, v56, v214, 0
	v_dot8_u32_u4 v34, v63, v226, v34
	v_dot8_u32_u4 v33, v58, v217, v33
	v_dot8_u32_u4 v35, v62, v227, v35
	v_dot8_u32_u4 v33, v60, v221, v33
	v_dot8_u32_u4 v36, v63, v228, v36
	v_dot8_u32_u4 v33, v62, v225, v33
	s_nop 2
	v_add_lshl_u32 v33, v34, v33, 4
	v_add3_u32 v33, v36, v35, v33
	s_nop 1
	v_add_u32_dpp v33, v33, v33 quad_perm:[1,0,3,2] row_mask:0xf bank_mask:0xf bound_ctrl:1
	s_nop 1
	v_add_u32_dpp v33, v33, v33 quad_perm:[2,3,0,1] row_mask:0xf bank_mask:0xf bound_ctrl:1
	s_nop 1
	v_add_u32_dpp v33, v33, v33 row_half_mirror row_mask:0xf bank_mask:0xf bound_ctrl:1
	s_nop 1
	v_add_u32_dpp v33, v33, v33 row_mirror row_mask:0xf bank_mask:0xf bound_ctrl:1
	v_cndmask_b32_e64 v233, v32, v33, s[14:15]
	ds_read_b128 v[32:35], v232 offset:32
	ds_read_b128 v[128:131], v232 offset:4112
	s_waitcnt vmcnt(15)
	v_cvt_scalef32_pk_f32_fp4 v[40:41], v24, 1.0
	s_waitcnt lgkmcnt(1)
	v_lshl_or_b32 v32, v32, 9, v203
	global_load_dwordx4 v[56:59], v32, s[46:47]
	global_load_dwordx4 v[36:39], v32, s[46:47] offset:256
	s_waitcnt lgkmcnt(0)
	v_pk_fma_f32 v[48:49], v[40:41], v[128:129], v[92:93] op_sel_hi:[1,0,1]
	v_cvt_scalef32_pk_f32_fp4 v[40:41], v24, 1.0 op_sel:[1,0,0]
	v_pk_fma_f32 v[50:51], v[40:41], v[128:129], v[94:95] op_sel_hi:[1,0,1]
	v_cvt_scalef32_pk_f32_fp4 v[40:41], v24, 1.0 op_sel:[0,1,0]
	v_pk_fma_f32 v[52:53], v[40:41], v[128:129], v[138:139] op_sel_hi:[1,0,1]
	v_cvt_scalef32_pk_f32_fp4 v[40:41], v24, 1.0 op_sel:[1,1,0]
	v_pk_fma_f32 v[54:55], v[40:41], v[128:129], v[140:141] op_sel_hi:[1,0,1]
	v_cvt_scalef32_pk_f32_fp4 v[40:41], v25, 1.0
	v_pk_fma_f32 v[92:93], v[40:41], v[128:129], v[142:143] op_sel_hi:[1,0,1]
	v_cvt_scalef32_pk_f32_fp4 v[40:41], v25, 1.0 op_sel:[1,0,0]
	v_pk_fma_f32 v[94:95], v[40:41], v[128:129], v[144:145] op_sel_hi:[1,0,1]
	v_cvt_scalef32_pk_f32_fp4 v[40:41], v25, 1.0 op_sel:[0,1,0]
	v_pk_fma_f32 v[138:139], v[40:41], v[128:129], v[146:147] op_sel_hi:[1,0,1]
	v_cvt_scalef32_pk_f32_fp4 v[40:41], v26, 1.0
	v_pk_fma_f32 v[140:141], v[40:41], v[128:129], v[150:151] op_sel_hi:[1,0,1]
	v_cvt_scalef32_pk_f32_fp4 v[40:41], v26, 1.0 op_sel:[1,0,0]
	v_pk_fma_f32 v[142:143], v[40:41], v[128:129], v[152:153] op_sel_hi:[1,0,1]
	v_cvt_scalef32_pk_f32_fp4 v[40:41], v26, 1.0 op_sel:[0,1,0]
	v_pk_fma_f32 v[144:145], v[40:41], v[128:129], v[154:155] op_sel_hi:[1,0,1]
	v_cvt_scalef32_pk_f32_fp4 v[40:41], v26, 1.0 op_sel:[1,1,0]
	v_cvt_scalef32_pk_f32_fp4 v[24:25], v25, 1.0 op_sel:[1,1,0]
	v_pk_fma_f32 v[146:147], v[40:41], v[128:129], v[156:157] op_sel_hi:[1,0,1]
	v_cvt_scalef32_pk_f32_fp4 v[40:41], v27, 1.0
	v_pk_fma_f32 v[24:25], v[24:25], v[128:129], v[148:149] op_sel_hi:[1,0,1]
	v_pk_fma_f32 v[148:149], v[40:41], v[128:129], v[158:159] op_sel_hi:[1,0,1]
	v_cvt_scalef32_pk_f32_fp4 v[40:41], v27, 1.0 op_sel:[1,0,0]
	v_pk_fma_f32 v[150:151], v[40:41], v[128:129], v[160:161] op_sel_hi:[1,0,1]
	v_cvt_scalef32_pk_f32_fp4 v[40:41], v27, 1.0 op_sel:[0,1,0]
	v_pk_fma_f32 v[152:153], v[40:41], v[128:129], v[162:163] op_sel_hi:[1,0,1]
	s_waitcnt vmcnt(16)
	v_cvt_scalef32_pk_f32_fp4 v[40:41], v4, 1.0
	v_pk_fma_f32 v[154:155], v[40:41], v[128:129], v[166:167] op_sel_hi:[1,0,1]
	v_cvt_scalef32_pk_f32_fp4 v[40:41], v4, 1.0 op_sel:[1,0,0]
	v_pk_fma_f32 v[156:157], v[40:41], v[128:129], v[168:169] op_sel_hi:[1,0,1]
	v_cvt_scalef32_pk_f32_fp4 v[40:41], v4, 1.0 op_sel:[0,1,0]
	v_pk_fma_f32 v[158:159], v[40:41], v[128:129], v[170:171] op_sel_hi:[1,0,1]
	v_cvt_scalef32_pk_f32_fp4 v[40:41], v4, 1.0 op_sel:[1,1,0]
	v_pk_fma_f32 v[160:161], v[40:41], v[128:129], v[172:173] op_sel_hi:[1,0,1]
	v_cvt_scalef32_pk_f32_fp4 v[40:41], v5, 1.0
	v_cvt_scalef32_pk_f32_fp4 v[26:27], v27, 1.0 op_sel:[1,1,0]
	v_pk_fma_f32 v[162:163], v[40:41], v[128:129], v[174:175] op_sel_hi:[1,0,1]
	v_cvt_scalef32_pk_f32_fp4 v[40:41], v5, 1.0 op_sel:[1,0,0]
	v_pk_fma_f32 v[26:27], v[26:27], v[128:129], v[164:165] op_sel_hi:[1,0,1]
	v_pk_fma_f32 v[164:165], v[40:41], v[128:129], v[176:177] op_sel_hi:[1,0,1]
	v_cvt_scalef32_pk_f32_fp4 v[40:41], v5, 1.0 op_sel:[0,1,0]
	v_pk_fma_f32 v[166:167], v[40:41], v[128:129], v[178:179] op_sel_hi:[1,0,1]
	v_cvt_scalef32_pk_f32_fp4 v[40:41], v6, 1.0
	v_pk_fma_f32 v[168:169], v[40:41], v[128:129], v[182:183] op_sel_hi:[1,0,1]
	v_cvt_scalef32_pk_f32_fp4 v[40:41], v6, 1.0 op_sel:[1,0,0]
	v_pk_fma_f32 v[170:171], v[40:41], v[128:129], v[184:185] op_sel_hi:[1,0,1]
	v_cvt_scalef32_pk_f32_fp4 v[40:41], v6, 1.0 op_sel:[0,1,0]
	v_pk_fma_f32 v[172:173], v[40:41], v[128:129], v[186:187] op_sel_hi:[1,0,1]
	v_cvt_scalef32_pk_f32_fp4 v[40:41], v6, 1.0 op_sel:[1,1,0]
	v_pk_fma_f32 v[174:175], v[40:41], v[128:129], v[188:189] op_sel_hi:[1,0,1]
	v_cvt_scalef32_pk_f32_fp4 v[40:41], v7, 1.0
	v_pk_fma_f32 v[176:177], v[40:41], v[128:129], v[190:191] op_sel_hi:[1,0,1]
	v_cvt_scalef32_pk_f32_fp4 v[40:41], v7, 1.0 op_sel:[1,0,0]
	v_cvt_scalef32_pk_f32_fp4 v[4:5], v5, 1.0 op_sel:[1,1,0]
	v_pk_fma_f32 v[178:179], v[40:41], v[128:129], v[192:193] op_sel_hi:[1,0,1]
	v_cvt_scalef32_pk_f32_fp4 v[40:41], v7, 1.0 op_sel:[0,1,0]
	v_cvt_scalef32_pk_f32_fp4 v[6:7], v7, 1.0 op_sel:[1,1,0]
	v_pk_fma_f32 v[4:5], v[4:5], v[128:129], v[180:181] op_sel_hi:[1,0,1]
	v_pk_fma_f32 v[180:181], v[40:41], v[128:129], v[194:195] op_sel_hi:[1,0,1]
	v_pk_fma_f32 v[6:7], v[6:7], v[128:129], v[196:197] op_sel_hi:[1,0,1]
	v_lshl_or_b32 v32, v33, 9, v203
	global_load_dwordx4 v[60:63], v32, s[46:47]
	global_load_dwordx4 v[40:43], v32, s[46:47] offset:256
	s_waitcnt vmcnt(17)
	v_cvt_scalef32_pk_f32_fp4 v[32:33], v28, 1.0
	v_pk_fma_f32 v[32:33], v[32:33], v[128:129], v[48:49] op_sel:[0,1,0]
	v_cvt_scalef32_pk_f32_fp4 v[48:49], v28, 1.0 op_sel:[1,0,0]
	v_pk_fma_f32 v[182:183], v[48:49], v[128:129], v[50:51] op_sel:[0,1,0]
	v_cvt_scalef32_pk_f32_fp4 v[48:49], v28, 1.0 op_sel:[0,1,0]
	v_pk_fma_f32 v[52:53], v[48:49], v[128:129], v[52:53] op_sel:[0,1,0]
	v_cvt_scalef32_pk_f32_fp4 v[48:49], v28, 1.0 op_sel:[1,1,0]
	v_pk_fma_f32 v[54:55], v[48:49], v[128:129], v[54:55] op_sel:[0,1,0]
	v_cvt_scalef32_pk_f32_fp4 v[48:49], v29, 1.0
	v_pk_fma_f32 v[184:185], v[48:49], v[128:129], v[92:93] op_sel:[0,1,0]
	v_cvt_scalef32_pk_f32_fp4 v[48:49], v29, 1.0 op_sel:[1,0,0]
	v_pk_fma_f32 v[186:187], v[48:49], v[128:129], v[94:95] op_sel:[0,1,0]
	v_cvt_scalef32_pk_f32_fp4 v[48:49], v29, 1.0 op_sel:[0,1,0]
	v_cvt_scalef32_pk_f32_fp4 v[28:29], v29, 1.0 op_sel:[1,1,0]
	v_pk_fma_f32 v[138:139], v[48:49], v[128:129], v[138:139] op_sel:[0,1,0]
	v_pk_fma_f32 v[24:25], v[28:29], v[128:129], v[24:25] op_sel:[0,1,0]
	v_cvt_scalef32_pk_f32_fp4 v[28:29], v30, 1.0
	v_cvt_scalef32_pk_f32_fp4 v[48:49], v30, 1.0 op_sel:[1,0,0]
	v_pk_fma_f32 v[28:29], v[28:29], v[128:129], v[140:141] op_sel:[0,1,0]
	v_pk_fma_f32 v[140:141], v[48:49], v[128:129], v[142:143] op_sel:[0,1,0]
	v_cvt_scalef32_pk_f32_fp4 v[48:49], v30, 1.0 op_sel:[0,1,0]
	v_pk_fma_f32 v[142:143], v[48:49], v[128:129], v[144:145] op_sel:[0,1,0]
	v_cvt_scalef32_pk_f32_fp4 v[48:49], v30, 1.0 op_sel:[1,1,0]
	v_pk_fma_f32 v[144:145], v[48:49], v[128:129], v[146:147] op_sel:[0,1,0]
	v_cvt_scalef32_pk_f32_fp4 v[48:49], v31, 1.0
	v_pk_fma_f32 v[146:147], v[48:49], v[128:129], v[148:149] op_sel:[0,1,0]
	v_cvt_scalef32_pk_f32_fp4 v[48:49], v31, 1.0 op_sel:[1,0,0]
	v_pk_fma_f32 v[148:149], v[48:49], v[128:129], v[150:151] op_sel:[0,1,0]
	v_cvt_scalef32_pk_f32_fp4 v[48:49], v31, 1.0 op_sel:[0,1,0]
	v_pk_fma_f32 v[150:151], v[48:49], v[128:129], v[152:153] op_sel:[0,1,0]
	v_cvt_scalef32_pk_f32_fp4 v[30:31], v31, 1.0 op_sel:[1,1,0]
	s_waitcnt vmcnt(16)
	v_cvt_scalef32_pk_f32_fp4 v[48:49], v8, 1.0 op_sel:[1,0,0]
	v_pk_fma_f32 v[26:27], v[30:31], v[128:129], v[26:27] op_sel:[0,1,0]
	v_cvt_scalef32_pk_f32_fp4 v[30:31], v8, 1.0
	v_pk_fma_f32 v[152:153], v[48:49], v[128:129], v[156:157] op_sel:[0,1,0]
	v_cvt_scalef32_pk_f32_fp4 v[48:49], v8, 1.0 op_sel:[0,1,0]
	v_pk_fma_f32 v[30:31], v[30:31], v[128:129], v[154:155] op_sel:[0,1,0]
	v_pk_fma_f32 v[154:155], v[48:49], v[128:129], v[158:159] op_sel:[0,1,0]
	v_cvt_scalef32_pk_f32_fp4 v[48:49], v8, 1.0 op_sel:[1,1,0]
	v_pk_fma_f32 v[156:157], v[48:49], v[128:129], v[160:161] op_sel:[0,1,0]
	v_cvt_scalef32_pk_f32_fp4 v[48:49], v9, 1.0
	v_pk_fma_f32 v[158:159], v[48:49], v[128:129], v[162:163] op_sel:[0,1,0]
	v_cvt_scalef32_pk_f32_fp4 v[48:49], v9, 1.0 op_sel:[1,0,0]
	v_pk_fma_f32 v[160:161], v[48:49], v[128:129], v[164:165] op_sel:[0,1,0]
	v_cvt_scalef32_pk_f32_fp4 v[48:49], v9, 1.0 op_sel:[0,1,0]
	v_pk_fma_f32 v[162:163], v[48:49], v[128:129], v[166:167] op_sel:[0,1,0]
	v_cvt_scalef32_pk_f32_fp4 v[48:49], v10, 1.0 op_sel:[1,0,0]
	v_cvt_scalef32_pk_f32_fp4 v[8:9], v9, 1.0 op_sel:[1,1,0]
	v_pk_fma_f32 v[164:165], v[48:49], v[128:129], v[170:171] op_sel:[0,1,0]
	v_cvt_scalef32_pk_f32_fp4 v[48:49], v10, 1.0 op_sel:[0,1,0]
	v_pk_fma_f32 v[4:5], v[8:9], v[128:129], v[4:5] op_sel:[0,1,0]
	v_cvt_scalef32_pk_f32_fp4 v[8:9], v10, 1.0
	v_pk_fma_f32 v[166:167], v[48:49], v[128:129], v[172:173] op_sel:[0,1,0]
	v_cvt_scalef32_pk_f32_fp4 v[48:49], v10, 1.0 op_sel:[1,1,0]
	v_pk_fma_f32 v[8:9], v[8:9], v[128:129], v[168:169] op_sel:[0,1,0]
	v_pk_fma_f32 v[168:169], v[48:49], v[128:129], v[174:175] op_sel:[0,1,0]
	v_cvt_scalef32_pk_f32_fp4 v[48:49], v11, 1.0
	v_pk_fma_f32 v[170:171], v[48:49], v[128:129], v[176:177] op_sel:[0,1,0]
	v_cvt_scalef32_pk_f32_fp4 v[48:49], v11, 1.0 op_sel:[1,0,0]
	v_pk_fma_f32 v[172:173], v[48:49], v[128:129], v[178:179] op_sel:[0,1,0]
	v_cvt_scalef32_pk_f32_fp4 v[48:49], v11, 1.0 op_sel:[0,1,0]
	v_cvt_scalef32_pk_f32_fp4 v[10:11], v11, 1.0 op_sel:[1,1,0]
	v_pk_fma_f32 v[174:175], v[48:49], v[128:129], v[180:181] op_sel:[0,1,0]
	v_pk_fma_f32 v[6:7], v[10:11], v[128:129], v[6:7] op_sel:[0,1,0]
	v_lshl_or_b32 v10, v34, 9, v203
	global_load_dwordx4 v[92:95], v10, s[46:47]
	global_load_dwordx4 v[48:51], v10, s[46:47] offset:256
	s_waitcnt vmcnt(17)
	v_cvt_scalef32_pk_f32_fp4 v[10:11], v124, 1.0
	v_pk_fma_f32 v[10:11], v[10:11], v[130:131], v[32:33] op_sel_hi:[1,0,1]
	v_cvt_scalef32_pk_f32_fp4 v[32:33], v124, 1.0 op_sel:[1,0,0]
	v_pk_fma_f32 v[128:129], v[32:33], v[130:131], v[182:183] op_sel_hi:[1,0,1]
	v_cvt_scalef32_pk_f32_fp4 v[32:33], v124, 1.0 op_sel:[0,1,0]
	v_pk_fma_f32 v[176:177], v[32:33], v[130:131], v[52:53] op_sel_hi:[1,0,1]
	v_cvt_scalef32_pk_f32_fp4 v[32:33], v124, 1.0 op_sel:[1,1,0]
	v_pk_fma_f32 v[178:179], v[32:33], v[130:131], v[54:55] op_sel_hi:[1,0,1]
	v_cvt_scalef32_pk_f32_fp4 v[32:33], v125, 1.0
	v_pk_fma_f32 v[180:181], v[32:33], v[130:131], v[184:185] op_sel_hi:[1,0,1]
	v_cvt_scalef32_pk_f32_fp4 v[32:33], v125, 1.0 op_sel:[1,0,0]
	v_pk_fma_f32 v[182:183], v[32:33], v[130:131], v[186:187] op_sel_hi:[1,0,1]
	v_cvt_scalef32_pk_f32_fp4 v[32:33], v125, 1.0 op_sel:[0,1,0]
	v_pk_fma_f32 v[184:185], v[32:33], v[130:131], v[138:139] op_sel_hi:[1,0,1]
	v_cvt_scalef32_pk_f32_fp4 v[32:33], v125, 1.0 op_sel:[1,1,0]
	v_pk_fma_f32 v[24:25], v[32:33], v[130:131], v[24:25] op_sel_hi:[1,0,1]
	v_cvt_scalef32_pk_f32_fp4 v[32:33], v126, 1.0
	v_pk_fma_f32 v[28:29], v[32:33], v[130:131], v[28:29] op_sel_hi:[1,0,1]
	v_cvt_scalef32_pk_f32_fp4 v[32:33], v126, 1.0 op_sel:[1,0,0]
	v_pk_fma_f32 v[124:125], v[32:33], v[130:131], v[140:141] op_sel_hi:[1,0,1]
	v_cvt_scalef32_pk_f32_fp4 v[32:33], v126, 1.0 op_sel:[0,1,0]
	v_pk_fma_f32 v[186:187], v[32:33], v[130:131], v[142:143] op_sel_hi:[1,0,1]
	v_cvt_scalef32_pk_f32_fp4 v[32:33], v126, 1.0 op_sel:[1,1,0]
	v_pk_fma_f32 v[188:189], v[32:33], v[130:131], v[144:145] op_sel_hi:[1,0,1]
	v_cvt_scalef32_pk_f32_fp4 v[32:33], v127, 1.0
	v_pk_fma_f32 v[190:191], v[32:33], v[130:131], v[146:147] op_sel_hi:[1,0,1]
	v_cvt_scalef32_pk_f32_fp4 v[32:33], v127, 1.0 op_sel:[1,0,0]
	v_pk_fma_f32 v[192:193], v[32:33], v[130:131], v[148:149] op_sel_hi:[1,0,1]
	v_cvt_scalef32_pk_f32_fp4 v[32:33], v127, 1.0 op_sel:[0,1,0]
	v_pk_fma_f32 v[194:195], v[32:33], v[130:131], v[150:151] op_sel_hi:[1,0,1]
	v_cvt_scalef32_pk_f32_fp4 v[32:33], v127, 1.0 op_sel:[1,1,0]
	v_pk_fma_f32 v[26:27], v[32:33], v[130:131], v[26:27] op_sel_hi:[1,0,1]
	s_waitcnt vmcnt(16)
	v_cvt_scalef32_pk_f32_fp4 v[32:33], v16, 1.0
	v_pk_fma_f32 v[30:31], v[32:33], v[130:131], v[30:31] op_sel_hi:[1,0,1]
	v_cvt_scalef32_pk_f32_fp4 v[32:33], v16, 1.0 op_sel:[1,0,0]
	v_pk_fma_f32 v[126:127], v[32:33], v[130:131], v[152:153] op_sel_hi:[1,0,1]
	v_cvt_scalef32_pk_f32_fp4 v[32:33], v16, 1.0 op_sel:[0,1,0]
	v_pk_fma_f32 v[196:197], v[32:33], v[130:131], v[154:155] op_sel_hi:[1,0,1]
	v_cvt_scalef32_pk_f32_fp4 v[32:33], v16, 1.0 op_sel:[1,1,0]
	v_pk_fma_f32 v[198:199], v[32:33], v[130:131], v[156:157] op_sel_hi:[1,0,1]
	v_cvt_scalef32_pk_f32_fp4 v[32:33], v17, 1.0
	v_pk_fma_f32 v[200:201], v[32:33], v[130:131], v[158:159] op_sel_hi:[1,0,1]
	v_cvt_scalef32_pk_f32_fp4 v[32:33], v17, 1.0 op_sel:[1,0,0]
	v_pk_fma_f32 v[234:235], v[32:33], v[130:131], v[160:161] op_sel_hi:[1,0,1]
	v_cvt_scalef32_pk_f32_fp4 v[32:33], v17, 1.0 op_sel:[0,1,0]
	v_pk_fma_f32 v[236:237], v[32:33], v[130:131], v[162:163] op_sel_hi:[1,0,1]
	v_cvt_scalef32_pk_f32_fp4 v[32:33], v18, 1.0 op_sel:[0,1,0]
	v_pk_fma_f32 v[238:239], v[32:33], v[130:131], v[166:167] op_sel_hi:[1,0,1]
	v_cvt_scalef32_pk_f32_fp4 v[32:33], v18, 1.0 op_sel:[1,1,0]
	v_cvt_scalef32_pk_f32_fp4 v[16:17], v17, 1.0 op_sel:[1,1,0]
	v_pk_fma_f32 v[240:241], v[32:33], v[130:131], v[168:169] op_sel_hi:[1,0,1]
	v_cvt_scalef32_pk_f32_fp4 v[32:33], v19, 1.0
	v_pk_fma_f32 v[4:5], v[16:17], v[130:131], v[4:5] op_sel_hi:[1,0,1]
	v_cvt_scalef32_pk_f32_fp4 v[16:17], v18, 1.0
	v_pk_fma_f32 v[242:243], v[32:33], v[130:131], v[170:171] op_sel_hi:[1,0,1]
	v_cvt_scalef32_pk_f32_fp4 v[32:33], v19, 1.0 op_sel:[1,0,0]
	v_pk_fma_f32 v[8:9], v[16:17], v[130:131], v[8:9] op_sel_hi:[1,0,1]
	v_cvt_scalef32_pk_f32_fp4 v[16:17], v18, 1.0 op_sel:[1,0,0]
	v_pk_fma_f32 v[244:245], v[32:33], v[130:131], v[172:173] op_sel_hi:[1,0,1]
	v_cvt_scalef32_pk_f32_fp4 v[32:33], v19, 1.0 op_sel:[0,1,0]
	v_cvt_scalef32_pk_f32_fp4 v[18:19], v19, 1.0 op_sel:[1,1,0]
	v_pk_fma_f32 v[16:17], v[16:17], v[130:131], v[164:165] op_sel_hi:[1,0,1]
	v_pk_fma_f32 v[6:7], v[18:19], v[130:131], v[6:7] op_sel_hi:[1,0,1]
	v_pk_fma_f32 v[246:247], v[32:33], v[130:131], v[174:175] op_sel_hi:[1,0,1]
	v_lshl_or_b32 v18, v35, 9, v203
	global_load_dwordx4 v[52:55], v18, s[46:47]
	global_load_dwordx4 v[32:35], v18, s[46:47] offset:256
	v_mov_b32_e32 v18, v131
	s_waitcnt vmcnt(17)
	v_cvt_scalef32_pk_f32_fp4 v[130:131], v20, 1.0
	v_pk_fma_f32 v[138:139], v[130:131], v[18:19], v[10:11] op_sel_hi:[1,0,1]
	v_cvt_scalef32_pk_f32_fp4 v[10:11], v20, 1.0 op_sel:[1,0,0]
	v_pk_fma_f32 v[140:141], v[10:11], v[18:19], v[128:129] op_sel_hi:[1,0,1]
	v_cvt_scalef32_pk_f32_fp4 v[10:11], v20, 1.0 op_sel:[0,1,0]
	v_pk_fma_f32 v[142:143], v[10:11], v[18:19], v[176:177] op_sel_hi:[1,0,1]
	v_cvt_scalef32_pk_f32_fp4 v[10:11], v20, 1.0 op_sel:[1,1,0]
	v_pk_fma_f32 v[144:145], v[10:11], v[18:19], v[178:179] op_sel_hi:[1,0,1]
	v_cvt_scalef32_pk_f32_fp4 v[10:11], v21, 1.0
	v_pk_fma_f32 v[146:147], v[10:11], v[18:19], v[180:181] op_sel_hi:[1,0,1]
	v_cvt_scalef32_pk_f32_fp4 v[10:11], v21, 1.0 op_sel:[1,0,0]
	v_pk_fma_f32 v[148:149], v[10:11], v[18:19], v[182:183] op_sel_hi:[1,0,1]
	v_cvt_scalef32_pk_f32_fp4 v[10:11], v21, 1.0 op_sel:[0,1,0]
	v_pk_fma_f32 v[150:151], v[10:11], v[18:19], v[184:185] op_sel_hi:[1,0,1]
	v_cvt_scalef32_pk_f32_fp4 v[10:11], v21, 1.0 op_sel:[1,1,0]
	v_pk_fma_f32 v[152:153], v[10:11], v[18:19], v[24:25] op_sel_hi:[1,0,1]
	v_cvt_scalef32_pk_f32_fp4 v[10:11], v22, 1.0
	v_pk_fma_f32 v[154:155], v[10:11], v[18:19], v[28:29] op_sel_hi:[1,0,1]
	v_cvt_scalef32_pk_f32_fp4 v[10:11], v22, 1.0 op_sel:[1,0,0]
	v_pk_fma_f32 v[156:157], v[10:11], v[18:19], v[124:125] op_sel_hi:[1,0,1]
	v_cvt_scalef32_pk_f32_fp4 v[10:11], v22, 1.0 op_sel:[0,1,0]
	v_pk_fma_f32 v[158:159], v[10:11], v[18:19], v[186:187] op_sel_hi:[1,0,1]
	v_cvt_scalef32_pk_f32_fp4 v[10:11], v22, 1.0 op_sel:[1,1,0]
	v_pk_fma_f32 v[160:161], v[10:11], v[18:19], v[188:189] op_sel_hi:[1,0,1]
	v_cvt_scalef32_pk_f32_fp4 v[10:11], v23, 1.0
	v_pk_fma_f32 v[162:163], v[10:11], v[18:19], v[190:191] op_sel_hi:[1,0,1]
	v_cvt_scalef32_pk_f32_fp4 v[10:11], v23, 1.0 op_sel:[1,0,0]
	v_pk_fma_f32 v[164:165], v[10:11], v[18:19], v[192:193] op_sel_hi:[1,0,1]
	v_cvt_scalef32_pk_f32_fp4 v[10:11], v23, 1.0 op_sel:[0,1,0]
	v_pk_fma_f32 v[166:167], v[10:11], v[18:19], v[194:195] op_sel_hi:[1,0,1]
	v_cvt_scalef32_pk_f32_fp4 v[10:11], v23, 1.0 op_sel:[1,1,0]
	v_pk_fma_f32 v[168:169], v[10:11], v[18:19], v[26:27] op_sel_hi:[1,0,1]
	s_waitcnt vmcnt(16)
	v_cvt_scalef32_pk_f32_fp4 v[10:11], v0, 1.0
	v_pk_fma_f32 v[170:171], v[10:11], v[18:19], v[30:31] op_sel_hi:[1,0,1]
	v_cvt_scalef32_pk_f32_fp4 v[10:11], v0, 1.0 op_sel:[1,0,0]
	v_pk_fma_f32 v[172:173], v[10:11], v[18:19], v[126:127] op_sel_hi:[1,0,1]
	v_cvt_scalef32_pk_f32_fp4 v[10:11], v0, 1.0 op_sel:[0,1,0]
	v_pk_fma_f32 v[174:175], v[10:11], v[18:19], v[196:197] op_sel_hi:[1,0,1]
	v_cvt_scalef32_pk_f32_fp4 v[10:11], v0, 1.0 op_sel:[1,1,0]
	v_pk_fma_f32 v[176:177], v[10:11], v[18:19], v[198:199] op_sel_hi:[1,0,1]
	v_cvt_scalef32_pk_f32_fp4 v[10:11], v1, 1.0
	v_pk_fma_f32 v[178:179], v[10:11], v[18:19], v[200:201] op_sel_hi:[1,0,1]
	v_cvt_scalef32_pk_f32_fp4 v[10:11], v1, 1.0 op_sel:[1,0,0]
	v_pk_fma_f32 v[180:181], v[10:11], v[18:19], v[234:235] op_sel_hi:[1,0,1]
	v_cvt_scalef32_pk_f32_fp4 v[10:11], v1, 1.0 op_sel:[0,1,0]
	v_cvt_scalef32_pk_f32_fp4 v[0:1], v1, 1.0 op_sel:[1,1,0]
	v_pk_fma_f32 v[184:185], v[0:1], v[18:19], v[4:5] op_sel_hi:[1,0,1]
	v_cvt_scalef32_pk_f32_fp4 v[0:1], v2, 1.0
	v_pk_fma_f32 v[186:187], v[0:1], v[18:19], v[8:9] op_sel_hi:[1,0,1]
	v_cvt_scalef32_pk_f32_fp4 v[0:1], v2, 1.0 op_sel:[1,0,0]
	v_pk_fma_f32 v[188:189], v[0:1], v[18:19], v[16:17] op_sel_hi:[1,0,1]
	v_cvt_scalef32_pk_f32_fp4 v[0:1], v2, 1.0 op_sel:[0,1,0]
	v_pk_fma_f32 v[190:191], v[0:1], v[18:19], v[238:239] op_sel_hi:[1,0,1]
	v_cvt_scalef32_pk_f32_fp4 v[0:1], v2, 1.0 op_sel:[1,1,0]
	v_pk_fma_f32 v[192:193], v[0:1], v[18:19], v[240:241] op_sel_hi:[1,0,1]
	v_cvt_scalef32_pk_f32_fp4 v[0:1], v3, 1.0
	v_pk_fma_f32 v[194:195], v[0:1], v[18:19], v[242:243] op_sel_hi:[1,0,1]
	v_cvt_scalef32_pk_f32_fp4 v[0:1], v3, 1.0 op_sel:[1,0,0]
	v_pk_fma_f32 v[196:197], v[0:1], v[18:19], v[244:245] op_sel_hi:[1,0,1]
	v_cvt_scalef32_pk_f32_fp4 v[0:1], v3, 1.0 op_sel:[0,1,0]
	v_pk_fma_f32 v[182:183], v[10:11], v[18:19], v[236:237] op_sel_hi:[1,0,1]
	v_pk_fma_f32 v[198:199], v[0:1], v[18:19], v[246:247] op_sel_hi:[1,0,1]
	v_cvt_scalef32_pk_f32_fp4 v[0:1], v3, 1.0 op_sel:[1,1,0]
	v_pk_fma_f32 v[200:201], v[0:1], v[18:19], v[6:7] op_sel_hi:[1,0,1]
	s_min_u32 s33, s65, 27
	v_lshl_add_u32 v0, s33, 4, v204
	ds_read_b128 v[22:25], v0 offset:64
	v_dot8_u32_u4 v0, v12, v214, 0
	v_dot8_u32_u4 v1, v13, v215, 0
	v_dot8_u32_u4 v0, v14, v217, v0
	v_dot8_u32_u4 v2, v12, v132, 0
	v_dot8_u32_u4 v3, v13, v216, 0
	v_dot8_u32_u4 v0, v112, v221, v0
	v_dot8_u32_u4 v1, v15, v218, v1
	v_dot8_u32_u4 v2, v14, v219, v2
	v_dot8_u32_u4 v3, v15, v220, v3
	v_dot8_u32_u4 v125, v114, v225, v0
	s_waitcnt lgkmcnt(0)
	v_lshl_or_b32 v0, v22, 9, v203
	v_lshl_or_b32 v8, v23, 9, v203
	v_lshl_or_b32 v20, v24, 9, v203
	v_lshl_or_b32 v28, v25, 9, v203
	v_dot8_u32_u4 v124, v113, v222, v1
	v_dot8_u32_u4 v112, v112, v223, v2
	v_dot8_u32_u4 v113, v113, v224, v3
	global_load_dwordx4 v[12:15], v0, s[36:37]
	s_nop 0
	global_load_dwordx4 v[0:3], v0, s[36:37] offset:256
	s_nop 0
	global_load_dwordx4 v[4:7], v8, s[36:37]
	s_nop 0
	global_load_dwordx4 v[8:11], v8, s[36:37] offset:256
	s_nop 0
	global_load_dwordx4 v[16:19], v20, s[36:37]
	s_nop 0
	global_load_dwordx4 v[20:23], v20, s[36:37] offset:256
	s_nop 0
	global_load_dwordx4 v[24:27], v28, s[36:37]
	s_nop 0
	global_load_dwordx4 v[28:31], v28, s[36:37] offset:256
	v_dot8_u32_u4 v124, v115, v226, v124
	v_dot8_u32_u4 v112, v114, v227, v112
	v_dot8_u32_u4 v113, v115, v228, v113
	s_nop 0
	v_add_lshl_u32 v114, v124, v125, 4
	s_nop 0
	v_add3_u32 v112, v113, v112, v114
	v_dot8_u32_u4 v113, v96, v214, 0
	v_dot8_u32_u4 v114, v97, v215, 0
	v_dot8_u32_u4 v96, v96, v132, 0
	v_dot8_u32_u4 v97, v97, v216, 0
	v_dot8_u32_u4 v113, v98, v217, v113
	v_dot8_u32_u4 v114, v99, v218, v114
	v_dot8_u32_u4 v96, v98, v219, v96
	v_dot8_u32_u4 v97, v99, v220, v97
	v_dot8_u32_u4 v98, v116, v221, v113
	v_dot8_u32_u4 v99, v117, v222, v114
	v_dot8_u32_u4 v96, v116, v223, v96
	v_dot8_u32_u4 v97, v117, v224, v97
	v_dot8_u32_u4 v98, v118, v225, v98
	v_dot8_u32_u4 v99, v119, v226, v99
	v_dot8_u32_u4 v96, v118, v227, v96
	v_dot8_u32_u4 v97, v119, v228, v97
	v_add_u32_dpp v112, v112, v112 quad_perm:[1,0,3,2] row_mask:0xf bank_mask:0xf bound_ctrl:1
	v_add_lshl_u32 v98, v99, v98, 4
	v_dot8_u32_u4 v99, v104, v132, 0
	v_add3_u32 v96, v97, v96, v98
	v_dot8_u32_u4 v97, v104, v214, 0
	v_dot8_u32_u4 v98, v105, v215, 0
	v_dot8_u32_u4 v104, v105, v216, 0
	v_dot8_u32_u4 v97, v106, v217, v97
	v_dot8_u32_u4 v98, v107, v218, v98
	v_dot8_u32_u4 v99, v106, v219, v99
	v_dot8_u32_u4 v104, v107, v220, v104
	v_dot8_u32_u4 v97, v120, v221, v97
	v_dot8_u32_u4 v98, v121, v222, v98
	v_dot8_u32_u4 v99, v120, v223, v99
	v_dot8_u32_u4 v104, v121, v224, v104
	v_dot8_u32_u4 v97, v122, v225, v97
	v_dot8_u32_u4 v98, v123, v226, v98
	v_dot8_u32_u4 v99, v122, v227, v99
	v_dot8_u32_u4 v104, v123, v228, v104
	v_add_u32_dpp v112, v112, v112 quad_perm:[2,3,0,1] row_mask:0xf bank_mask:0xf bound_ctrl:1
	v_add_lshl_u32 v97, v98, v97, 4
	v_add_u32_dpp v96, v96, v96 quad_perm:[1,0,3,2] row_mask:0xf bank_mask:0xf bound_ctrl:1
	v_add3_u32 v97, v104, v99, v97
	v_add_u32_dpp v112, v112, v112 row_half_mirror row_mask:0xf bank_mask:0xf bound_ctrl:1
	v_add_u32_dpp v96, v96, v96 quad_perm:[2,3,0,1] row_mask:0xf bank_mask:0xf bound_ctrl:1
	v_add_u32_dpp v97, v97, v97 quad_perm:[1,0,3,2] row_mask:0xf bank_mask:0xf bound_ctrl:1
	v_add_u32_dpp v112, v112, v112 row_mirror row_mask:0xf bank_mask:0xf bound_ctrl:1
	v_add_u32_dpp v96, v96, v96 row_half_mirror row_mask:0xf bank_mask:0xf bound_ctrl:1
	v_add_u32_dpp v97, v97, v97 quad_perm:[2,3,0,1] row_mask:0xf bank_mask:0xf bound_ctrl:1
	v_cndmask_b32_e64 v112, v233, v112, s[16:17]
	v_add_u32_dpp v96, v96, v96 row_mirror row_mask:0xf bank_mask:0xf bound_ctrl:1
	v_add_u32_dpp v97, v97, v97 row_half_mirror row_mask:0xf bank_mask:0xf bound_ctrl:1
	v_cndmask_b32_e64 v96, v112, v96, s[18:19]
	v_dot8_u32_u4 v98, v109, v215, 0
	v_add_u32_dpp v97, v97, v97 row_mirror row_mask:0xf bank_mask:0xf bound_ctrl:1
	v_cndmask_b32_e64 v96, v96, v97, s[20:21]
	v_dot8_u32_u4 v97, v108, v214, 0
	v_dot8_u32_u4 v99, v108, v132, 0
	v_dot8_u32_u4 v104, v109, v216, 0
	v_dot8_u32_u4 v97, v110, v217, v97
	v_dot8_u32_u4 v98, v111, v218, v98
	v_dot8_u32_u4 v99, v110, v219, v99
	v_dot8_u32_u4 v104, v111, v220, v104
	v_dot8_u32_u4 v97, v100, v221, v97
	v_dot8_u32_u4 v98, v101, v222, v98
	v_dot8_u32_u4 v99, v100, v223, v99
	v_dot8_u32_u4 v100, v101, v224, v104
	v_dot8_u32_u4 v97, v102, v225, v97
	v_dot8_u32_u4 v98, v103, v226, v98
	v_dot8_u32_u4 v99, v102, v227, v99
	v_dot8_u32_u4 v100, v103, v228, v100
	s_nop 0
	v_add_lshl_u32 v97, v98, v97, 4
	s_nop 0
	v_add3_u32 v97, v100, v99, v97
	s_nop 1
	v_add_u32_dpp v97, v97, v97 quad_perm:[1,0,3,2] row_mask:0xf bank_mask:0xf bound_ctrl:1
	s_nop 1
	v_add_u32_dpp v97, v97, v97 quad_perm:[2,3,0,1] row_mask:0xf bank_mask:0xf bound_ctrl:1
	s_nop 1
	v_add_u32_dpp v97, v97, v97 row_half_mirror row_mask:0xf bank_mask:0xf bound_ctrl:1
	s_nop 1
	v_add_u32_dpp v97, v97, v97 row_mirror row_mask:0xf bank_mask:0xf bound_ctrl:1
	v_cndmask_b32_e64 v233, v96, v97, s[22:23]
	ds_read_b128 v[96:99], v232 offset:48
	ds_read_b128 v[128:131], v232 offset:4128
	s_waitcnt vmcnt(15)
	v_cvt_scalef32_pk_f32_fp4 v[104:105], v56, 1.0 op_sel:[0,1,0]
	v_cvt_scalef32_pk_f32_fp4 v[100:101], v56, 1.0
	v_cvt_scalef32_pk_f32_fp4 v[102:103], v56, 1.0 op_sel:[1,0,0]
	s_waitcnt lgkmcnt(1)
	v_lshl_or_b32 v96, v96, 9, v203
	global_load_dwordx4 v[124:127], v96, s[46:47]
	global_load_dwordx4 v[112:115], v96, s[46:47] offset:256
	s_waitcnt lgkmcnt(0)
	v_pk_fma_f32 v[108:109], v[104:105], v[128:129], v[142:143] op_sel_hi:[1,0,1]
	v_cvt_scalef32_pk_f32_fp4 v[104:105], v56, 1.0 op_sel:[1,1,0]
	v_pk_fma_f32 v[110:111], v[104:105], v[128:129], v[144:145] op_sel_hi:[1,0,1]
	v_cvt_scalef32_pk_f32_fp4 v[104:105], v57, 1.0
	v_pk_fma_f32 v[116:117], v[104:105], v[128:129], v[146:147] op_sel_hi:[1,0,1]
	v_cvt_scalef32_pk_f32_fp4 v[104:105], v57, 1.0 op_sel:[1,0,0]
	v_pk_fma_f32 v[118:119], v[104:105], v[128:129], v[148:149] op_sel_hi:[1,0,1]
	v_cvt_scalef32_pk_f32_fp4 v[104:105], v57, 1.0 op_sel:[0,1,0]
	v_pk_fma_f32 v[100:101], v[100:101], v[128:129], v[138:139] op_sel_hi:[1,0,1]
	v_pk_fma_f32 v[138:139], v[104:105], v[128:129], v[150:151] op_sel_hi:[1,0,1]
	v_cvt_scalef32_pk_f32_fp4 v[104:105], v58, 1.0
	v_pk_fma_f32 v[102:103], v[102:103], v[128:129], v[140:141] op_sel_hi:[1,0,1]
	v_pk_fma_f32 v[140:141], v[104:105], v[128:129], v[154:155] op_sel_hi:[1,0,1]
	v_cvt_scalef32_pk_f32_fp4 v[104:105], v58, 1.0 op_sel:[1,0,0]
	v_pk_fma_f32 v[142:143], v[104:105], v[128:129], v[156:157] op_sel_hi:[1,0,1]
	v_cvt_scalef32_pk_f32_fp4 v[104:105], v58, 1.0 op_sel:[0,1,0]
	v_pk_fma_f32 v[144:145], v[104:105], v[128:129], v[158:159] op_sel_hi:[1,0,1]
	v_cvt_scalef32_pk_f32_fp4 v[104:105], v58, 1.0 op_sel:[1,1,0]
	v_pk_fma_f32 v[146:147], v[104:105], v[128:129], v[160:161] op_sel_hi:[1,0,1]
	v_cvt_scalef32_pk_f32_fp4 v[104:105], v59, 1.0
	v_pk_fma_f32 v[148:149], v[104:105], v[128:129], v[162:163] op_sel_hi:[1,0,1]
	v_cvt_scalef32_pk_f32_fp4 v[104:105], v59, 1.0 op_sel:[1,0,0]
	v_cvt_scalef32_pk_f32_fp4 v[56:57], v57, 1.0 op_sel:[1,1,0]
	v_pk_fma_f32 v[150:151], v[104:105], v[128:129], v[164:165] op_sel_hi:[1,0,1]
	v_cvt_scalef32_pk_f32_fp4 v[104:105], v59, 1.0 op_sel:[0,1,0]
	v_pk_fma_f32 v[56:57], v[56:57], v[128:129], v[152:153] op_sel_hi:[1,0,1]
	v_pk_fma_f32 v[152:153], v[104:105], v[128:129], v[166:167] op_sel_hi:[1,0,1]
	s_waitcnt vmcnt(16)
	v_cvt_scalef32_pk_f32_fp4 v[104:105], v36, 1.0
	v_pk_fma_f32 v[154:155], v[104:105], v[128:129], v[170:171] op_sel_hi:[1,0,1]
	v_cvt_scalef32_pk_f32_fp4 v[104:105], v36, 1.0 op_sel:[1,0,0]
	v_pk_fma_f32 v[156:157], v[104:105], v[128:129], v[172:173] op_sel_hi:[1,0,1]
	v_cvt_scalef32_pk_f32_fp4 v[104:105], v36, 1.0 op_sel:[0,1,0]
	v_pk_fma_f32 v[158:159], v[104:105], v[128:129], v[174:175] op_sel_hi:[1,0,1]
	v_cvt_scalef32_pk_f32_fp4 v[104:105], v36, 1.0 op_sel:[1,1,0]
	v_pk_fma_f32 v[160:161], v[104:105], v[128:129], v[176:177] op_sel_hi:[1,0,1]
	v_cvt_scalef32_pk_f32_fp4 v[104:105], v37, 1.0
	v_pk_fma_f32 v[162:163], v[104:105], v[128:129], v[178:179] op_sel_hi:[1,0,1]
	v_cvt_scalef32_pk_f32_fp4 v[104:105], v37, 1.0 op_sel:[1,0,0]
	v_pk_fma_f32 v[164:165], v[104:105], v[128:129], v[180:181] op_sel_hi:[1,0,1]
	v_cvt_scalef32_pk_f32_fp4 v[104:105], v37, 1.0 op_sel:[0,1,0]
	v_cvt_scalef32_pk_f32_fp4 v[58:59], v59, 1.0 op_sel:[1,1,0]
	v_pk_fma_f32 v[166:167], v[104:105], v[128:129], v[182:183] op_sel_hi:[1,0,1]
	v_cvt_scalef32_pk_f32_fp4 v[104:105], v38, 1.0
	v_pk_fma_f32 v[58:59], v[58:59], v[128:129], v[168:169] op_sel_hi:[1,0,1]
	v_pk_fma_f32 v[168:169], v[104:105], v[128:129], v[186:187] op_sel_hi:[1,0,1]
	v_cvt_scalef32_pk_f32_fp4 v[104:105], v38, 1.0 op_sel:[1,0,0]
	v_pk_fma_f32 v[170:171], v[104:105], v[128:129], v[188:189] op_sel_hi:[1,0,1]
	v_cvt_scalef32_pk_f32_fp4 v[104:105], v38, 1.0 op_sel:[0,1,0]
	v_pk_fma_f32 v[172:173], v[104:105], v[128:129], v[190:191] op_sel_hi:[1,0,1]
	v_cvt_scalef32_pk_f32_fp4 v[104:105], v38, 1.0 op_sel:[1,1,0]
	v_pk_fma_f32 v[174:175], v[104:105], v[128:129], v[192:193] op_sel_hi:[1,0,1]
	v_cvt_scalef32_pk_f32_fp4 v[104:105], v39, 1.0
	v_pk_fma_f32 v[176:177], v[104:105], v[128:129], v[194:195] op_sel_hi:[1,0,1]
	v_cvt_scalef32_pk_f32_fp4 v[104:105], v39, 1.0 op_sel:[1,0,0]
	v_cvt_scalef32_pk_f32_fp4 v[36:37], v37, 1.0 op_sel:[1,1,0]
	v_pk_fma_f32 v[178:179], v[104:105], v[128:129], v[196:197] op_sel_hi:[1,0,1]
	v_cvt_scalef32_pk_f32_fp4 v[104:105], v39, 1.0 op_sel:[0,1,0]
	v_cvt_scalef32_pk_f32_fp4 v[38:39], v39, 1.0 op_sel:[1,1,0]
	v_pk_fma_f32 v[36:37], v[36:37], v[128:129], v[184:185] op_sel_hi:[1,0,1]
	v_pk_fma_f32 v[180:181], v[104:105], v[128:129], v[198:199] op_sel_hi:[1,0,1]
	v_pk_fma_f32 v[38:39], v[38:39], v[128:129], v[200:201] op_sel_hi:[1,0,1]
	v_lshl_or_b32 v96, v97, 9, v203
	global_load_dwordx4 v[120:123], v96, s[46:47]
	global_load_dwordx4 v[104:107], v96, s[46:47] offset:256
	s_waitcnt vmcnt(17)
	v_cvt_scalef32_pk_f32_fp4 v[96:97], v60, 1.0
	v_pk_fma_f32 v[96:97], v[96:97], v[128:129], v[100:101] op_sel:[0,1,0]
	v_cvt_scalef32_pk_f32_fp4 v[100:101], v60, 1.0 op_sel:[1,0,0]
	v_pk_fma_f32 v[182:183], v[100:101], v[128:129], v[102:103] op_sel:[0,1,0]
	v_cvt_scalef32_pk_f32_fp4 v[100:101], v60, 1.0 op_sel:[0,1,0]
	v_pk_fma_f32 v[108:109], v[100:101], v[128:129], v[108:109] op_sel:[0,1,0]
	v_cvt_scalef32_pk_f32_fp4 v[100:101], v60, 1.0 op_sel:[1,1,0]
	v_pk_fma_f32 v[110:111], v[100:101], v[128:129], v[110:111] op_sel:[0,1,0]
	v_cvt_scalef32_pk_f32_fp4 v[100:101], v61, 1.0
	v_pk_fma_f32 v[184:185], v[100:101], v[128:129], v[116:117] op_sel:[0,1,0]
	v_cvt_scalef32_pk_f32_fp4 v[100:101], v61, 1.0 op_sel:[1,0,0]
	v_pk_fma_f32 v[186:187], v[100:101], v[128:129], v[118:119] op_sel:[0,1,0]
	v_cvt_scalef32_pk_f32_fp4 v[100:101], v61, 1.0 op_sel:[0,1,0]
	v_cvt_scalef32_pk_f32_fp4 v[60:61], v61, 1.0 op_sel:[1,1,0]
	v_pk_fma_f32 v[138:139], v[100:101], v[128:129], v[138:139] op_sel:[0,1,0]
	v_pk_fma_f32 v[56:57], v[60:61], v[128:129], v[56:57] op_sel:[0,1,0]
	v_cvt_scalef32_pk_f32_fp4 v[60:61], v62, 1.0
	v_cvt_scalef32_pk_f32_fp4 v[100:101], v62, 1.0 op_sel:[1,0,0]
	v_pk_fma_f32 v[60:61], v[60:61], v[128:129], v[140:141] op_sel:[0,1,0]
	v_pk_fma_f32 v[140:141], v[100:101], v[128:129], v[142:143] op_sel:[0,1,0]
	v_cvt_scalef32_pk_f32_fp4 v[100:101], v62, 1.0 op_sel:[0,1,0]
	v_pk_fma_f32 v[142:143], v[100:101], v[128:129], v[144:145] op_sel:[0,1,0]
	v_cvt_scalef32_pk_f32_fp4 v[100:101], v62, 1.0 op_sel:[1,1,0]
	v_pk_fma_f32 v[144:145], v[100:101], v[128:129], v[146:147] op_sel:[0,1,0]
	v_cvt_scalef32_pk_f32_fp4 v[100:101], v63, 1.0
	v_pk_fma_f32 v[146:147], v[100:101], v[128:129], v[148:149] op_sel:[0,1,0]
	v_cvt_scalef32_pk_f32_fp4 v[100:101], v63, 1.0 op_sel:[1,0,0]
	v_pk_fma_f32 v[148:149], v[100:101], v[128:129], v[150:151] op_sel:[0,1,0]
	v_cvt_scalef32_pk_f32_fp4 v[100:101], v63, 1.0 op_sel:[0,1,0]
	v_pk_fma_f32 v[150:151], v[100:101], v[128:129], v[152:153] op_sel:[0,1,0]
	v_cvt_scalef32_pk_f32_fp4 v[62:63], v63, 1.0 op_sel:[1,1,0]
	s_waitcnt vmcnt(16)
	v_cvt_scalef32_pk_f32_fp4 v[100:101], v40, 1.0 op_sel:[1,0,0]
	v_pk_fma_f32 v[58:59], v[62:63], v[128:129], v[58:59] op_sel:[0,1,0]
	v_cvt_scalef32_pk_f32_fp4 v[62:63], v40, 1.0
	v_pk_fma_f32 v[152:153], v[100:101], v[128:129], v[156:157] op_sel:[0,1,0]
	v_cvt_scalef32_pk_f32_fp4 v[100:101], v40, 1.0 op_sel:[0,1,0]
	v_pk_fma_f32 v[62:63], v[62:63], v[128:129], v[154:155] op_sel:[0,1,0]
	v_pk_fma_f32 v[154:155], v[100:101], v[128:129], v[158:159] op_sel:[0,1,0]
	v_cvt_scalef32_pk_f32_fp4 v[100:101], v40, 1.0 op_sel:[1,1,0]
	v_pk_fma_f32 v[156:157], v[100:101], v[128:129], v[160:161] op_sel:[0,1,0]
	v_cvt_scalef32_pk_f32_fp4 v[100:101], v41, 1.0
	v_pk_fma_f32 v[158:159], v[100:101], v[128:129], v[162:163] op_sel:[0,1,0]
	v_cvt_scalef32_pk_f32_fp4 v[100:101], v41, 1.0 op_sel:[1,0,0]
	v_pk_fma_f32 v[160:161], v[100:101], v[128:129], v[164:165] op_sel:[0,1,0]
	v_cvt_scalef32_pk_f32_fp4 v[100:101], v41, 1.0 op_sel:[0,1,0]
	v_pk_fma_f32 v[162:163], v[100:101], v[128:129], v[166:167] op_sel:[0,1,0]
	v_cvt_scalef32_pk_f32_fp4 v[100:101], v42, 1.0 op_sel:[1,0,0]
	v_cvt_scalef32_pk_f32_fp4 v[40:41], v41, 1.0 op_sel:[1,1,0]
	v_pk_fma_f32 v[164:165], v[100:101], v[128:129], v[170:171] op_sel:[0,1,0]
	v_cvt_scalef32_pk_f32_fp4 v[100:101], v42, 1.0 op_sel:[0,1,0]
	v_pk_fma_f32 v[36:37], v[40:41], v[128:129], v[36:37] op_sel:[0,1,0]
	v_cvt_scalef32_pk_f32_fp4 v[40:41], v42, 1.0
	v_pk_fma_f32 v[166:167], v[100:101], v[128:129], v[172:173] op_sel:[0,1,0]
	v_cvt_scalef32_pk_f32_fp4 v[100:101], v42, 1.0 op_sel:[1,1,0]
	v_pk_fma_f32 v[40:41], v[40:41], v[128:129], v[168:169] op_sel:[0,1,0]
	v_pk_fma_f32 v[168:169], v[100:101], v[128:129], v[174:175] op_sel:[0,1,0]
	v_cvt_scalef32_pk_f32_fp4 v[100:101], v43, 1.0
	v_pk_fma_f32 v[170:171], v[100:101], v[128:129], v[176:177] op_sel:[0,1,0]
	v_cvt_scalef32_pk_f32_fp4 v[100:101], v43, 1.0 op_sel:[1,0,0]
	v_pk_fma_f32 v[172:173], v[100:101], v[128:129], v[178:179] op_sel:[0,1,0]
	v_cvt_scalef32_pk_f32_fp4 v[100:101], v43, 1.0 op_sel:[0,1,0]
	v_cvt_scalef32_pk_f32_fp4 v[42:43], v43, 1.0 op_sel:[1,1,0]
	v_pk_fma_f32 v[174:175], v[100:101], v[128:129], v[180:181] op_sel:[0,1,0]
	v_pk_fma_f32 v[38:39], v[42:43], v[128:129], v[38:39] op_sel:[0,1,0]
	v_lshl_or_b32 v42, v98, 9, v203
	global_load_dwordx4 v[116:119], v42, s[46:47]
	global_load_dwordx4 v[100:103], v42, s[46:47] offset:256
	s_waitcnt vmcnt(17)
	v_cvt_scalef32_pk_f32_fp4 v[42:43], v92, 1.0
	v_pk_fma_f32 v[42:43], v[42:43], v[130:131], v[96:97] op_sel_hi:[1,0,1]
	v_cvt_scalef32_pk_f32_fp4 v[96:97], v92, 1.0 op_sel:[1,0,0]
	v_pk_fma_f32 v[128:129], v[96:97], v[130:131], v[182:183] op_sel_hi:[1,0,1]
	v_cvt_scalef32_pk_f32_fp4 v[96:97], v92, 1.0 op_sel:[0,1,0]
	v_pk_fma_f32 v[176:177], v[96:97], v[130:131], v[108:109] op_sel_hi:[1,0,1]
	v_cvt_scalef32_pk_f32_fp4 v[96:97], v92, 1.0 op_sel:[1,1,0]
	v_pk_fma_f32 v[178:179], v[96:97], v[130:131], v[110:111] op_sel_hi:[1,0,1]
	v_cvt_scalef32_pk_f32_fp4 v[96:97], v93, 1.0
	v_pk_fma_f32 v[180:181], v[96:97], v[130:131], v[184:185] op_sel_hi:[1,0,1]
	v_cvt_scalef32_pk_f32_fp4 v[96:97], v93, 1.0 op_sel:[1,0,0]
	v_pk_fma_f32 v[182:183], v[96:97], v[130:131], v[186:187] op_sel_hi:[1,0,1]
	v_cvt_scalef32_pk_f32_fp4 v[96:97], v93, 1.0 op_sel:[0,1,0]
	v_pk_fma_f32 v[184:185], v[96:97], v[130:131], v[138:139] op_sel_hi:[1,0,1]
	v_cvt_scalef32_pk_f32_fp4 v[96:97], v94, 1.0 op_sel:[0,1,0]
	v_pk_fma_f32 v[186:187], v[96:97], v[130:131], v[142:143] op_sel_hi:[1,0,1]
	v_cvt_scalef32_pk_f32_fp4 v[96:97], v94, 1.0 op_sel:[1,1,0]
	v_pk_fma_f32 v[188:189], v[96:97], v[130:131], v[144:145] op_sel_hi:[1,0,1]
	v_cvt_scalef32_pk_f32_fp4 v[96:97], v95, 1.0
	v_pk_fma_f32 v[190:191], v[96:97], v[130:131], v[146:147] op_sel_hi:[1,0,1]
	v_cvt_scalef32_pk_f32_fp4 v[96:97], v95, 1.0 op_sel:[1,0,0]
	v_pk_fma_f32 v[192:193], v[96:97], v[130:131], v[148:149] op_sel_hi:[1,0,1]
	v_cvt_scalef32_pk_f32_fp4 v[96:97], v95, 1.0 op_sel:[0,1,0]
	v_pk_fma_f32 v[194:195], v[96:97], v[130:131], v[150:151] op_sel_hi:[1,0,1]
	s_waitcnt vmcnt(16)
	v_cvt_scalef32_pk_f32_fp4 v[96:97], v48, 1.0 op_sel:[0,1,0]
	v_pk_fma_f32 v[196:197], v[96:97], v[130:131], v[154:155] op_sel_hi:[1,0,1]
	v_cvt_scalef32_pk_f32_fp4 v[96:97], v48, 1.0 op_sel:[1,1,0]
	v_pk_fma_f32 v[198:199], v[96:97], v[130:131], v[156:157] op_sel_hi:[1,0,1]
	v_cvt_scalef32_pk_f32_fp4 v[96:97], v49, 1.0
	v_cvt_scalef32_pk_f32_fp4 v[92:93], v93, 1.0 op_sel:[1,1,0]
	v_pk_fma_f32 v[200:201], v[96:97], v[130:131], v[158:159] op_sel_hi:[1,0,1]
	v_cvt_scalef32_pk_f32_fp4 v[96:97], v49, 1.0 op_sel:[1,0,0]
	v_pk_fma_f32 v[56:57], v[92:93], v[130:131], v[56:57] op_sel_hi:[1,0,1]
	v_cvt_scalef32_pk_f32_fp4 v[92:93], v94, 1.0
	v_pk_fma_f32 v[234:235], v[96:97], v[130:131], v[160:161] op_sel_hi:[1,0,1]
	v_cvt_scalef32_pk_f32_fp4 v[96:97], v49, 1.0 op_sel:[0,1,0]
	v_pk_fma_f32 v[60:61], v[92:93], v[130:131], v[60:61] op_sel_hi:[1,0,1]
	v_cvt_scalef32_pk_f32_fp4 v[92:93], v94, 1.0 op_sel:[1,0,0]
	v_cvt_scalef32_pk_f32_fp4 v[94:95], v95, 1.0 op_sel:[1,1,0]
	v_pk_fma_f32 v[236:237], v[96:97], v[130:131], v[162:163] op_sel_hi:[1,0,1]
	v_cvt_scalef32_pk_f32_fp4 v[96:97], v50, 1.0 op_sel:[0,1,0]
	v_pk_fma_f32 v[58:59], v[94:95], v[130:131], v[58:59] op_sel_hi:[1,0,1]
	v_cvt_scalef32_pk_f32_fp4 v[94:95], v48, 1.0
	v_pk_fma_f32 v[238:239], v[96:97], v[130:131], v[166:167] op_sel_hi:[1,0,1]
	v_cvt_scalef32_pk_f32_fp4 v[96:97], v50, 1.0 op_sel:[1,1,0]
	v_pk_fma_f32 v[62:63], v[94:95], v[130:131], v[62:63] op_sel_hi:[1,0,1]
	v_cvt_scalef32_pk_f32_fp4 v[94:95], v48, 1.0 op_sel:[1,0,0]
	v_cvt_scalef32_pk_f32_fp4 v[48:49], v49, 1.0 op_sel:[1,1,0]
	v_pk_fma_f32 v[240:241], v[96:97], v[130:131], v[168:169] op_sel_hi:[1,0,1]
	v_cvt_scalef32_pk_f32_fp4 v[96:97], v51, 1.0
	v_pk_fma_f32 v[36:37], v[48:49], v[130:131], v[36:37] op_sel_hi:[1,0,1]
	v_cvt_scalef32_pk_f32_fp4 v[48:49], v50, 1.0
	v_pk_fma_f32 v[242:243], v[96:97], v[130:131], v[170:171] op_sel_hi:[1,0,1]
	v_cvt_scalef32_pk_f32_fp4 v[96:97], v51, 1.0 op_sel:[1,0,0]
	v_pk_fma_f32 v[40:41], v[48:49], v[130:131], v[40:41] op_sel_hi:[1,0,1]
	v_cvt_scalef32_pk_f32_fp4 v[48:49], v50, 1.0 op_sel:[1,0,0]
	v_pk_fma_f32 v[244:245], v[96:97], v[130:131], v[172:173] op_sel_hi:[1,0,1]
	v_cvt_scalef32_pk_f32_fp4 v[96:97], v51, 1.0 op_sel:[0,1,0]
	v_cvt_scalef32_pk_f32_fp4 v[50:51], v51, 1.0 op_sel:[1,1,0]
	v_pk_fma_f32 v[92:93], v[92:93], v[130:131], v[140:141] op_sel_hi:[1,0,1]
	v_pk_fma_f32 v[94:95], v[94:95], v[130:131], v[152:153] op_sel_hi:[1,0,1]
	v_pk_fma_f32 v[48:49], v[48:49], v[130:131], v[164:165] op_sel_hi:[1,0,1]
	v_pk_fma_f32 v[38:39], v[50:51], v[130:131], v[38:39] op_sel_hi:[1,0,1]
	v_pk_fma_f32 v[246:247], v[96:97], v[130:131], v[174:175] op_sel_hi:[1,0,1]
	v_lshl_or_b32 v50, v99, 9, v203
	global_load_dwordx4 v[108:111], v50, s[46:47]
	global_load_dwordx4 v[96:99], v50, s[46:47] offset:256
	v_mov_b32_e32 v50, v131
	s_waitcnt vmcnt(17)
	v_cvt_scalef32_pk_f32_fp4 v[130:131], v52, 1.0
	v_pk_fma_f32 v[138:139], v[130:131], v[50:51], v[42:43] op_sel_hi:[1,0,1]
	v_cvt_scalef32_pk_f32_fp4 v[42:43], v52, 1.0 op_sel:[1,0,0]
	v_pk_fma_f32 v[140:141], v[42:43], v[50:51], v[128:129] op_sel_hi:[1,0,1]
	v_cvt_scalef32_pk_f32_fp4 v[42:43], v52, 1.0 op_sel:[0,1,0]
	v_pk_fma_f32 v[142:143], v[42:43], v[50:51], v[176:177] op_sel_hi:[1,0,1]
	v_cvt_scalef32_pk_f32_fp4 v[42:43], v52, 1.0 op_sel:[1,1,0]
	v_pk_fma_f32 v[144:145], v[42:43], v[50:51], v[178:179] op_sel_hi:[1,0,1]
	v_cvt_scalef32_pk_f32_fp4 v[42:43], v53, 1.0
	v_pk_fma_f32 v[146:147], v[42:43], v[50:51], v[180:181] op_sel_hi:[1,0,1]
	v_cvt_scalef32_pk_f32_fp4 v[42:43], v53, 1.0 op_sel:[1,0,0]
	v_pk_fma_f32 v[148:149], v[42:43], v[50:51], v[182:183] op_sel_hi:[1,0,1]
	v_cvt_scalef32_pk_f32_fp4 v[42:43], v53, 1.0 op_sel:[0,1,0]
	v_pk_fma_f32 v[150:151], v[42:43], v[50:51], v[184:185] op_sel_hi:[1,0,1]
	v_cvt_scalef32_pk_f32_fp4 v[42:43], v53, 1.0 op_sel:[1,1,0]
	v_pk_fma_f32 v[152:153], v[42:43], v[50:51], v[56:57] op_sel_hi:[1,0,1]
	v_cvt_scalef32_pk_f32_fp4 v[42:43], v54, 1.0
	v_pk_fma_f32 v[154:155], v[42:43], v[50:51], v[60:61] op_sel_hi:[1,0,1]
	v_cvt_scalef32_pk_f32_fp4 v[42:43], v54, 1.0 op_sel:[1,0,0]
	v_pk_fma_f32 v[156:157], v[42:43], v[50:51], v[92:93] op_sel_hi:[1,0,1]
	v_cvt_scalef32_pk_f32_fp4 v[42:43], v54, 1.0 op_sel:[0,1,0]
	v_pk_fma_f32 v[158:159], v[42:43], v[50:51], v[186:187] op_sel_hi:[1,0,1]
	v_cvt_scalef32_pk_f32_fp4 v[42:43], v54, 1.0 op_sel:[1,1,0]
	v_pk_fma_f32 v[160:161], v[42:43], v[50:51], v[188:189] op_sel_hi:[1,0,1]
	v_cvt_scalef32_pk_f32_fp4 v[42:43], v55, 1.0
	v_pk_fma_f32 v[162:163], v[42:43], v[50:51], v[190:191] op_sel_hi:[1,0,1]
	v_cvt_scalef32_pk_f32_fp4 v[42:43], v55, 1.0 op_sel:[1,0,0]
	v_pk_fma_f32 v[164:165], v[42:43], v[50:51], v[192:193] op_sel_hi:[1,0,1]
	v_cvt_scalef32_pk_f32_fp4 v[42:43], v55, 1.0 op_sel:[0,1,0]
	v_pk_fma_f32 v[166:167], v[42:43], v[50:51], v[194:195] op_sel_hi:[1,0,1]
	v_cvt_scalef32_pk_f32_fp4 v[42:43], v55, 1.0 op_sel:[1,1,0]
	v_pk_fma_f32 v[168:169], v[42:43], v[50:51], v[58:59] op_sel_hi:[1,0,1]
	s_waitcnt vmcnt(16)
	v_cvt_scalef32_pk_f32_fp4 v[42:43], v32, 1.0
	v_pk_fma_f32 v[170:171], v[42:43], v[50:51], v[62:63] op_sel_hi:[1,0,1]
	v_cvt_scalef32_pk_f32_fp4 v[42:43], v32, 1.0 op_sel:[1,0,0]
	v_pk_fma_f32 v[172:173], v[42:43], v[50:51], v[94:95] op_sel_hi:[1,0,1]
	v_cvt_scalef32_pk_f32_fp4 v[42:43], v32, 1.0 op_sel:[0,1,0]
	v_pk_fma_f32 v[174:175], v[42:43], v[50:51], v[196:197] op_sel_hi:[1,0,1]
	v_cvt_scalef32_pk_f32_fp4 v[42:43], v32, 1.0 op_sel:[1,1,0]
	v_pk_fma_f32 v[176:177], v[42:43], v[50:51], v[198:199] op_sel_hi:[1,0,1]
	v_cvt_scalef32_pk_f32_fp4 v[42:43], v33, 1.0
	v_pk_fma_f32 v[178:179], v[42:43], v[50:51], v[200:201] op_sel_hi:[1,0,1]
	v_cvt_scalef32_pk_f32_fp4 v[42:43], v33, 1.0 op_sel:[1,0,0]
	v_pk_fma_f32 v[180:181], v[42:43], v[50:51], v[234:235] op_sel_hi:[1,0,1]
	v_cvt_scalef32_pk_f32_fp4 v[42:43], v33, 1.0 op_sel:[0,1,0]
	v_cvt_scalef32_pk_f32_fp4 v[32:33], v33, 1.0 op_sel:[1,1,0]
	v_pk_fma_f32 v[184:185], v[32:33], v[50:51], v[36:37] op_sel_hi:[1,0,1]
	v_cvt_scalef32_pk_f32_fp4 v[32:33], v34, 1.0
	v_pk_fma_f32 v[186:187], v[32:33], v[50:51], v[40:41] op_sel_hi:[1,0,1]
	v_cvt_scalef32_pk_f32_fp4 v[32:33], v34, 1.0 op_sel:[1,0,0]
	v_pk_fma_f32 v[188:189], v[32:33], v[50:51], v[48:49] op_sel_hi:[1,0,1]
	v_cvt_scalef32_pk_f32_fp4 v[32:33], v34, 1.0 op_sel:[0,1,0]
	v_pk_fma_f32 v[190:191], v[32:33], v[50:51], v[238:239] op_sel_hi:[1,0,1]
	v_cvt_scalef32_pk_f32_fp4 v[32:33], v34, 1.0 op_sel:[1,1,0]
	v_pk_fma_f32 v[192:193], v[32:33], v[50:51], v[240:241] op_sel_hi:[1,0,1]
	v_cvt_scalef32_pk_f32_fp4 v[32:33], v35, 1.0
	v_pk_fma_f32 v[194:195], v[32:33], v[50:51], v[242:243] op_sel_hi:[1,0,1]
	v_cvt_scalef32_pk_f32_fp4 v[32:33], v35, 1.0 op_sel:[1,0,0]
	v_pk_fma_f32 v[196:197], v[32:33], v[50:51], v[244:245] op_sel_hi:[1,0,1]
	v_cvt_scalef32_pk_f32_fp4 v[32:33], v35, 1.0 op_sel:[0,1,0]
	v_pk_fma_f32 v[182:183], v[42:43], v[50:51], v[236:237] op_sel_hi:[1,0,1]
	v_pk_fma_f32 v[198:199], v[32:33], v[50:51], v[246:247] op_sel_hi:[1,0,1]
	v_cvt_scalef32_pk_f32_fp4 v[32:33], v35, 1.0 op_sel:[1,1,0]
	v_pk_fma_f32 v[200:201], v[32:33], v[50:51], v[38:39] op_sel_hi:[1,0,1]
	s_min_u32 s33, s65, 26
	v_lshl_add_u32 v32, s33, 4, v204
	ds_read_b128 v[54:57], v32 offset:80
	v_dot8_u32_u4 v32, v44, v214, 0
	v_dot8_u32_u4 v33, v45, v215, 0
	v_dot8_u32_u4 v32, v46, v217, v32
	v_dot8_u32_u4 v34, v44, v132, 0
	v_dot8_u32_u4 v35, v45, v216, 0
	v_dot8_u32_u4 v32, v64, v221, v32
	v_dot8_u32_u4 v33, v47, v218, v33
	v_dot8_u32_u4 v34, v46, v219, v34
	v_dot8_u32_u4 v35, v47, v220, v35
	v_dot8_u32_u4 v93, v66, v225, v32
	s_waitcnt lgkmcnt(0)
	v_lshl_or_b32 v32, v54, 9, v203
	v_lshl_or_b32 v40, v55, 9, v203
	v_lshl_or_b32 v52, v56, 9, v203
	v_lshl_or_b32 v60, v57, 9, v203
	v_dot8_u32_u4 v92, v65, v222, v33
	v_dot8_u32_u4 v64, v64, v223, v34
	v_dot8_u32_u4 v65, v65, v224, v35
	global_load_dwordx4 v[44:47], v32, s[36:37]
	s_nop 0
	global_load_dwordx4 v[32:35], v32, s[36:37] offset:256
	s_nop 0
	global_load_dwordx4 v[36:39], v40, s[36:37]
	s_nop 0
	global_load_dwordx4 v[40:43], v40, s[36:37] offset:256
	s_nop 0
	global_load_dwordx4 v[48:51], v52, s[36:37]
	s_nop 0
	global_load_dwordx4 v[52:55], v52, s[36:37] offset:256
	s_nop 0
	global_load_dwordx4 v[56:59], v60, s[36:37]
	s_nop 0
	global_load_dwordx4 v[60:63], v60, s[36:37] offset:256
	v_dot8_u32_u4 v92, v67, v226, v92
	v_dot8_u32_u4 v64, v66, v227, v64
	v_dot8_u32_u4 v65, v67, v228, v65
	v_dot8_u32_u4 v67, v80, v132, 0
	v_add_lshl_u32 v66, v92, v93, 4
	v_dot8_u32_u4 v67, v82, v219, v67
	v_add3_u32 v64, v65, v64, v66
	v_dot8_u32_u4 v65, v80, v214, 0
	v_dot8_u32_u4 v66, v81, v215, 0
	v_dot8_u32_u4 v80, v81, v216, 0
	v_dot8_u32_u4 v65, v82, v217, v65
	v_dot8_u32_u4 v66, v83, v218, v66
	v_dot8_u32_u4 v80, v83, v220, v80
	v_dot8_u32_u4 v65, v68, v221, v65
	v_dot8_u32_u4 v66, v69, v222, v66
	v_dot8_u32_u4 v67, v68, v223, v67
	v_dot8_u32_u4 v68, v69, v224, v80
	v_dot8_u32_u4 v65, v70, v225, v65
	v_dot8_u32_u4 v66, v71, v226, v66
	v_dot8_u32_u4 v67, v70, v227, v67
	v_dot8_u32_u4 v68, v71, v228, v68
	v_add_u32_dpp v64, v64, v64 quad_perm:[1,0,3,2] row_mask:0xf bank_mask:0xf bound_ctrl:1
	v_add_lshl_u32 v65, v66, v65, 4
	v_dot8_u32_u4 v66, v85, v215, 0
	v_add3_u32 v65, v68, v67, v65
	v_add_u32_dpp v64, v64, v64 quad_perm:[2,3,0,1] row_mask:0xf bank_mask:0xf bound_ctrl:1
	v_dot8_u32_u4 v67, v84, v132, 0
	v_add_u32_dpp v65, v65, v65 quad_perm:[1,0,3,2] row_mask:0xf bank_mask:0xf bound_ctrl:1
	v_add_u32_dpp v64, v64, v64 row_half_mirror row_mask:0xf bank_mask:0xf bound_ctrl:1
	v_dot8_u32_u4 v68, v85, v216, 0
	v_add_u32_dpp v65, v65, v65 quad_perm:[2,3,0,1] row_mask:0xf bank_mask:0xf bound_ctrl:1
	v_add_u32_dpp v64, v64, v64 row_mirror row_mask:0xf bank_mask:0xf bound_ctrl:1
	v_cndmask_b32_e64 v64, v233, v64, s[24:25]
	v_add_u32_dpp v65, v65, v65 row_half_mirror row_mask:0xf bank_mask:0xf bound_ctrl:1
	v_dot8_u32_u4 v66, v87, v218, v66
	v_dot8_u32_u4 v67, v86, v219, v67
	v_add_u32_dpp v65, v65, v65 row_mirror row_mask:0xf bank_mask:0xf bound_ctrl:1
	v_cndmask_b32_e64 v64, v64, v65, s[26:27]
	v_dot8_u32_u4 v65, v84, v214, 0
	v_dot8_u32_u4 v68, v87, v220, v68
	v_dot8_u32_u4 v65, v86, v217, v65
	v_dot8_u32_u4 v66, v73, v222, v66
	v_dot8_u32_u4 v65, v72, v221, v65
	v_dot8_u32_u4 v67, v72, v223, v67
	v_dot8_u32_u4 v68, v73, v224, v68
	v_dot8_u32_u4 v65, v74, v225, v65
	v_dot8_u32_u4 v66, v75, v226, v66
	v_dot8_u32_u4 v67, v74, v227, v67
	v_dot8_u32_u4 v68, v75, v228, v68
	s_nop 0
	v_add_lshl_u32 v65, v66, v65, 4
	v_dot8_u32_u4 v66, v89, v215, 0
	v_add3_u32 v65, v68, v67, v65
	v_dot8_u32_u4 v67, v88, v132, 0
	v_dot8_u32_u4 v68, v89, v216, 0
	v_add_u32_dpp v65, v65, v65 quad_perm:[1,0,3,2] row_mask:0xf bank_mask:0xf bound_ctrl:1
	v_dot8_u32_u4 v66, v91, v218, v66
	v_dot8_u32_u4 v67, v90, v219, v67
	v_add_u32_dpp v65, v65, v65 quad_perm:[2,3,0,1] row_mask:0xf bank_mask:0xf bound_ctrl:1
	v_dot8_u32_u4 v68, v91, v220, v68
	v_dot8_u32_u4 v66, v77, v222, v66
	v_add_u32_dpp v65, v65, v65 row_half_mirror row_mask:0xf bank_mask:0xf bound_ctrl:1
	v_dot8_u32_u4 v67, v76, v223, v67
	v_dot8_u32_u4 v68, v77, v224, v68
	v_add_u32_dpp v65, v65, v65 row_mirror row_mask:0xf bank_mask:0xf bound_ctrl:1
	v_cndmask_b32_e64 v64, v64, v65, s[28:29]
	v_dot8_u32_u4 v65, v88, v214, 0
	v_dot8_u32_u4 v66, v79, v226, v66
	v_dot8_u32_u4 v65, v90, v217, v65
	v_dot8_u32_u4 v67, v78, v227, v67
	v_dot8_u32_u4 v65, v76, v221, v65
	v_dot8_u32_u4 v68, v79, v228, v68
	v_dot8_u32_u4 v65, v78, v225, v65
	s_nop 2
	v_add_lshl_u32 v65, v66, v65, 4
	v_add3_u32 v65, v68, v67, v65
	s_nop 1
	v_add_u32_dpp v65, v65, v65 quad_perm:[1,0,3,2] row_mask:0xf bank_mask:0xf bound_ctrl:1
	s_nop 1
	v_add_u32_dpp v65, v65, v65 quad_perm:[2,3,0,1] row_mask:0xf bank_mask:0xf bound_ctrl:1
	s_nop 1
	v_add_u32_dpp v65, v65, v65 row_half_mirror row_mask:0xf bank_mask:0xf bound_ctrl:1
	s_nop 1
	v_add_u32_dpp v65, v65, v65 row_mirror row_mask:0xf bank_mask:0xf bound_ctrl:1
	v_cndmask_b32_e64 v233, v64, v65, s[30:31]
	ds_read_b128 v[64:67], v232 offset:64
	ds_read_b128 v[128:131], v232 offset:4144
	s_waitcnt vmcnt(15)
	v_cvt_scalef32_pk_f32_fp4 v[68:69], v124, 1.0
	v_cvt_scalef32_pk_f32_fp4 v[80:81], v125, 1.0 op_sel:[0,1,0]
	v_cvt_scalef32_pk_f32_fp4 v[70:71], v124, 1.0 op_sel:[1,0,0]
	s_waitcnt lgkmcnt(1)
	v_lshl_or_b32 v64, v64, 9, v203
	global_load_dwordx4 v[92:95], v64, s[46:47]
	global_load_dwordx4 v[88:91], v64, s[46:47] offset:256
	s_waitcnt lgkmcnt(0)
	v_pk_fma_f32 v[68:69], v[68:69], v[128:129], v[138:139] op_sel_hi:[1,0,1]
	v_pk_fma_f32 v[138:139], v[80:81], v[128:129], v[150:151] op_sel_hi:[1,0,1]
	v_cvt_scalef32_pk_f32_fp4 v[80:81], v125, 1.0 op_sel:[1,1,0]
	v_cvt_scalef32_pk_f32_fp4 v[72:73], v124, 1.0 op_sel:[0,1,0]
	v_cvt_scalef32_pk_f32_fp4 v[74:75], v124, 1.0 op_sel:[1,1,0]
	v_cvt_scalef32_pk_f32_fp4 v[76:77], v125, 1.0
	v_cvt_scalef32_pk_f32_fp4 v[78:79], v125, 1.0 op_sel:[1,0,0]
	v_pk_fma_f32 v[124:125], v[80:81], v[128:129], v[152:153] op_sel_hi:[1,0,1]
	v_cvt_scalef32_pk_f32_fp4 v[80:81], v126, 1.0
	v_pk_fma_f32 v[70:71], v[70:71], v[128:129], v[140:141] op_sel_hi:[1,0,1]
	v_pk_fma_f32 v[140:141], v[80:81], v[128:129], v[154:155] op_sel_hi:[1,0,1]
	v_cvt_scalef32_pk_f32_fp4 v[80:81], v126, 1.0 op_sel:[1,0,0]
	v_pk_fma_f32 v[72:73], v[72:73], v[128:129], v[142:143] op_sel_hi:[1,0,1]
	v_pk_fma_f32 v[142:143], v[80:81], v[128:129], v[156:157] op_sel_hi:[1,0,1]
	v_cvt_scalef32_pk_f32_fp4 v[80:81], v126, 1.0 op_sel:[0,1,0]
	v_pk_fma_f32 v[74:75], v[74:75], v[128:129], v[144:145] op_sel_hi:[1,0,1]
	v_pk_fma_f32 v[144:145], v[80:81], v[128:129], v[158:159] op_sel_hi:[1,0,1]
	v_cvt_scalef32_pk_f32_fp4 v[80:81], v126, 1.0 op_sel:[1,1,0]
	v_pk_fma_f32 v[76:77], v[76:77], v[128:129], v[146:147] op_sel_hi:[1,0,1]
	v_pk_fma_f32 v[146:147], v[80:81], v[128:129], v[160:161] op_sel_hi:[1,0,1]
	v_cvt_scalef32_pk_f32_fp4 v[80:81], v127, 1.0
	v_pk_fma_f32 v[78:79], v[78:79], v[128:129], v[148:149] op_sel_hi:[1,0,1]
	v_pk_fma_f32 v[148:149], v[80:81], v[128:129], v[162:163] op_sel_hi:[1,0,1]
	v_cvt_scalef32_pk_f32_fp4 v[80:81], v127, 1.0 op_sel:[1,0,0]
	v_pk_fma_f32 v[150:151], v[80:81], v[128:129], v[164:165] op_sel_hi:[1,0,1]
	v_cvt_scalef32_pk_f32_fp4 v[80:81], v127, 1.0 op_sel:[0,1,0]
	v_pk_fma_f32 v[152:153], v[80:81], v[128:129], v[166:167] op_sel_hi:[1,0,1]
	v_cvt_scalef32_pk_f32_fp4 v[80:81], v127, 1.0 op_sel:[1,1,0]
	v_pk_fma_f32 v[126:127], v[80:81], v[128:129], v[168:169] op_sel_hi:[1,0,1]
	s_waitcnt vmcnt(16)
	v_cvt_scalef32_pk_f32_fp4 v[80:81], v112, 1.0
	v_pk_fma_f32 v[154:155], v[80:81], v[128:129], v[170:171] op_sel_hi:[1,0,1]
	v_cvt_scalef32_pk_f32_fp4 v[80:81], v112, 1.0 op_sel:[1,0,0]
	v_pk_fma_f32 v[156:157], v[80:81], v[128:129], v[172:173] op_sel_hi:[1,0,1]
	v_cvt_scalef32_pk_f32_fp4 v[80:81], v112, 1.0 op_sel:[0,1,0]
	v_pk_fma_f32 v[158:159], v[80:81], v[128:129], v[174:175] op_sel_hi:[1,0,1]
	v_cvt_scalef32_pk_f32_fp4 v[80:81], v112, 1.0 op_sel:[1,1,0]
	v_pk_fma_f32 v[160:161], v[80:81], v[128:129], v[176:177] op_sel_hi:[1,0,1]
	v_cvt_scalef32_pk_f32_fp4 v[80:81], v113, 1.0
	v_pk_fma_f32 v[162:163], v[80:81], v[128:129], v[178:179] op_sel_hi:[1,0,1]
	v_cvt_scalef32_pk_f32_fp4 v[80:81], v113, 1.0 op_sel:[1,0,0]
	v_pk_fma_f32 v[164:165], v[80:81], v[128:129], v[180:181] op_sel_hi:[1,0,1]
	v_cvt_scalef32_pk_f32_fp4 v[80:81], v113, 1.0 op_sel:[0,1,0]
	v_pk_fma_f32 v[166:167], v[80:81], v[128:129], v[182:183] op_sel_hi:[1,0,1]
	v_cvt_scalef32_pk_f32_fp4 v[80:81], v113, 1.0 op_sel:[1,1,0]
	v_pk_fma_f32 v[112:113], v[80:81], v[128:129], v[184:185] op_sel_hi:[1,0,1]
	v_cvt_scalef32_pk_f32_fp4 v[80:81], v114, 1.0
	v_pk_fma_f32 v[168:169], v[80:81], v[128:129], v[186:187] op_sel_hi:[1,0,1]
	v_cvt_scalef32_pk_f32_fp4 v[80:81], v114, 1.0 op_sel:[1,0,0]
	v_pk_fma_f32 v[170:171], v[80:81], v[128:129], v[188:189] op_sel_hi:[1,0,1]
	v_cvt_scalef32_pk_f32_fp4 v[80:81], v114, 1.0 op_sel:[0,1,0]
	v_pk_fma_f32 v[172:173], v[80:81], v[128:129], v[190:191] op_sel_hi:[1,0,1]
	v_cvt_scalef32_pk_f32_fp4 v[80:81], v114, 1.0 op_sel:[1,1,0]
	v_pk_fma_f32 v[174:175], v[80:81], v[128:129], v[192:193] op_sel_hi:[1,0,1]
	v_cvt_scalef32_pk_f32_fp4 v[80:81], v115, 1.0
	v_pk_fma_f32 v[176:177], v[80:81], v[128:129], v[194:195] op_sel_hi:[1,0,1]
	v_cvt_scalef32_pk_f32_fp4 v[80:81], v115, 1.0 op_sel:[1,0,0]
	v_pk_fma_f32 v[178:179], v[80:81], v[128:129], v[196:197] op_sel_hi:[1,0,1]
	v_cvt_scalef32_pk_f32_fp4 v[80:81], v115, 1.0 op_sel:[0,1,0]
	v_add_u32_e32 v232, 64, v232
	v_pk_fma_f32 v[180:181], v[80:81], v[128:129], v[198:199] op_sel_hi:[1,0,1]
	v_cvt_scalef32_pk_f32_fp4 v[80:81], v115, 1.0 op_sel:[1,1,0]
	v_pk_fma_f32 v[114:115], v[80:81], v[128:129], v[200:201] op_sel_hi:[1,0,1]
	v_lshl_or_b32 v64, v65, 9, v203
	global_load_dwordx4 v[84:87], v64, s[46:47]
	global_load_dwordx4 v[80:83], v64, s[46:47] offset:256
	s_waitcnt vmcnt(17)
	v_cvt_scalef32_pk_f32_fp4 v[64:65], v120, 1.0
	v_pk_fma_f32 v[64:65], v[64:65], v[128:129], v[68:69] op_sel:[0,1,0]
	v_cvt_scalef32_pk_f32_fp4 v[68:69], v120, 1.0 op_sel:[1,0,0]
	v_pk_fma_f32 v[68:69], v[68:69], v[128:129], v[70:71] op_sel:[0,1,0]
	v_cvt_scalef32_pk_f32_fp4 v[70:71], v120, 1.0 op_sel:[0,1,0]
	v_pk_fma_f32 v[70:71], v[70:71], v[128:129], v[72:73] op_sel:[0,1,0]
	v_cvt_scalef32_pk_f32_fp4 v[72:73], v120, 1.0 op_sel:[1,1,0]
	v_pk_fma_f32 v[182:183], v[72:73], v[128:129], v[74:75] op_sel:[0,1,0]
	v_cvt_scalef32_pk_f32_fp4 v[72:73], v121, 1.0
	v_pk_fma_f32 v[184:185], v[72:73], v[128:129], v[76:77] op_sel:[0,1,0]
	v_cvt_scalef32_pk_f32_fp4 v[72:73], v121, 1.0 op_sel:[1,0,0]
	v_pk_fma_f32 v[186:187], v[72:73], v[128:129], v[78:79] op_sel:[0,1,0]
	v_cvt_scalef32_pk_f32_fp4 v[72:73], v121, 1.0 op_sel:[0,1,0]
	v_pk_fma_f32 v[138:139], v[72:73], v[128:129], v[138:139] op_sel:[0,1,0]
	v_cvt_scalef32_pk_f32_fp4 v[72:73], v121, 1.0 op_sel:[1,1,0]
	v_pk_fma_f32 v[120:121], v[72:73], v[128:129], v[124:125] op_sel:[0,1,0]
	v_cvt_scalef32_pk_f32_fp4 v[72:73], v122, 1.0
	v_pk_fma_f32 v[124:125], v[72:73], v[128:129], v[140:141] op_sel:[0,1,0]
	v_cvt_scalef32_pk_f32_fp4 v[72:73], v122, 1.0 op_sel:[1,0,0]
	v_pk_fma_f32 v[140:141], v[72:73], v[128:129], v[142:143] op_sel:[0,1,0]
	v_cvt_scalef32_pk_f32_fp4 v[72:73], v122, 1.0 op_sel:[0,1,0]
	v_pk_fma_f32 v[142:143], v[72:73], v[128:129], v[144:145] op_sel:[0,1,0]
	v_cvt_scalef32_pk_f32_fp4 v[72:73], v122, 1.0 op_sel:[1,1,0]
	v_pk_fma_f32 v[144:145], v[72:73], v[128:129], v[146:147] op_sel:[0,1,0]
	v_cvt_scalef32_pk_f32_fp4 v[72:73], v123, 1.0
	v_pk_fma_f32 v[146:147], v[72:73], v[128:129], v[148:149] op_sel:[0,1,0]
	v_cvt_scalef32_pk_f32_fp4 v[72:73], v123, 1.0 op_sel:[1,0,0]
	v_pk_fma_f32 v[148:149], v[72:73], v[128:129], v[150:151] op_sel:[0,1,0]
	v_cvt_scalef32_pk_f32_fp4 v[72:73], v123, 1.0 op_sel:[0,1,0]
	v_pk_fma_f32 v[150:151], v[72:73], v[128:129], v[152:153] op_sel:[0,1,0]
	v_cvt_scalef32_pk_f32_fp4 v[72:73], v123, 1.0 op_sel:[1,1,0]
	v_pk_fma_f32 v[122:123], v[72:73], v[128:129], v[126:127] op_sel:[0,1,0]
	s_waitcnt vmcnt(16)
	v_cvt_scalef32_pk_f32_fp4 v[72:73], v104, 1.0
	v_pk_fma_f32 v[126:127], v[72:73], v[128:129], v[154:155] op_sel:[0,1,0]
	v_cvt_scalef32_pk_f32_fp4 v[72:73], v104, 1.0 op_sel:[1,0,0]
	v_pk_fma_f32 v[152:153], v[72:73], v[128:129], v[156:157] op_sel:[0,1,0]
	v_cvt_scalef32_pk_f32_fp4 v[72:73], v104, 1.0 op_sel:[0,1,0]
	v_pk_fma_f32 v[154:155], v[72:73], v[128:129], v[158:159] op_sel:[0,1,0]
	v_cvt_scalef32_pk_f32_fp4 v[72:73], v104, 1.0 op_sel:[1,1,0]
	v_pk_fma_f32 v[156:157], v[72:73], v[128:129], v[160:161] op_sel:[0,1,0]
	v_cvt_scalef32_pk_f32_fp4 v[72:73], v105, 1.0
	v_pk_fma_f32 v[158:159], v[72:73], v[128:129], v[162:163] op_sel:[0,1,0]
	v_cvt_scalef32_pk_f32_fp4 v[72:73], v105, 1.0 op_sel:[1,0,0]
	v_pk_fma_f32 v[160:161], v[72:73], v[128:129], v[164:165] op_sel:[0,1,0]
	v_cvt_scalef32_pk_f32_fp4 v[72:73], v105, 1.0 op_sel:[0,1,0]
	v_pk_fma_f32 v[162:163], v[72:73], v[128:129], v[166:167] op_sel:[0,1,0]
	v_cvt_scalef32_pk_f32_fp4 v[72:73], v105, 1.0 op_sel:[1,1,0]
	v_pk_fma_f32 v[104:105], v[72:73], v[128:129], v[112:113] op_sel:[0,1,0]
	v_cvt_scalef32_pk_f32_fp4 v[72:73], v106, 1.0
	v_pk_fma_f32 v[112:113], v[72:73], v[128:129], v[168:169] op_sel:[0,1,0]
	v_cvt_scalef32_pk_f32_fp4 v[72:73], v106, 1.0 op_sel:[1,0,0]
	v_pk_fma_f32 v[164:165], v[72:73], v[128:129], v[170:171] op_sel:[0,1,0]
	v_cvt_scalef32_pk_f32_fp4 v[72:73], v106, 1.0 op_sel:[0,1,0]
	v_pk_fma_f32 v[166:167], v[72:73], v[128:129], v[172:173] op_sel:[0,1,0]
	v_cvt_scalef32_pk_f32_fp4 v[72:73], v106, 1.0 op_sel:[1,1,0]
	v_pk_fma_f32 v[168:169], v[72:73], v[128:129], v[174:175] op_sel:[0,1,0]
	v_cvt_scalef32_pk_f32_fp4 v[72:73], v107, 1.0
	v_pk_fma_f32 v[170:171], v[72:73], v[128:129], v[176:177] op_sel:[0,1,0]
	v_cvt_scalef32_pk_f32_fp4 v[72:73], v107, 1.0 op_sel:[1,0,0]
	v_pk_fma_f32 v[172:173], v[72:73], v[128:129], v[178:179] op_sel:[0,1,0]
	v_cvt_scalef32_pk_f32_fp4 v[72:73], v107, 1.0 op_sel:[0,1,0]
	v_pk_fma_f32 v[174:175], v[72:73], v[128:129], v[180:181] op_sel:[0,1,0]
	v_cvt_scalef32_pk_f32_fp4 v[72:73], v107, 1.0 op_sel:[1,1,0]
	v_pk_fma_f32 v[106:107], v[72:73], v[128:129], v[114:115] op_sel:[0,1,0]
	v_lshl_or_b32 v66, v66, 9, v203
	global_load_dwordx4 v[76:79], v66, s[46:47]
	global_load_dwordx4 v[72:75], v66, s[46:47] offset:256
	s_waitcnt vmcnt(17)
	v_cvt_scalef32_pk_f32_fp4 v[114:115], v116, 1.0
	v_pk_fma_f32 v[114:115], v[114:115], v[130:131], v[64:65] op_sel_hi:[1,0,1]
	v_cvt_scalef32_pk_f32_fp4 v[64:65], v116, 1.0 op_sel:[1,0,0]
	v_pk_fma_f32 v[128:129], v[64:65], v[130:131], v[68:69] op_sel_hi:[1,0,1]
	v_cvt_scalef32_pk_f32_fp4 v[64:65], v116, 1.0 op_sel:[0,1,0]
	v_pk_fma_f32 v[176:177], v[64:65], v[130:131], v[70:71] op_sel_hi:[1,0,1]
	v_cvt_scalef32_pk_f32_fp4 v[64:65], v116, 1.0 op_sel:[1,1,0]
	v_pk_fma_f32 v[178:179], v[64:65], v[130:131], v[182:183] op_sel_hi:[1,0,1]
	v_cvt_scalef32_pk_f32_fp4 v[64:65], v117, 1.0
	v_pk_fma_f32 v[180:181], v[64:65], v[130:131], v[184:185] op_sel_hi:[1,0,1]
	v_cvt_scalef32_pk_f32_fp4 v[64:65], v117, 1.0 op_sel:[1,0,0]
	v_pk_fma_f32 v[182:183], v[64:65], v[130:131], v[186:187] op_sel_hi:[1,0,1]
	v_cvt_scalef32_pk_f32_fp4 v[64:65], v117, 1.0 op_sel:[0,1,0]
	v_pk_fma_f32 v[184:185], v[64:65], v[130:131], v[138:139] op_sel_hi:[1,0,1]
	v_cvt_scalef32_pk_f32_fp4 v[64:65], v117, 1.0 op_sel:[1,1,0]
	v_pk_fma_f32 v[116:117], v[64:65], v[130:131], v[120:121] op_sel_hi:[1,0,1]
	v_cvt_scalef32_pk_f32_fp4 v[64:65], v118, 1.0
	v_pk_fma_f32 v[120:121], v[64:65], v[130:131], v[124:125] op_sel_hi:[1,0,1]
	v_cvt_scalef32_pk_f32_fp4 v[64:65], v118, 1.0 op_sel:[1,0,0]
	v_pk_fma_f32 v[186:187], v[64:65], v[130:131], v[140:141] op_sel_hi:[1,0,1]
	v_cvt_scalef32_pk_f32_fp4 v[64:65], v118, 1.0 op_sel:[0,1,0]
	v_pk_fma_f32 v[188:189], v[64:65], v[130:131], v[142:143] op_sel_hi:[1,0,1]
	v_cvt_scalef32_pk_f32_fp4 v[64:65], v118, 1.0 op_sel:[1,1,0]
	v_pk_fma_f32 v[190:191], v[64:65], v[130:131], v[144:145] op_sel_hi:[1,0,1]
	v_cvt_scalef32_pk_f32_fp4 v[64:65], v119, 1.0
	v_pk_fma_f32 v[192:193], v[64:65], v[130:131], v[146:147] op_sel_hi:[1,0,1]
	v_cvt_scalef32_pk_f32_fp4 v[64:65], v119, 1.0 op_sel:[1,0,0]
	v_pk_fma_f32 v[194:195], v[64:65], v[130:131], v[148:149] op_sel_hi:[1,0,1]
	v_cvt_scalef32_pk_f32_fp4 v[64:65], v119, 1.0 op_sel:[0,1,0]
	v_pk_fma_f32 v[196:197], v[64:65], v[130:131], v[150:151] op_sel_hi:[1,0,1]
	v_cvt_scalef32_pk_f32_fp4 v[64:65], v119, 1.0 op_sel:[1,1,0]
	v_pk_fma_f32 v[118:119], v[64:65], v[130:131], v[122:123] op_sel_hi:[1,0,1]
	s_waitcnt vmcnt(16)
	v_cvt_scalef32_pk_f32_fp4 v[64:65], v100, 1.0
	v_pk_fma_f32 v[122:123], v[64:65], v[130:131], v[126:127] op_sel_hi:[1,0,1]
	v_cvt_scalef32_pk_f32_fp4 v[64:65], v100, 1.0 op_sel:[1,0,0]
	v_pk_fma_f32 v[126:127], v[64:65], v[130:131], v[152:153] op_sel_hi:[1,0,1]
	v_cvt_scalef32_pk_f32_fp4 v[64:65], v100, 1.0 op_sel:[0,1,0]
	v_pk_fma_f32 v[198:199], v[64:65], v[130:131], v[154:155] op_sel_hi:[1,0,1]
	v_cvt_scalef32_pk_f32_fp4 v[64:65], v100, 1.0 op_sel:[1,1,0]
	v_pk_fma_f32 v[200:201], v[64:65], v[130:131], v[156:157] op_sel_hi:[1,0,1]
	v_cvt_scalef32_pk_f32_fp4 v[64:65], v101, 1.0
	v_pk_fma_f32 v[234:235], v[64:65], v[130:131], v[158:159] op_sel_hi:[1,0,1]
	v_cvt_scalef32_pk_f32_fp4 v[64:65], v101, 1.0 op_sel:[1,0,0]
	v_pk_fma_f32 v[236:237], v[64:65], v[130:131], v[160:161] op_sel_hi:[1,0,1]
	v_cvt_scalef32_pk_f32_fp4 v[64:65], v101, 1.0 op_sel:[0,1,0]
	v_pk_fma_f32 v[238:239], v[64:65], v[130:131], v[162:163] op_sel_hi:[1,0,1]
	v_cvt_scalef32_pk_f32_fp4 v[64:65], v101, 1.0 op_sel:[1,1,0]
	v_pk_fma_f32 v[100:101], v[64:65], v[130:131], v[104:105] op_sel_hi:[1,0,1]
	v_cvt_scalef32_pk_f32_fp4 v[64:65], v102, 1.0
	v_pk_fma_f32 v[104:105], v[64:65], v[130:131], v[112:113] op_sel_hi:[1,0,1]
	v_cvt_scalef32_pk_f32_fp4 v[64:65], v102, 1.0 op_sel:[1,0,0]
	v_pk_fma_f32 v[112:113], v[64:65], v[130:131], v[164:165] op_sel_hi:[1,0,1]
	v_cvt_scalef32_pk_f32_fp4 v[64:65], v102, 1.0 op_sel:[0,1,0]
	v_pk_fma_f32 v[240:241], v[64:65], v[130:131], v[166:167] op_sel_hi:[1,0,1]
	v_cvt_scalef32_pk_f32_fp4 v[64:65], v102, 1.0 op_sel:[1,1,0]
	v_pk_fma_f32 v[242:243], v[64:65], v[130:131], v[168:169] op_sel_hi:[1,0,1]
	v_cvt_scalef32_pk_f32_fp4 v[64:65], v103, 1.0
	v_pk_fma_f32 v[244:245], v[64:65], v[130:131], v[170:171] op_sel_hi:[1,0,1]
	v_cvt_scalef32_pk_f32_fp4 v[64:65], v103, 1.0 op_sel:[1,0,0]
	v_pk_fma_f32 v[246:247], v[64:65], v[130:131], v[172:173] op_sel_hi:[1,0,1]
	v_cvt_scalef32_pk_f32_fp4 v[64:65], v103, 1.0 op_sel:[0,1,0]
	v_pk_fma_f32 v[248:249], v[64:65], v[130:131], v[174:175] op_sel_hi:[1,0,1]
	v_cvt_scalef32_pk_f32_fp4 v[64:65], v103, 1.0 op_sel:[1,1,0]
	v_pk_fma_f32 v[102:103], v[64:65], v[130:131], v[106:107] op_sel_hi:[1,0,1]
	v_lshl_or_b32 v64, v67, 9, v203
	global_load_dwordx4 v[68:71], v64, s[46:47]
	s_nop 0
	global_load_dwordx4 v[64:67], v64, s[46:47] offset:256
	v_mov_b32_e32 v106, v131
	s_waitcnt vmcnt(17)
	v_cvt_scalef32_pk_f32_fp4 v[124:125], v108, 1.0
	v_pk_fma_f32 v[124:125], v[124:125], v[106:107], v[114:115] op_sel_hi:[1,0,1]
	v_cvt_scalef32_pk_f32_fp4 v[114:115], v108, 1.0 op_sel:[1,0,0]
	v_pk_fma_f32 v[130:131], v[114:115], v[106:107], v[128:129] op_sel_hi:[1,0,1]
	v_cvt_scalef32_pk_f32_fp4 v[114:115], v108, 1.0 op_sel:[0,1,0]
	v_pk_fma_f32 v[138:139], v[114:115], v[106:107], v[176:177] op_sel_hi:[1,0,1]
	v_cvt_scalef32_pk_f32_fp4 v[114:115], v108, 1.0 op_sel:[1,1,0]
	v_pk_fma_f32 v[140:141], v[114:115], v[106:107], v[178:179] op_sel_hi:[1,0,1]
	v_cvt_scalef32_pk_f32_fp4 v[114:115], v109, 1.0
	v_pk_fma_f32 v[142:143], v[114:115], v[106:107], v[180:181] op_sel_hi:[1,0,1]
	v_cvt_scalef32_pk_f32_fp4 v[114:115], v109, 1.0 op_sel:[1,0,0]
	v_pk_fma_f32 v[144:145], v[114:115], v[106:107], v[182:183] op_sel_hi:[1,0,1]
	v_cvt_scalef32_pk_f32_fp4 v[114:115], v109, 1.0 op_sel:[0,1,0]
	v_cvt_scalef32_pk_f32_fp4 v[108:109], v109, 1.0 op_sel:[1,1,0]
	v_pk_fma_f32 v[148:149], v[108:109], v[106:107], v[116:117] op_sel_hi:[1,0,1]
	v_cvt_scalef32_pk_f32_fp4 v[108:109], v110, 1.0
	v_pk_fma_f32 v[150:151], v[108:109], v[106:107], v[120:121] op_sel_hi:[1,0,1]
	v_cvt_scalef32_pk_f32_fp4 v[108:109], v110, 1.0 op_sel:[1,0,0]
	v_pk_fma_f32 v[152:153], v[108:109], v[106:107], v[186:187] op_sel_hi:[1,0,1]
	v_cvt_scalef32_pk_f32_fp4 v[108:109], v110, 1.0 op_sel:[0,1,0]
	v_pk_fma_f32 v[154:155], v[108:109], v[106:107], v[188:189] op_sel_hi:[1,0,1]
	v_cvt_scalef32_pk_f32_fp4 v[108:109], v110, 1.0 op_sel:[1,1,0]
	v_pk_fma_f32 v[156:157], v[108:109], v[106:107], v[190:191] op_sel_hi:[1,0,1]
	v_cvt_scalef32_pk_f32_fp4 v[108:109], v111, 1.0
	v_pk_fma_f32 v[158:159], v[108:109], v[106:107], v[192:193] op_sel_hi:[1,0,1]
	v_cvt_scalef32_pk_f32_fp4 v[108:109], v111, 1.0 op_sel:[1,0,0]
	v_pk_fma_f32 v[160:161], v[108:109], v[106:107], v[194:195] op_sel_hi:[1,0,1]
	v_cvt_scalef32_pk_f32_fp4 v[108:109], v111, 1.0 op_sel:[0,1,0]
	v_pk_fma_f32 v[162:163], v[108:109], v[106:107], v[196:197] op_sel_hi:[1,0,1]
	v_cvt_scalef32_pk_f32_fp4 v[108:109], v111, 1.0 op_sel:[1,1,0]
	v_pk_fma_f32 v[164:165], v[108:109], v[106:107], v[118:119] op_sel_hi:[1,0,1]
	s_waitcnt vmcnt(16)
	v_cvt_scalef32_pk_f32_fp4 v[108:109], v96, 1.0
	v_pk_fma_f32 v[166:167], v[108:109], v[106:107], v[122:123] op_sel_hi:[1,0,1]
	v_cvt_scalef32_pk_f32_fp4 v[108:109], v96, 1.0 op_sel:[1,0,0]
	v_pk_fma_f32 v[168:169], v[108:109], v[106:107], v[126:127] op_sel_hi:[1,0,1]
	v_cvt_scalef32_pk_f32_fp4 v[108:109], v96, 1.0 op_sel:[0,1,0]
	v_pk_fma_f32 v[170:171], v[108:109], v[106:107], v[198:199] op_sel_hi:[1,0,1]
	v_cvt_scalef32_pk_f32_fp4 v[108:109], v96, 1.0 op_sel:[1,1,0]
	v_pk_fma_f32 v[172:173], v[108:109], v[106:107], v[200:201] op_sel_hi:[1,0,1]
	v_cvt_scalef32_pk_f32_fp4 v[108:109], v97, 1.0
	v_pk_fma_f32 v[174:175], v[108:109], v[106:107], v[234:235] op_sel_hi:[1,0,1]
	v_cvt_scalef32_pk_f32_fp4 v[108:109], v97, 1.0 op_sel:[1,0,0]
	v_pk_fma_f32 v[176:177], v[108:109], v[106:107], v[236:237] op_sel_hi:[1,0,1]
	v_cvt_scalef32_pk_f32_fp4 v[108:109], v97, 1.0 op_sel:[0,1,0]
	v_cvt_scalef32_pk_f32_fp4 v[96:97], v97, 1.0 op_sel:[1,1,0]
	v_pk_fma_f32 v[180:181], v[96:97], v[106:107], v[100:101] op_sel_hi:[1,0,1]
	v_cvt_scalef32_pk_f32_fp4 v[96:97], v98, 1.0
	v_pk_fma_f32 v[182:183], v[96:97], v[106:107], v[104:105] op_sel_hi:[1,0,1]
	v_cvt_scalef32_pk_f32_fp4 v[96:97], v98, 1.0 op_sel:[1,0,0]
	v_pk_fma_f32 v[146:147], v[114:115], v[106:107], v[184:185] op_sel_hi:[1,0,1]
	v_pk_fma_f32 v[184:185], v[96:97], v[106:107], v[112:113] op_sel_hi:[1,0,1]
	v_cvt_scalef32_pk_f32_fp4 v[96:97], v98, 1.0 op_sel:[0,1,0]
	v_pk_fma_f32 v[186:187], v[96:97], v[106:107], v[240:241] op_sel_hi:[1,0,1]
	v_cvt_scalef32_pk_f32_fp4 v[96:97], v98, 1.0 op_sel:[1,1,0]
	v_pk_fma_f32 v[188:189], v[96:97], v[106:107], v[242:243] op_sel_hi:[1,0,1]
	v_cvt_scalef32_pk_f32_fp4 v[96:97], v99, 1.0
	v_pk_fma_f32 v[190:191], v[96:97], v[106:107], v[244:245] op_sel_hi:[1,0,1]
	v_cvt_scalef32_pk_f32_fp4 v[96:97], v99, 1.0 op_sel:[1,0,0]
	v_pk_fma_f32 v[192:193], v[96:97], v[106:107], v[246:247] op_sel_hi:[1,0,1]
	v_cvt_scalef32_pk_f32_fp4 v[96:97], v99, 1.0 op_sel:[0,1,0]
	v_pk_fma_f32 v[194:195], v[96:97], v[106:107], v[248:249] op_sel_hi:[1,0,1]
	v_cvt_scalef32_pk_f32_fp4 v[96:97], v99, 1.0 op_sel:[1,1,0]
	v_pk_fma_f32 v[178:179], v[108:109], v[106:107], v[238:239] op_sel_hi:[1,0,1]
	v_pk_fma_f32 v[196:197], v[96:97], v[106:107], v[102:103] op_sel_hi:[1,0,1]
	v_cvt_f32_u32_e32 v98, v233
	ds_read_b64 v[96:97], v205 offset:6144
	ds_read_b32 v99, v229 offset:2112
	s_cmp_gt_u32 s65, 27
	v_fmac_f32_e32 v98, 0xc3000000, v231
	s_waitcnt lgkmcnt(1)
	v_pk_mul_f32 v[96:97], v[96:97], v[136:137]
	s_nop 0
	v_sub_f32_e32 v97, v98, v97
	v_mul_f32_e32 v96, v96, v97
	v_mul_f32_e32 v97, 0x3f3504f3, v96
	v_fma_f32 v98, |v97|, s61, 1.0
	v_div_scale_f32 v100, s[66:67], v98, v98, 1.0
	v_rcp_f32_e32 v101, v100
	v_div_scale_f32 v102, vcc, 1.0, v98, 1.0
	v_mul_f32_e32 v96, 0.5, v96
	v_fma_f32 v103, -v100, v101, 1.0
	v_fmac_f32_e32 v101, v103, v101
	v_mul_f32_e32 v103, v102, v101
	v_fma_f32 v104, -v100, v103, v102
	v_fmac_f32_e32 v103, v104, v101
	v_fma_f32 v100, -v100, v103, v102
	v_div_fmas_f32 v100, v100, v101, v103
	v_div_fixup_f32 v98, v100, v98, 1.0
	v_mul_f32_e64 v101, |v97|, |v97|
	v_fmamk_f32 v100, v98, 0x3f87dc22, v210
	v_mul_f32_e32 v101, 0xbfb8aa3b, v101
	v_fmaak_f32 v100, v98, v100, 0x3fb5f0e3
	v_exp_f32_e32 v101, v101
	v_fmaak_f32 v100, v98, v100, 0xbe91a98e
	v_fmaak_f32 v100, v98, v100, 0x3e827906
	v_mul_f32_e32 v98, v98, v100
	v_fma_f32 v98, -v101, v98, 1.0
	v_bfi_b32 v97, s62, v98, v97
	v_add_f32_e32 v97, 1.0, v97
	v_mul_f32_e32 v96, v96, v97
	s_waitcnt lgkmcnt(0)
	v_mul_f32_e32 v96, v99, v96
	v_mul_f32_e32 v96, v230, v96
	ds_write_b32 v229, v96 offset:4160
	s_cbranch_scc0 .LBB0_1753
	ds_read_b128 v[0:3], v204 offset:464
	ds_read_b128 v[14:17], v204 offset:4544
	s_waitcnt vmcnt(7)
	v_cvt_scalef32_pk_f32_fp4 v[8:9], v92, 1.0
	s_waitcnt lgkmcnt(1)
	v_lshl_or_b32 v0, v0, 9, v203
	global_load_dwordx4 v[20:23], v0, s[46:47]
	global_load_dwordx4 v[4:7], v0, s[46:47] offset:256
	s_waitcnt lgkmcnt(0)
	v_pk_fma_f32 v[12:13], v[8:9], v[14:15], v[124:125] op_sel_hi:[1,0,1]
	v_cvt_scalef32_pk_f32_fp4 v[8:9], v92, 1.0 op_sel:[1,0,0]
	v_pk_fma_f32 v[18:19], v[8:9], v[14:15], v[130:131] op_sel_hi:[1,0,1]
	v_cvt_scalef32_pk_f32_fp4 v[8:9], v92, 1.0 op_sel:[0,1,0]
	v_pk_fma_f32 v[24:25], v[8:9], v[14:15], v[138:139] op_sel_hi:[1,0,1]
	v_cvt_scalef32_pk_f32_fp4 v[8:9], v92, 1.0 op_sel:[1,1,0]
	v_pk_fma_f32 v[26:27], v[8:9], v[14:15], v[140:141] op_sel_hi:[1,0,1]
	v_cvt_scalef32_pk_f32_fp4 v[8:9], v93, 1.0
	v_pk_fma_f32 v[32:33], v[8:9], v[14:15], v[142:143] op_sel_hi:[1,0,1]
	v_cvt_scalef32_pk_f32_fp4 v[8:9], v93, 1.0 op_sel:[1,0,0]
	v_pk_fma_f32 v[34:35], v[8:9], v[14:15], v[144:145] op_sel_hi:[1,0,1]
	v_cvt_scalef32_pk_f32_fp4 v[8:9], v93, 1.0 op_sel:[0,1,0]
	v_pk_fma_f32 v[36:37], v[8:9], v[14:15], v[146:147] op_sel_hi:[1,0,1]
	v_cvt_scalef32_pk_f32_fp4 v[8:9], v93, 1.0 op_sel:[1,1,0]
	v_pk_fma_f32 v[38:39], v[8:9], v[14:15], v[148:149] op_sel_hi:[1,0,1]
	v_cvt_scalef32_pk_f32_fp4 v[8:9], v94, 1.0
	v_pk_fma_f32 v[40:41], v[8:9], v[14:15], v[150:151] op_sel_hi:[1,0,1]
	v_cvt_scalef32_pk_f32_fp4 v[8:9], v94, 1.0 op_sel:[1,0,0]
	v_pk_fma_f32 v[42:43], v[8:9], v[14:15], v[152:153] op_sel_hi:[1,0,1]
	v_cvt_scalef32_pk_f32_fp4 v[8:9], v94, 1.0 op_sel:[0,1,0]
	v_pk_fma_f32 v[44:45], v[8:9], v[14:15], v[154:155] op_sel_hi:[1,0,1]
	v_cvt_scalef32_pk_f32_fp4 v[8:9], v94, 1.0 op_sel:[1,1,0]
	v_pk_fma_f32 v[46:47], v[8:9], v[14:15], v[156:157] op_sel_hi:[1,0,1]
	v_cvt_scalef32_pk_f32_fp4 v[8:9], v95, 1.0
	v_pk_fma_f32 v[48:49], v[8:9], v[14:15], v[158:159] op_sel_hi:[1,0,1]
	v_cvt_scalef32_pk_f32_fp4 v[8:9], v95, 1.0 op_sel:[1,0,0]
	v_pk_fma_f32 v[50:51], v[8:9], v[14:15], v[160:161] op_sel_hi:[1,0,1]
	v_cvt_scalef32_pk_f32_fp4 v[8:9], v95, 1.0 op_sel:[0,1,0]
	v_pk_fma_f32 v[52:53], v[8:9], v[14:15], v[162:163] op_sel_hi:[1,0,1]
	v_cvt_scalef32_pk_f32_fp4 v[8:9], v95, 1.0 op_sel:[1,1,0]
	v_pk_fma_f32 v[54:55], v[8:9], v[14:15], v[164:165] op_sel_hi:[1,0,1]
	s_waitcnt vmcnt(8)
	v_cvt_scalef32_pk_f32_fp4 v[8:9], v88, 1.0
	v_pk_fma_f32 v[56:57], v[8:9], v[14:15], v[166:167] op_sel_hi:[1,0,1]
	v_cvt_scalef32_pk_f32_fp4 v[8:9], v88, 1.0 op_sel:[1,0,0]
	v_pk_fma_f32 v[58:59], v[8:9], v[14:15], v[168:169] op_sel_hi:[1,0,1]
	v_cvt_scalef32_pk_f32_fp4 v[8:9], v88, 1.0 op_sel:[0,1,0]
	v_pk_fma_f32 v[60:61], v[8:9], v[14:15], v[170:171] op_sel_hi:[1,0,1]
	v_cvt_scalef32_pk_f32_fp4 v[8:9], v88, 1.0 op_sel:[1,1,0]
	v_pk_fma_f32 v[62:63], v[8:9], v[14:15], v[172:173] op_sel_hi:[1,0,1]
	v_cvt_scalef32_pk_f32_fp4 v[8:9], v89, 1.0
	v_pk_fma_f32 v[92:93], v[8:9], v[14:15], v[174:175] op_sel_hi:[1,0,1]
	v_cvt_scalef32_pk_f32_fp4 v[8:9], v89, 1.0 op_sel:[1,0,0]
	v_pk_fma_f32 v[94:95], v[8:9], v[14:15], v[176:177] op_sel_hi:[1,0,1]
	v_cvt_scalef32_pk_f32_fp4 v[8:9], v89, 1.0 op_sel:[0,1,0]
	v_pk_fma_f32 v[96:97], v[8:9], v[14:15], v[178:179] op_sel_hi:[1,0,1]
	v_cvt_scalef32_pk_f32_fp4 v[8:9], v89, 1.0 op_sel:[1,1,0]
	v_pk_fma_f32 v[88:89], v[8:9], v[14:15], v[180:181] op_sel_hi:[1,0,1]
	v_cvt_scalef32_pk_f32_fp4 v[8:9], v90, 1.0
	v_pk_fma_f32 v[98:99], v[8:9], v[14:15], v[182:183] op_sel_hi:[1,0,1]
	v_cvt_scalef32_pk_f32_fp4 v[8:9], v90, 1.0 op_sel:[1,0,0]
	v_pk_fma_f32 v[100:101], v[8:9], v[14:15], v[184:185] op_sel_hi:[1,0,1]
	v_cvt_scalef32_pk_f32_fp4 v[8:9], v90, 1.0 op_sel:[0,1,0]
	v_pk_fma_f32 v[102:103], v[8:9], v[14:15], v[186:187] op_sel_hi:[1,0,1]
	v_cvt_scalef32_pk_f32_fp4 v[8:9], v90, 1.0 op_sel:[1,1,0]
	v_pk_fma_f32 v[104:105], v[8:9], v[14:15], v[188:189] op_sel_hi:[1,0,1]
	v_cvt_scalef32_pk_f32_fp4 v[8:9], v91, 1.0
	v_pk_fma_f32 v[106:107], v[8:9], v[14:15], v[190:191] op_sel_hi:[1,0,1]
	v_cvt_scalef32_pk_f32_fp4 v[8:9], v91, 1.0 op_sel:[1,0,0]
	v_pk_fma_f32 v[108:109], v[8:9], v[14:15], v[192:193] op_sel_hi:[1,0,1]
	v_cvt_scalef32_pk_f32_fp4 v[8:9], v91, 1.0 op_sel:[0,1,0]
	v_pk_fma_f32 v[110:111], v[8:9], v[14:15], v[194:195] op_sel_hi:[1,0,1]
	v_cvt_scalef32_pk_f32_fp4 v[8:9], v91, 1.0 op_sel:[1,1,0]
	v_pk_fma_f32 v[90:91], v[8:9], v[14:15], v[196:197] op_sel_hi:[1,0,1]
	v_lshl_or_b32 v0, v1, 9, v203
	global_load_dwordx4 v[28:31], v0, s[46:47]
	global_load_dwordx4 v[8:11], v0, s[46:47] offset:256
	s_waitcnt vmcnt(9)
	v_cvt_scalef32_pk_f32_fp4 v[0:1], v84, 1.0
	v_pk_fma_f32 v[0:1], v[0:1], v[14:15], v[12:13] op_sel:[0,1,0]
	v_cvt_scalef32_pk_f32_fp4 v[12:13], v84, 1.0 op_sel:[1,0,0]
	v_pk_fma_f32 v[18:19], v[12:13], v[14:15], v[18:19] op_sel:[0,1,0]
	v_cvt_scalef32_pk_f32_fp4 v[12:13], v84, 1.0 op_sel:[0,1,0]
	v_pk_fma_f32 v[24:25], v[12:13], v[14:15], v[24:25] op_sel:[0,1,0]
	v_cvt_scalef32_pk_f32_fp4 v[12:13], v84, 1.0 op_sel:[1,1,0]
	v_pk_fma_f32 v[26:27], v[12:13], v[14:15], v[26:27] op_sel:[0,1,0]
	v_cvt_scalef32_pk_f32_fp4 v[12:13], v85, 1.0
	v_pk_fma_f32 v[112:113], v[12:13], v[14:15], v[32:33] op_sel:[0,1,0]
	v_cvt_scalef32_pk_f32_fp4 v[12:13], v85, 1.0 op_sel:[1,0,0]
	v_pk_fma_f32 v[114:115], v[12:13], v[14:15], v[34:35] op_sel:[0,1,0]
	v_cvt_scalef32_pk_f32_fp4 v[12:13], v85, 1.0 op_sel:[0,1,0]
	v_pk_fma_f32 v[36:37], v[12:13], v[14:15], v[36:37] op_sel:[0,1,0]
	v_cvt_scalef32_pk_f32_fp4 v[12:13], v85, 1.0 op_sel:[1,1,0]
	v_pk_fma_f32 v[38:39], v[12:13], v[14:15], v[38:39] op_sel:[0,1,0]
	v_cvt_scalef32_pk_f32_fp4 v[12:13], v86, 1.0
	v_pk_fma_f32 v[40:41], v[12:13], v[14:15], v[40:41] op_sel:[0,1,0]
	v_cvt_scalef32_pk_f32_fp4 v[12:13], v86, 1.0 op_sel:[1,0,0]
	v_pk_fma_f32 v[42:43], v[12:13], v[14:15], v[42:43] op_sel:[0,1,0]
	v_cvt_scalef32_pk_f32_fp4 v[12:13], v86, 1.0 op_sel:[0,1,0]
	v_pk_fma_f32 v[44:45], v[12:13], v[14:15], v[44:45] op_sel:[0,1,0]
	v_cvt_scalef32_pk_f32_fp4 v[12:13], v86, 1.0 op_sel:[1,1,0]
	v_pk_fma_f32 v[46:47], v[12:13], v[14:15], v[46:47] op_sel:[0,1,0]
	v_cvt_scalef32_pk_f32_fp4 v[12:13], v87, 1.0
	v_pk_fma_f32 v[48:49], v[12:13], v[14:15], v[48:49] op_sel:[0,1,0]
	v_cvt_scalef32_pk_f32_fp4 v[12:13], v87, 1.0 op_sel:[1,0,0]
	v_pk_fma_f32 v[50:51], v[12:13], v[14:15], v[50:51] op_sel:[0,1,0]
	v_cvt_scalef32_pk_f32_fp4 v[12:13], v87, 1.0 op_sel:[0,1,0]
	v_pk_fma_f32 v[52:53], v[12:13], v[14:15], v[52:53] op_sel:[0,1,0]
	v_cvt_scalef32_pk_f32_fp4 v[12:13], v87, 1.0 op_sel:[1,1,0]
	v_pk_fma_f32 v[54:55], v[12:13], v[14:15], v[54:55] op_sel:[0,1,0]
	s_waitcnt vmcnt(8)
	v_cvt_scalef32_pk_f32_fp4 v[12:13], v80, 1.0
	v_pk_fma_f32 v[56:57], v[12:13], v[14:15], v[56:57] op_sel:[0,1,0]
	v_cvt_scalef32_pk_f32_fp4 v[12:13], v80, 1.0 op_sel:[1,0,0]
	v_pk_fma_f32 v[58:59], v[12:13], v[14:15], v[58:59] op_sel:[0,1,0]
	v_cvt_scalef32_pk_f32_fp4 v[12:13], v80, 1.0 op_sel:[0,1,0]
	v_pk_fma_f32 v[60:61], v[12:13], v[14:15], v[60:61] op_sel:[0,1,0]
	v_cvt_scalef32_pk_f32_fp4 v[12:13], v80, 1.0 op_sel:[1,1,0]
	v_pk_fma_f32 v[62:63], v[12:13], v[14:15], v[62:63] op_sel:[0,1,0]
	v_cvt_scalef32_pk_f32_fp4 v[12:13], v81, 1.0
	v_pk_fma_f32 v[84:85], v[12:13], v[14:15], v[92:93] op_sel:[0,1,0]
	v_cvt_scalef32_pk_f32_fp4 v[12:13], v81, 1.0 op_sel:[1,0,0]
	v_pk_fma_f32 v[86:87], v[12:13], v[14:15], v[94:95] op_sel:[0,1,0]
	v_cvt_scalef32_pk_f32_fp4 v[12:13], v81, 1.0 op_sel:[0,1,0]
	v_pk_fma_f32 v[92:93], v[12:13], v[14:15], v[96:97] op_sel:[0,1,0]
	v_cvt_scalef32_pk_f32_fp4 v[12:13], v81, 1.0 op_sel:[1,1,0]
	v_pk_fma_f32 v[80:81], v[12:13], v[14:15], v[88:89] op_sel:[0,1,0]
	v_cvt_scalef32_pk_f32_fp4 v[12:13], v82, 1.0
	v_pk_fma_f32 v[88:89], v[12:13], v[14:15], v[98:99] op_sel:[0,1,0]
	v_cvt_scalef32_pk_f32_fp4 v[12:13], v82, 1.0 op_sel:[1,0,0]
	v_pk_fma_f32 v[94:95], v[12:13], v[14:15], v[100:101] op_sel:[0,1,0]
	v_cvt_scalef32_pk_f32_fp4 v[12:13], v82, 1.0 op_sel:[0,1,0]
	v_pk_fma_f32 v[96:97], v[12:13], v[14:15], v[102:103] op_sel:[0,1,0]
	v_cvt_scalef32_pk_f32_fp4 v[12:13], v82, 1.0 op_sel:[1,1,0]
	v_pk_fma_f32 v[98:99], v[12:13], v[14:15], v[104:105] op_sel:[0,1,0]
	v_cvt_scalef32_pk_f32_fp4 v[12:13], v83, 1.0
	v_pk_fma_f32 v[100:101], v[12:13], v[14:15], v[106:107] op_sel:[0,1,0]
	v_cvt_scalef32_pk_f32_fp4 v[12:13], v83, 1.0 op_sel:[1,0,0]
	v_pk_fma_f32 v[102:103], v[12:13], v[14:15], v[108:109] op_sel:[0,1,0]
	v_cvt_scalef32_pk_f32_fp4 v[12:13], v83, 1.0 op_sel:[0,1,0]
	v_pk_fma_f32 v[104:105], v[12:13], v[14:15], v[110:111] op_sel:[0,1,0]
	v_cvt_scalef32_pk_f32_fp4 v[12:13], v83, 1.0 op_sel:[1,1,0]
	v_pk_fma_f32 v[82:83], v[12:13], v[14:15], v[90:91] op_sel:[0,1,0]
	v_lshl_or_b32 v2, v2, 9, v203
	global_load_dwordx4 v[32:35], v2, s[46:47]
	global_load_dwordx4 v[12:15], v2, s[46:47] offset:256
	s_waitcnt vmcnt(9)
	v_cvt_scalef32_pk_f32_fp4 v[90:91], v76, 1.0
	v_pk_fma_f32 v[90:91], v[90:91], v[16:17], v[0:1] op_sel_hi:[1,0,1]
	v_cvt_scalef32_pk_f32_fp4 v[0:1], v76, 1.0 op_sel:[1,0,0]
	v_pk_fma_f32 v[18:19], v[0:1], v[16:17], v[18:19] op_sel_hi:[1,0,1]
	v_cvt_scalef32_pk_f32_fp4 v[0:1], v76, 1.0 op_sel:[0,1,0]
	v_pk_fma_f32 v[106:107], v[0:1], v[16:17], v[24:25] op_sel_hi:[1,0,1]
	v_cvt_scalef32_pk_f32_fp4 v[0:1], v76, 1.0 op_sel:[1,1,0]
	v_pk_fma_f32 v[108:109], v[0:1], v[16:17], v[26:27] op_sel_hi:[1,0,1]
	v_cvt_scalef32_pk_f32_fp4 v[0:1], v77, 1.0
	v_pk_fma_f32 v[110:111], v[0:1], v[16:17], v[112:113] op_sel_hi:[1,0,1]
	v_cvt_scalef32_pk_f32_fp4 v[0:1], v77, 1.0 op_sel:[1,0,0]
	v_pk_fma_f32 v[112:113], v[0:1], v[16:17], v[114:115] op_sel_hi:[1,0,1]
	v_cvt_scalef32_pk_f32_fp4 v[0:1], v77, 1.0 op_sel:[0,1,0]
	v_pk_fma_f32 v[36:37], v[0:1], v[16:17], v[36:37] op_sel_hi:[1,0,1]
	v_cvt_scalef32_pk_f32_fp4 v[0:1], v77, 1.0 op_sel:[1,1,0]
	v_pk_fma_f32 v[38:39], v[0:1], v[16:17], v[38:39] op_sel_hi:[1,0,1]
	v_cvt_scalef32_pk_f32_fp4 v[0:1], v78, 1.0
	v_pk_fma_f32 v[40:41], v[0:1], v[16:17], v[40:41] op_sel_hi:[1,0,1]
	v_cvt_scalef32_pk_f32_fp4 v[0:1], v78, 1.0 op_sel:[1,0,0]
	v_pk_fma_f32 v[42:43], v[0:1], v[16:17], v[42:43] op_sel_hi:[1,0,1]
	v_cvt_scalef32_pk_f32_fp4 v[0:1], v78, 1.0 op_sel:[0,1,0]
	v_pk_fma_f32 v[44:45], v[0:1], v[16:17], v[44:45] op_sel_hi:[1,0,1]
	v_cvt_scalef32_pk_f32_fp4 v[0:1], v78, 1.0 op_sel:[1,1,0]
	v_pk_fma_f32 v[46:47], v[0:1], v[16:17], v[46:47] op_sel_hi:[1,0,1]
	v_cvt_scalef32_pk_f32_fp4 v[0:1], v79, 1.0
	v_pk_fma_f32 v[48:49], v[0:1], v[16:17], v[48:49] op_sel_hi:[1,0,1]
	v_cvt_scalef32_pk_f32_fp4 v[0:1], v79, 1.0 op_sel:[1,0,0]
	v_pk_fma_f32 v[50:51], v[0:1], v[16:17], v[50:51] op_sel_hi:[1,0,1]
	v_cvt_scalef32_pk_f32_fp4 v[0:1], v79, 1.0 op_sel:[0,1,0]
	v_pk_fma_f32 v[52:53], v[0:1], v[16:17], v[52:53] op_sel_hi:[1,0,1]
	v_cvt_scalef32_pk_f32_fp4 v[0:1], v79, 1.0 op_sel:[1,1,0]
	v_pk_fma_f32 v[54:55], v[0:1], v[16:17], v[54:55] op_sel_hi:[1,0,1]
	s_waitcnt vmcnt(8)
	v_cvt_scalef32_pk_f32_fp4 v[0:1], v72, 1.0
	v_pk_fma_f32 v[56:57], v[0:1], v[16:17], v[56:57] op_sel_hi:[1,0,1]
	v_cvt_scalef32_pk_f32_fp4 v[0:1], v72, 1.0 op_sel:[1,0,0]
	v_pk_fma_f32 v[58:59], v[0:1], v[16:17], v[58:59] op_sel_hi:[1,0,1]
	v_cvt_scalef32_pk_f32_fp4 v[0:1], v72, 1.0 op_sel:[0,1,0]
	v_pk_fma_f32 v[60:61], v[0:1], v[16:17], v[60:61] op_sel_hi:[1,0,1]
	v_cvt_scalef32_pk_f32_fp4 v[0:1], v72, 1.0 op_sel:[1,1,0]
	v_pk_fma_f32 v[62:63], v[0:1], v[16:17], v[62:63] op_sel_hi:[1,0,1]
	v_cvt_scalef32_pk_f32_fp4 v[0:1], v73, 1.0
	v_pk_fma_f32 v[76:77], v[0:1], v[16:17], v[84:85] op_sel_hi:[1,0,1]
	v_cvt_scalef32_pk_f32_fp4 v[0:1], v73, 1.0 op_sel:[1,0,0]
	v_pk_fma_f32 v[78:79], v[0:1], v[16:17], v[86:87] op_sel_hi:[1,0,1]
	v_cvt_scalef32_pk_f32_fp4 v[0:1], v73, 1.0 op_sel:[0,1,0]
	v_pk_fma_f32 v[84:85], v[0:1], v[16:17], v[92:93] op_sel_hi:[1,0,1]
	v_cvt_scalef32_pk_f32_fp4 v[0:1], v73, 1.0 op_sel:[1,1,0]
	v_pk_fma_f32 v[72:73], v[0:1], v[16:17], v[80:81] op_sel_hi:[1,0,1]
	v_cvt_scalef32_pk_f32_fp4 v[0:1], v74, 1.0
	v_pk_fma_f32 v[80:81], v[0:1], v[16:17], v[88:89] op_sel_hi:[1,0,1]
	v_cvt_scalef32_pk_f32_fp4 v[0:1], v74, 1.0 op_sel:[1,0,0]
	v_pk_fma_f32 v[86:87], v[0:1], v[16:17], v[94:95] op_sel_hi:[1,0,1]
	v_cvt_scalef32_pk_f32_fp4 v[0:1], v74, 1.0 op_sel:[0,1,0]
	v_pk_fma_f32 v[88:89], v[0:1], v[16:17], v[96:97] op_sel_hi:[1,0,1]
	v_cvt_scalef32_pk_f32_fp4 v[0:1], v74, 1.0 op_sel:[1,1,0]
	v_pk_fma_f32 v[92:93], v[0:1], v[16:17], v[98:99] op_sel_hi:[1,0,1]
	v_cvt_scalef32_pk_f32_fp4 v[0:1], v75, 1.0
	v_pk_fma_f32 v[94:95], v[0:1], v[16:17], v[100:101] op_sel_hi:[1,0,1]
	v_cvt_scalef32_pk_f32_fp4 v[0:1], v75, 1.0 op_sel:[1,0,0]
	v_pk_fma_f32 v[96:97], v[0:1], v[16:17], v[102:103] op_sel_hi:[1,0,1]
	v_cvt_scalef32_pk_f32_fp4 v[0:1], v75, 1.0 op_sel:[0,1,0]
	v_pk_fma_f32 v[98:99], v[0:1], v[16:17], v[104:105] op_sel_hi:[1,0,1]
	v_cvt_scalef32_pk_f32_fp4 v[0:1], v75, 1.0 op_sel:[1,1,0]
	v_pk_fma_f32 v[74:75], v[0:1], v[16:17], v[82:83] op_sel_hi:[1,0,1]
	v_lshl_or_b32 v0, v3, 9, v203
	global_load_dwordx4 v[24:27], v0, s[46:47]
	s_nop 0
	global_load_dwordx4 v[0:3], v0, s[46:47] offset:256
	v_mov_b32_e32 v16, v17
	s_waitcnt vmcnt(9)
	v_cvt_scalef32_pk_f32_fp4 v[82:83], v68, 1.0
	v_pk_fma_f32 v[82:83], v[82:83], v[16:17], v[90:91] op_sel_hi:[1,0,1]
	v_cvt_scalef32_pk_f32_fp4 v[90:91], v68, 1.0 op_sel:[1,0,0]
	v_pk_fma_f32 v[90:91], v[90:91], v[16:17], v[18:19] op_sel_hi:[1,0,1]
	v_cvt_scalef32_pk_f32_fp4 v[18:19], v68, 1.0 op_sel:[0,1,0]
	v_pk_fma_f32 v[100:101], v[18:19], v[16:17], v[106:107] op_sel_hi:[1,0,1]
	v_cvt_scalef32_pk_f32_fp4 v[18:19], v68, 1.0 op_sel:[1,1,0]
	v_pk_fma_f32 v[102:103], v[18:19], v[16:17], v[108:109] op_sel_hi:[1,0,1]
	v_cvt_scalef32_pk_f32_fp4 v[18:19], v69, 1.0
	v_pk_fma_f32 v[104:105], v[18:19], v[16:17], v[110:111] op_sel_hi:[1,0,1]
	v_cvt_scalef32_pk_f32_fp4 v[18:19], v69, 1.0 op_sel:[1,0,0]
	v_pk_fma_f32 v[106:107], v[18:19], v[16:17], v[112:113] op_sel_hi:[1,0,1]
	v_cvt_scalef32_pk_f32_fp4 v[18:19], v69, 1.0 op_sel:[0,1,0]
	v_pk_fma_f32 v[108:109], v[18:19], v[16:17], v[36:37] op_sel_hi:[1,0,1]
	v_cvt_scalef32_pk_f32_fp4 v[18:19], v69, 1.0 op_sel:[1,1,0]
	v_pk_fma_f32 v[68:69], v[18:19], v[16:17], v[38:39] op_sel_hi:[1,0,1]
	v_cvt_scalef32_pk_f32_fp4 v[18:19], v70, 1.0
	v_pk_fma_f32 v[40:41], v[18:19], v[16:17], v[40:41] op_sel_hi:[1,0,1]
	v_cvt_scalef32_pk_f32_fp4 v[18:19], v70, 1.0 op_sel:[1,0,0]
	v_pk_fma_f32 v[42:43], v[18:19], v[16:17], v[42:43] op_sel_hi:[1,0,1]
	v_cvt_scalef32_pk_f32_fp4 v[18:19], v70, 1.0 op_sel:[0,1,0]
	v_pk_fma_f32 v[110:111], v[18:19], v[16:17], v[44:45] op_sel_hi:[1,0,1]
	v_cvt_scalef32_pk_f32_fp4 v[18:19], v70, 1.0 op_sel:[1,1,0]
	v_pk_fma_f32 v[112:113], v[18:19], v[16:17], v[46:47] op_sel_hi:[1,0,1]
	v_cvt_scalef32_pk_f32_fp4 v[18:19], v71, 1.0
	v_pk_fma_f32 v[114:115], v[18:19], v[16:17], v[48:49] op_sel_hi:[1,0,1]
	v_cvt_scalef32_pk_f32_fp4 v[18:19], v71, 1.0 op_sel:[1,0,0]
	v_pk_fma_f32 v[116:117], v[18:19], v[16:17], v[50:51] op_sel_hi:[1,0,1]
	v_cvt_scalef32_pk_f32_fp4 v[18:19], v71, 1.0 op_sel:[0,1,0]
	v_pk_fma_f32 v[52:53], v[18:19], v[16:17], v[52:53] op_sel_hi:[1,0,1]
	v_cvt_scalef32_pk_f32_fp4 v[18:19], v71, 1.0 op_sel:[1,1,0]
	v_pk_fma_f32 v[54:55], v[18:19], v[16:17], v[54:55] op_sel_hi:[1,0,1]
	s_waitcnt vmcnt(8)
	v_cvt_scalef32_pk_f32_fp4 v[18:19], v64, 1.0
	v_pk_fma_f32 v[56:57], v[18:19], v[16:17], v[56:57] op_sel_hi:[1,0,1]
	v_cvt_scalef32_pk_f32_fp4 v[18:19], v64, 1.0 op_sel:[1,0,0]
	v_pk_fma_f32 v[58:59], v[18:19], v[16:17], v[58:59] op_sel_hi:[1,0,1]
	v_cvt_scalef32_pk_f32_fp4 v[18:19], v64, 1.0 op_sel:[0,1,0]
	v_pk_fma_f32 v[60:61], v[18:19], v[16:17], v[60:61] op_sel_hi:[1,0,1]
	v_cvt_scalef32_pk_f32_fp4 v[18:19], v64, 1.0 op_sel:[1,1,0]
	v_pk_fma_f32 v[62:63], v[18:19], v[16:17], v[62:63] op_sel_hi:[1,0,1]
	v_cvt_scalef32_pk_f32_fp4 v[18:19], v65, 1.0
	v_pk_fma_f32 v[70:71], v[18:19], v[16:17], v[76:77] op_sel_hi:[1,0,1]
	v_cvt_scalef32_pk_f32_fp4 v[18:19], v65, 1.0 op_sel:[1,0,0]
	v_pk_fma_f32 v[76:77], v[18:19], v[16:17], v[78:79] op_sel_hi:[1,0,1]
	v_cvt_scalef32_pk_f32_fp4 v[18:19], v65, 1.0 op_sel:[0,1,0]
	v_pk_fma_f32 v[78:79], v[18:19], v[16:17], v[84:85] op_sel_hi:[1,0,1]
	v_cvt_scalef32_pk_f32_fp4 v[18:19], v65, 1.0 op_sel:[1,1,0]
	v_pk_fma_f32 v[64:65], v[18:19], v[16:17], v[72:73] op_sel_hi:[1,0,1]
	v_cvt_scalef32_pk_f32_fp4 v[18:19], v66, 1.0
	v_pk_fma_f32 v[72:73], v[18:19], v[16:17], v[80:81] op_sel_hi:[1,0,1]
	v_cvt_scalef32_pk_f32_fp4 v[18:19], v66, 1.0 op_sel:[1,0,0]
	v_pk_fma_f32 v[80:81], v[18:19], v[16:17], v[86:87] op_sel_hi:[1,0,1]
	v_cvt_scalef32_pk_f32_fp4 v[18:19], v66, 1.0 op_sel:[0,1,0]
	v_pk_fma_f32 v[84:85], v[18:19], v[16:17], v[88:89] op_sel_hi:[1,0,1]
	v_cvt_scalef32_pk_f32_fp4 v[18:19], v66, 1.0 op_sel:[1,1,0]
	v_pk_fma_f32 v[86:87], v[18:19], v[16:17], v[92:93] op_sel_hi:[1,0,1]
	v_cvt_scalef32_pk_f32_fp4 v[18:19], v67, 1.0
	v_pk_fma_f32 v[88:89], v[18:19], v[16:17], v[94:95] op_sel_hi:[1,0,1]
	v_cvt_scalef32_pk_f32_fp4 v[18:19], v67, 1.0 op_sel:[1,0,0]
	v_pk_fma_f32 v[92:93], v[18:19], v[16:17], v[96:97] op_sel_hi:[1,0,1]
	v_cvt_scalef32_pk_f32_fp4 v[18:19], v67, 1.0 op_sel:[0,1,0]
	v_pk_fma_f32 v[94:95], v[18:19], v[16:17], v[98:99] op_sel_hi:[1,0,1]
	v_cvt_scalef32_pk_f32_fp4 v[18:19], v67, 1.0 op_sel:[1,1,0]
	v_pk_fma_f32 v[66:67], v[18:19], v[16:17], v[74:75] op_sel_hi:[1,0,1]
	ds_read_b128 v[48:51], v204 offset:480
	ds_read_b128 v[44:47], v204 offset:4560
	s_waitcnt vmcnt(7)
	v_cvt_scalef32_pk_f32_fp4 v[74:75], v20, 1.0
	v_cvt_scalef32_pk_f32_fp4 v[96:97], v20, 1.0 op_sel:[1,1,0]
	v_cvt_scalef32_pk_f32_fp4 v[98:99], v21, 1.0
	s_waitcnt lgkmcnt(1)
	v_lshl_or_b32 v16, v48, 9, v203
	global_load_dwordx4 v[36:39], v16, s[46:47]
	s_nop 0
	global_load_dwordx4 v[16:19], v16, s[46:47] offset:256
	s_waitcnt lgkmcnt(0)
	v_pk_fma_f32 v[74:75], v[74:75], v[44:45], v[82:83] op_sel_hi:[1,0,1]
	v_cvt_scalef32_pk_f32_fp4 v[82:83], v20, 1.0 op_sel:[1,0,0]
	v_pk_fma_f32 v[82:83], v[82:83], v[44:45], v[90:91] op_sel_hi:[1,0,1]
	v_cvt_scalef32_pk_f32_fp4 v[90:91], v20, 1.0 op_sel:[0,1,0]
	v_pk_fma_f32 v[90:91], v[90:91], v[44:45], v[100:101] op_sel_hi:[1,0,1]
	v_pk_fma_f32 v[96:97], v[96:97], v[44:45], v[102:103] op_sel_hi:[1,0,1]
	v_cvt_scalef32_pk_f32_fp4 v[100:101], v21, 1.0 op_sel:[1,0,0]
	v_cvt_scalef32_pk_f32_fp4 v[102:103], v21, 1.0 op_sel:[0,1,0]
	v_cvt_scalef32_pk_f32_fp4 v[20:21], v21, 1.0 op_sel:[1,1,0]
	v_pk_fma_f32 v[68:69], v[20:21], v[44:45], v[68:69] op_sel_hi:[1,0,1]
	v_cvt_scalef32_pk_f32_fp4 v[20:21], v22, 1.0
	v_pk_fma_f32 v[98:99], v[98:99], v[44:45], v[104:105] op_sel_hi:[1,0,1]
	v_pk_fma_f32 v[104:105], v[20:21], v[44:45], v[40:41] op_sel_hi:[1,0,1]
	v_cvt_scalef32_pk_f32_fp4 v[20:21], v22, 1.0 op_sel:[1,0,0]
	v_pk_fma_f32 v[100:101], v[100:101], v[44:45], v[106:107] op_sel_hi:[1,0,1]
	v_pk_fma_f32 v[106:107], v[20:21], v[44:45], v[42:43] op_sel_hi:[1,0,1]
	v_cvt_scalef32_pk_f32_fp4 v[20:21], v22, 1.0 op_sel:[0,1,0]
	v_pk_fma_f32 v[102:103], v[102:103], v[44:45], v[108:109] op_sel_hi:[1,0,1]
	v_pk_fma_f32 v[108:109], v[20:21], v[44:45], v[110:111] op_sel_hi:[1,0,1]
	v_cvt_scalef32_pk_f32_fp4 v[20:21], v22, 1.0 op_sel:[1,1,0]
	v_pk_fma_f32 v[110:111], v[20:21], v[44:45], v[112:113] op_sel_hi:[1,0,1]
	v_cvt_scalef32_pk_f32_fp4 v[20:21], v23, 1.0
	v_pk_fma_f32 v[112:113], v[20:21], v[44:45], v[114:115] op_sel_hi:[1,0,1]
	v_cvt_scalef32_pk_f32_fp4 v[20:21], v23, 1.0 op_sel:[1,0,0]
	v_pk_fma_f32 v[114:115], v[20:21], v[44:45], v[116:117] op_sel_hi:[1,0,1]
	v_cvt_scalef32_pk_f32_fp4 v[20:21], v23, 1.0 op_sel:[0,1,0]
	v_pk_fma_f32 v[52:53], v[20:21], v[44:45], v[52:53] op_sel_hi:[1,0,1]
	v_cvt_scalef32_pk_f32_fp4 v[20:21], v23, 1.0 op_sel:[1,1,0]
	v_pk_fma_f32 v[54:55], v[20:21], v[44:45], v[54:55] op_sel_hi:[1,0,1]
	s_waitcnt vmcnt(8)
	v_cvt_scalef32_pk_f32_fp4 v[20:21], v4, 1.0
	v_pk_fma_f32 v[56:57], v[20:21], v[44:45], v[56:57] op_sel_hi:[1,0,1]
	v_cvt_scalef32_pk_f32_fp4 v[20:21], v4, 1.0 op_sel:[1,0,0]
	v_pk_fma_f32 v[58:59], v[20:21], v[44:45], v[58:59] op_sel_hi:[1,0,1]
	v_cvt_scalef32_pk_f32_fp4 v[20:21], v4, 1.0 op_sel:[0,1,0]
	v_pk_fma_f32 v[60:61], v[20:21], v[44:45], v[60:61] op_sel_hi:[1,0,1]
	v_cvt_scalef32_pk_f32_fp4 v[20:21], v4, 1.0 op_sel:[1,1,0]
	v_pk_fma_f32 v[62:63], v[20:21], v[44:45], v[62:63] op_sel_hi:[1,0,1]
	v_cvt_scalef32_pk_f32_fp4 v[20:21], v5, 1.0
	v_pk_fma_f32 v[70:71], v[20:21], v[44:45], v[70:71] op_sel_hi:[1,0,1]
	v_cvt_scalef32_pk_f32_fp4 v[20:21], v5, 1.0 op_sel:[1,0,0]
	v_pk_fma_f32 v[76:77], v[20:21], v[44:45], v[76:77] op_sel_hi:[1,0,1]
	v_cvt_scalef32_pk_f32_fp4 v[20:21], v5, 1.0 op_sel:[0,1,0]
	v_pk_fma_f32 v[78:79], v[20:21], v[44:45], v[78:79] op_sel_hi:[1,0,1]
	v_cvt_scalef32_pk_f32_fp4 v[4:5], v5, 1.0 op_sel:[1,1,0]
	v_cvt_scalef32_pk_f32_fp4 v[20:21], v6, 1.0
	v_pk_fma_f32 v[4:5], v[4:5], v[44:45], v[64:65] op_sel_hi:[1,0,1]
	v_pk_fma_f32 v[64:65], v[20:21], v[44:45], v[72:73] op_sel_hi:[1,0,1]
	v_cvt_scalef32_pk_f32_fp4 v[20:21], v6, 1.0 op_sel:[1,0,0]
	v_pk_fma_f32 v[72:73], v[20:21], v[44:45], v[80:81] op_sel_hi:[1,0,1]
	v_cvt_scalef32_pk_f32_fp4 v[20:21], v6, 1.0 op_sel:[0,1,0]
	v_pk_fma_f32 v[80:81], v[20:21], v[44:45], v[84:85] op_sel_hi:[1,0,1]
	v_cvt_scalef32_pk_f32_fp4 v[20:21], v6, 1.0 op_sel:[1,1,0]
	v_pk_fma_f32 v[84:85], v[20:21], v[44:45], v[86:87] op_sel_hi:[1,0,1]
	v_cvt_scalef32_pk_f32_fp4 v[20:21], v7, 1.0
	v_pk_fma_f32 v[86:87], v[20:21], v[44:45], v[88:89] op_sel_hi:[1,0,1]
	v_cvt_scalef32_pk_f32_fp4 v[20:21], v7, 1.0 op_sel:[1,0,0]
	v_pk_fma_f32 v[88:89], v[20:21], v[44:45], v[92:93] op_sel_hi:[1,0,1]
	v_cvt_scalef32_pk_f32_fp4 v[20:21], v7, 1.0 op_sel:[0,1,0]
	v_cvt_scalef32_pk_f32_fp4 v[6:7], v7, 1.0 op_sel:[1,1,0]
	v_pk_fma_f32 v[92:93], v[20:21], v[44:45], v[94:95] op_sel_hi:[1,0,1]
	v_pk_fma_f32 v[6:7], v[6:7], v[44:45], v[66:67] op_sel_hi:[1,0,1]
	v_lshl_or_b32 v20, v49, 9, v203
	global_load_dwordx4 v[40:43], v20, s[46:47]
	s_nop 0
	global_load_dwordx4 v[20:23], v20, s[46:47] offset:256
	s_waitcnt vmcnt(9)
	v_cvt_scalef32_pk_f32_fp4 v[48:49], v28, 1.0
	v_cvt_scalef32_pk_f32_fp4 v[66:67], v28, 1.0 op_sel:[1,0,0]
	v_pk_fma_f32 v[48:49], v[48:49], v[44:45], v[74:75] op_sel:[0,1,0]
	v_pk_fma_f32 v[66:67], v[66:67], v[44:45], v[82:83] op_sel:[0,1,0]
	v_cvt_scalef32_pk_f32_fp4 v[74:75], v28, 1.0 op_sel:[0,1,0]
	v_cvt_scalef32_pk_f32_fp4 v[82:83], v28, 1.0 op_sel:[1,1,0]
	v_pk_fma_f32 v[74:75], v[74:75], v[44:45], v[90:91] op_sel:[0,1,0]
	v_pk_fma_f32 v[82:83], v[82:83], v[44:45], v[96:97] op_sel:[0,1,0]
	v_cvt_scalef32_pk_f32_fp4 v[90:91], v29, 1.0
	v_cvt_scalef32_pk_f32_fp4 v[94:95], v29, 1.0 op_sel:[1,0,0]
	v_cvt_scalef32_pk_f32_fp4 v[96:97], v29, 1.0 op_sel:[0,1,0]
	v_cvt_scalef32_pk_f32_fp4 v[28:29], v29, 1.0 op_sel:[1,1,0]
	v_pk_fma_f32 v[68:69], v[28:29], v[44:45], v[68:69] op_sel:[0,1,0]
	v_cvt_scalef32_pk_f32_fp4 v[28:29], v30, 1.0
	v_pk_fma_f32 v[90:91], v[90:91], v[44:45], v[98:99] op_sel:[0,1,0]
	v_pk_fma_f32 v[98:99], v[28:29], v[44:45], v[104:105] op_sel:[0,1,0]
	v_cvt_scalef32_pk_f32_fp4 v[28:29], v30, 1.0 op_sel:[1,0,0]
	v_pk_fma_f32 v[94:95], v[94:95], v[44:45], v[100:101] op_sel:[0,1,0]
	v_pk_fma_f32 v[100:101], v[28:29], v[44:45], v[106:107] op_sel:[0,1,0]
	v_cvt_scalef32_pk_f32_fp4 v[28:29], v30, 1.0 op_sel:[0,1,0]
	v_pk_fma_f32 v[96:97], v[96:97], v[44:45], v[102:103] op_sel:[0,1,0]
	v_pk_fma_f32 v[102:103], v[28:29], v[44:45], v[108:109] op_sel:[0,1,0]
	v_cvt_scalef32_pk_f32_fp4 v[28:29], v30, 1.0 op_sel:[1,1,0]
	v_pk_fma_f32 v[104:105], v[28:29], v[44:45], v[110:111] op_sel:[0,1,0]
	v_cvt_scalef32_pk_f32_fp4 v[28:29], v31, 1.0
	v_pk_fma_f32 v[106:107], v[28:29], v[44:45], v[112:113] op_sel:[0,1,0]
	v_cvt_scalef32_pk_f32_fp4 v[28:29], v31, 1.0 op_sel:[1,0,0]
	v_pk_fma_f32 v[108:109], v[28:29], v[44:45], v[114:115] op_sel:[0,1,0]
	v_cvt_scalef32_pk_f32_fp4 v[28:29], v31, 1.0 op_sel:[0,1,0]
	v_pk_fma_f32 v[52:53], v[28:29], v[44:45], v[52:53] op_sel:[0,1,0]
	v_cvt_scalef32_pk_f32_fp4 v[28:29], v31, 1.0 op_sel:[1,1,0]
	v_pk_fma_f32 v[54:55], v[28:29], v[44:45], v[54:55] op_sel:[0,1,0]
	s_waitcnt vmcnt(8)
	v_cvt_scalef32_pk_f32_fp4 v[28:29], v8, 1.0
	v_pk_fma_f32 v[56:57], v[28:29], v[44:45], v[56:57] op_sel:[0,1,0]
	v_cvt_scalef32_pk_f32_fp4 v[28:29], v8, 1.0 op_sel:[1,0,0]
	v_pk_fma_f32 v[58:59], v[28:29], v[44:45], v[58:59] op_sel:[0,1,0]
	v_cvt_scalef32_pk_f32_fp4 v[28:29], v8, 1.0 op_sel:[0,1,0]
	v_pk_fma_f32 v[60:61], v[28:29], v[44:45], v[60:61] op_sel:[0,1,0]
	v_cvt_scalef32_pk_f32_fp4 v[28:29], v8, 1.0 op_sel:[1,1,0]
	v_pk_fma_f32 v[62:63], v[28:29], v[44:45], v[62:63] op_sel:[0,1,0]
	v_cvt_scalef32_pk_f32_fp4 v[28:29], v9, 1.0
	v_pk_fma_f32 v[70:71], v[28:29], v[44:45], v[70:71] op_sel:[0,1,0]
	v_cvt_scalef32_pk_f32_fp4 v[28:29], v9, 1.0 op_sel:[1,0,0]
	v_pk_fma_f32 v[76:77], v[28:29], v[44:45], v[76:77] op_sel:[0,1,0]
	v_cvt_scalef32_pk_f32_fp4 v[28:29], v9, 1.0 op_sel:[0,1,0]
	v_cvt_scalef32_pk_f32_fp4 v[8:9], v9, 1.0 op_sel:[1,1,0]
	v_pk_fma_f32 v[4:5], v[8:9], v[44:45], v[4:5] op_sel:[0,1,0]
	v_cvt_scalef32_pk_f32_fp4 v[8:9], v10, 1.0
	v_pk_fma_f32 v[64:65], v[8:9], v[44:45], v[64:65] op_sel:[0,1,0]
	v_cvt_scalef32_pk_f32_fp4 v[8:9], v10, 1.0 op_sel:[1,0,0]
	v_pk_fma_f32 v[72:73], v[8:9], v[44:45], v[72:73] op_sel:[0,1,0]
	v_cvt_scalef32_pk_f32_fp4 v[8:9], v10, 1.0 op_sel:[0,1,0]
	v_pk_fma_f32 v[80:81], v[8:9], v[44:45], v[80:81] op_sel:[0,1,0]
	v_cvt_scalef32_pk_f32_fp4 v[8:9], v10, 1.0 op_sel:[1,1,0]
	v_pk_fma_f32 v[84:85], v[8:9], v[44:45], v[84:85] op_sel:[0,1,0]
	v_cvt_scalef32_pk_f32_fp4 v[8:9], v11, 1.0
	v_pk_fma_f32 v[86:87], v[8:9], v[44:45], v[86:87] op_sel:[0,1,0]
	v_cvt_scalef32_pk_f32_fp4 v[8:9], v11, 1.0 op_sel:[1,0,0]
	v_pk_fma_f32 v[88:89], v[8:9], v[44:45], v[88:89] op_sel:[0,1,0]
	v_cvt_scalef32_pk_f32_fp4 v[8:9], v11, 1.0 op_sel:[0,1,0]
	v_pk_fma_f32 v[92:93], v[8:9], v[44:45], v[92:93] op_sel:[0,1,0]
	v_cvt_scalef32_pk_f32_fp4 v[8:9], v11, 1.0 op_sel:[1,1,0]
	v_pk_fma_f32 v[78:79], v[28:29], v[44:45], v[78:79] op_sel:[0,1,0]
	v_pk_fma_f32 v[6:7], v[8:9], v[44:45], v[6:7] op_sel:[0,1,0]
	v_lshl_or_b32 v8, v50, 9, v203
	global_load_dwordx4 v[28:31], v8, s[46:47]
	s_nop 0
	global_load_dwordx4 v[8:11], v8, s[46:47] offset:256
	s_waitcnt vmcnt(9)
	v_cvt_scalef32_pk_f32_fp4 v[44:45], v32, 1.0
	v_pk_fma_f32 v[44:45], v[44:45], v[46:47], v[48:49] op_sel_hi:[1,0,1]
	v_cvt_scalef32_pk_f32_fp4 v[48:49], v32, 1.0 op_sel:[1,0,0]
	v_pk_fma_f32 v[48:49], v[48:49], v[46:47], v[66:67] op_sel_hi:[1,0,1]
	v_cvt_scalef32_pk_f32_fp4 v[66:67], v32, 1.0 op_sel:[0,1,0]
	v_pk_fma_f32 v[66:67], v[66:67], v[46:47], v[74:75] op_sel_hi:[1,0,1]
	v_cvt_scalef32_pk_f32_fp4 v[74:75], v32, 1.0 op_sel:[1,1,0]
	v_pk_fma_f32 v[74:75], v[74:75], v[46:47], v[82:83] op_sel_hi:[1,0,1]
	v_cvt_scalef32_pk_f32_fp4 v[82:83], v33, 1.0
	v_pk_fma_f32 v[82:83], v[82:83], v[46:47], v[90:91] op_sel_hi:[1,0,1]
	v_cvt_scalef32_pk_f32_fp4 v[90:91], v33, 1.0 op_sel:[1,0,0]
	v_pk_fma_f32 v[90:91], v[90:91], v[46:47], v[94:95] op_sel_hi:[1,0,1]
	v_cvt_scalef32_pk_f32_fp4 v[94:95], v33, 1.0 op_sel:[0,1,0]
	v_cvt_scalef32_pk_f32_fp4 v[32:33], v33, 1.0 op_sel:[1,1,0]
	v_pk_fma_f32 v[32:33], v[32:33], v[46:47], v[68:69] op_sel_hi:[1,0,1]
	v_cvt_scalef32_pk_f32_fp4 v[68:69], v34, 1.0
	v_pk_fma_f32 v[94:95], v[94:95], v[46:47], v[96:97] op_sel_hi:[1,0,1]
	v_pk_fma_f32 v[68:69], v[68:69], v[46:47], v[98:99] op_sel_hi:[1,0,1]
	v_cvt_scalef32_pk_f32_fp4 v[96:97], v34, 1.0 op_sel:[1,0,0]
	v_cvt_scalef32_pk_f32_fp4 v[98:99], v34, 1.0 op_sel:[0,1,0]
	v_pk_fma_f32 v[96:97], v[96:97], v[46:47], v[100:101] op_sel_hi:[1,0,1]
	v_pk_fma_f32 v[98:99], v[98:99], v[46:47], v[102:103] op_sel_hi:[1,0,1]
	v_cvt_scalef32_pk_f32_fp4 v[100:101], v34, 1.0 op_sel:[1,1,0]
	v_cvt_scalef32_pk_f32_fp4 v[102:103], v35, 1.0
	v_pk_fma_f32 v[100:101], v[100:101], v[46:47], v[104:105] op_sel_hi:[1,0,1]
	v_pk_fma_f32 v[102:103], v[102:103], v[46:47], v[106:107] op_sel_hi:[1,0,1]
	v_cvt_scalef32_pk_f32_fp4 v[104:105], v35, 1.0 op_sel:[1,0,0]
	v_cvt_scalef32_pk_f32_fp4 v[106:107], v35, 1.0 op_sel:[0,1,0]
	v_cvt_scalef32_pk_f32_fp4 v[34:35], v35, 1.0 op_sel:[1,1,0]
	v_pk_fma_f32 v[34:35], v[34:35], v[46:47], v[54:55] op_sel_hi:[1,0,1]
	s_waitcnt vmcnt(8)
	v_cvt_scalef32_pk_f32_fp4 v[54:55], v12, 1.0
	v_pk_fma_f32 v[54:55], v[54:55], v[46:47], v[56:57] op_sel_hi:[1,0,1]
	v_cvt_scalef32_pk_f32_fp4 v[56:57], v12, 1.0 op_sel:[1,0,0]
	v_pk_fma_f32 v[56:57], v[56:57], v[46:47], v[58:59] op_sel_hi:[1,0,1]
	v_cvt_scalef32_pk_f32_fp4 v[58:59], v12, 1.0 op_sel:[0,1,0]
	v_pk_fma_f32 v[58:59], v[58:59], v[46:47], v[60:61] op_sel_hi:[1,0,1]
	v_cvt_scalef32_pk_f32_fp4 v[60:61], v12, 1.0 op_sel:[1,1,0]
	v_pk_fma_f32 v[60:61], v[60:61], v[46:47], v[62:63] op_sel_hi:[1,0,1]
	v_cvt_scalef32_pk_f32_fp4 v[62:63], v13, 1.0
	v_pk_fma_f32 v[62:63], v[62:63], v[46:47], v[70:71] op_sel_hi:[1,0,1]
	v_cvt_scalef32_pk_f32_fp4 v[70:71], v13, 1.0 op_sel:[1,0,0]
	v_pk_fma_f32 v[70:71], v[70:71], v[46:47], v[76:77] op_sel_hi:[1,0,1]
	v_cvt_scalef32_pk_f32_fp4 v[76:77], v13, 1.0 op_sel:[0,1,0]
	v_cvt_scalef32_pk_f32_fp4 v[12:13], v13, 1.0 op_sel:[1,1,0]
	v_pk_fma_f32 v[76:77], v[76:77], v[46:47], v[78:79] op_sel_hi:[1,0,1]
	v_pk_fma_f32 v[78:79], v[12:13], v[46:47], v[4:5] op_sel_hi:[1,0,1]
	v_cvt_scalef32_pk_f32_fp4 v[4:5], v14, 1.0
	v_pk_fma_f32 v[64:65], v[4:5], v[46:47], v[64:65] op_sel_hi:[1,0,1]
	v_cvt_scalef32_pk_f32_fp4 v[4:5], v14, 1.0 op_sel:[1,0,0]
	v_pk_fma_f32 v[72:73], v[4:5], v[46:47], v[72:73] op_sel_hi:[1,0,1]
	v_cvt_scalef32_pk_f32_fp4 v[4:5], v14, 1.0 op_sel:[0,1,0]
	v_pk_fma_f32 v[80:81], v[4:5], v[46:47], v[80:81] op_sel_hi:[1,0,1]
	v_cvt_scalef32_pk_f32_fp4 v[4:5], v14, 1.0 op_sel:[1,1,0]
	v_pk_fma_f32 v[84:85], v[4:5], v[46:47], v[84:85] op_sel_hi:[1,0,1]
	v_cvt_scalef32_pk_f32_fp4 v[4:5], v15, 1.0
	v_pk_fma_f32 v[86:87], v[4:5], v[46:47], v[86:87] op_sel_hi:[1,0,1]
	v_cvt_scalef32_pk_f32_fp4 v[4:5], v15, 1.0 op_sel:[1,0,0]
	v_pk_fma_f32 v[88:89], v[4:5], v[46:47], v[88:89] op_sel_hi:[1,0,1]
	v_cvt_scalef32_pk_f32_fp4 v[4:5], v15, 1.0 op_sel:[0,1,0]
	v_pk_fma_f32 v[92:93], v[4:5], v[46:47], v[92:93] op_sel_hi:[1,0,1]
	v_cvt_scalef32_pk_f32_fp4 v[4:5], v15, 1.0 op_sel:[1,1,0]
	v_pk_fma_f32 v[104:105], v[104:105], v[46:47], v[108:109] op_sel_hi:[1,0,1]
	v_pk_fma_f32 v[52:53], v[106:107], v[46:47], v[52:53] op_sel_hi:[1,0,1]
	v_pk_fma_f32 v[106:107], v[4:5], v[46:47], v[6:7] op_sel_hi:[1,0,1]
	v_lshl_or_b32 v4, v51, 9, v203
	global_load_dwordx4 v[12:15], v4, s[46:47]
	s_nop 0
	global_load_dwordx4 v[4:7], v4, s[46:47] offset:256
	v_mov_b32_e32 v46, v47
	s_waitcnt vmcnt(9)
	v_cvt_scalef32_pk_f32_fp4 v[50:51], v24, 1.0
	v_pk_fma_f32 v[50:51], v[50:51], v[46:47], v[44:45] op_sel_hi:[1,0,1]
	v_cvt_scalef32_pk_f32_fp4 v[44:45], v24, 1.0 op_sel:[1,0,0]
	v_pk_fma_f32 v[48:49], v[44:45], v[46:47], v[48:49] op_sel_hi:[1,0,1]
	v_cvt_scalef32_pk_f32_fp4 v[44:45], v24, 1.0 op_sel:[0,1,0]
	v_pk_fma_f32 v[66:67], v[44:45], v[46:47], v[66:67] op_sel_hi:[1,0,1]
	v_cvt_scalef32_pk_f32_fp4 v[44:45], v24, 1.0 op_sel:[1,1,0]
	v_pk_fma_f32 v[74:75], v[44:45], v[46:47], v[74:75] op_sel_hi:[1,0,1]
	v_cvt_scalef32_pk_f32_fp4 v[44:45], v25, 1.0
	v_pk_fma_f32 v[82:83], v[44:45], v[46:47], v[82:83] op_sel_hi:[1,0,1]
	v_cvt_scalef32_pk_f32_fp4 v[44:45], v25, 1.0 op_sel:[1,0,0]
	v_pk_fma_f32 v[90:91], v[44:45], v[46:47], v[90:91] op_sel_hi:[1,0,1]
	v_cvt_scalef32_pk_f32_fp4 v[44:45], v25, 1.0 op_sel:[0,1,0]
	v_cvt_scalef32_pk_f32_fp4 v[24:25], v25, 1.0 op_sel:[1,1,0]
	v_pk_fma_f32 v[108:109], v[24:25], v[46:47], v[32:33] op_sel_hi:[1,0,1]
	v_cvt_scalef32_pk_f32_fp4 v[24:25], v26, 1.0
	v_pk_fma_f32 v[68:69], v[24:25], v[46:47], v[68:69] op_sel_hi:[1,0,1]
	v_cvt_scalef32_pk_f32_fp4 v[24:25], v26, 1.0 op_sel:[1,0,0]
	v_pk_fma_f32 v[96:97], v[24:25], v[46:47], v[96:97] op_sel_hi:[1,0,1]
	v_cvt_scalef32_pk_f32_fp4 v[24:25], v26, 1.0 op_sel:[0,1,0]
	v_pk_fma_f32 v[98:99], v[24:25], v[46:47], v[98:99] op_sel_hi:[1,0,1]
	v_cvt_scalef32_pk_f32_fp4 v[24:25], v26, 1.0 op_sel:[1,1,0]
	v_pk_fma_f32 v[100:101], v[24:25], v[46:47], v[100:101] op_sel_hi:[1,0,1]
	v_cvt_scalef32_pk_f32_fp4 v[24:25], v27, 1.0
	v_pk_fma_f32 v[102:103], v[24:25], v[46:47], v[102:103] op_sel_hi:[1,0,1]
	v_cvt_scalef32_pk_f32_fp4 v[24:25], v27, 1.0 op_sel:[1,0,0]
	v_pk_fma_f32 v[104:105], v[24:25], v[46:47], v[104:105] op_sel_hi:[1,0,1]
	v_cvt_scalef32_pk_f32_fp4 v[24:25], v27, 1.0 op_sel:[0,1,0]
	v_pk_fma_f32 v[52:53], v[24:25], v[46:47], v[52:53] op_sel_hi:[1,0,1]
	v_cvt_scalef32_pk_f32_fp4 v[24:25], v27, 1.0 op_sel:[1,1,0]
	v_pk_fma_f32 v[110:111], v[24:25], v[46:47], v[34:35] op_sel_hi:[1,0,1]
	s_waitcnt vmcnt(8)
	v_cvt_scalef32_pk_f32_fp4 v[24:25], v0, 1.0
	v_pk_fma_f32 v[54:55], v[24:25], v[46:47], v[54:55] op_sel_hi:[1,0,1]
	v_cvt_scalef32_pk_f32_fp4 v[24:25], v0, 1.0 op_sel:[1,0,0]
	v_pk_fma_f32 v[56:57], v[24:25], v[46:47], v[56:57] op_sel_hi:[1,0,1]
	v_cvt_scalef32_pk_f32_fp4 v[24:25], v0, 1.0 op_sel:[0,1,0]
	v_pk_fma_f32 v[58:59], v[24:25], v[46:47], v[58:59] op_sel_hi:[1,0,1]
	v_cvt_scalef32_pk_f32_fp4 v[24:25], v0, 1.0 op_sel:[1,1,0]
	v_pk_fma_f32 v[60:61], v[24:25], v[46:47], v[60:61] op_sel_hi:[1,0,1]
	v_cvt_scalef32_pk_f32_fp4 v[24:25], v1, 1.0
	v_pk_fma_f32 v[62:63], v[24:25], v[46:47], v[62:63] op_sel_hi:[1,0,1]
	v_cvt_scalef32_pk_f32_fp4 v[24:25], v1, 1.0 op_sel:[1,0,0]
	v_pk_fma_f32 v[70:71], v[24:25], v[46:47], v[70:71] op_sel_hi:[1,0,1]
	v_cvt_scalef32_pk_f32_fp4 v[24:25], v1, 1.0 op_sel:[0,1,0]
	v_cvt_scalef32_pk_f32_fp4 v[0:1], v1, 1.0 op_sel:[1,1,0]
	v_pk_fma_f32 v[78:79], v[0:1], v[46:47], v[78:79] op_sel_hi:[1,0,1]
	v_cvt_scalef32_pk_f32_fp4 v[0:1], v2, 1.0
	v_pk_fma_f32 v[64:65], v[0:1], v[46:47], v[64:65] op_sel_hi:[1,0,1]
	v_cvt_scalef32_pk_f32_fp4 v[0:1], v2, 1.0 op_sel:[1,0,0]
	v_pk_fma_f32 v[72:73], v[0:1], v[46:47], v[72:73] op_sel_hi:[1,0,1]
	v_cvt_scalef32_pk_f32_fp4 v[0:1], v2, 1.0 op_sel:[0,1,0]
	v_pk_fma_f32 v[80:81], v[0:1], v[46:47], v[80:81] op_sel_hi:[1,0,1]
	v_cvt_scalef32_pk_f32_fp4 v[0:1], v2, 1.0 op_sel:[1,1,0]
	v_pk_fma_f32 v[84:85], v[0:1], v[46:47], v[84:85] op_sel_hi:[1,0,1]
	v_cvt_scalef32_pk_f32_fp4 v[0:1], v3, 1.0
	v_pk_fma_f32 v[86:87], v[0:1], v[46:47], v[86:87] op_sel_hi:[1,0,1]
	v_cvt_scalef32_pk_f32_fp4 v[0:1], v3, 1.0 op_sel:[1,0,0]
	v_pk_fma_f32 v[88:89], v[0:1], v[46:47], v[88:89] op_sel_hi:[1,0,1]
	v_cvt_scalef32_pk_f32_fp4 v[0:1], v3, 1.0 op_sel:[0,1,0]
	v_pk_fma_f32 v[92:93], v[0:1], v[46:47], v[92:93] op_sel_hi:[1,0,1]
	v_cvt_scalef32_pk_f32_fp4 v[0:1], v3, 1.0 op_sel:[1,1,0]
	v_pk_fma_f32 v[94:95], v[44:45], v[46:47], v[94:95] op_sel_hi:[1,0,1]
	v_pk_fma_f32 v[76:77], v[24:25], v[46:47], v[76:77] op_sel_hi:[1,0,1]
	v_pk_fma_f32 v[106:107], v[0:1], v[46:47], v[106:107] op_sel_hi:[1,0,1]
	ds_read_b128 v[44:47], v204 offset:496
	ds_read_b128 v[32:35], v204 offset:4576
	s_waitcnt vmcnt(7)
	v_cvt_scalef32_pk_f32_fp4 v[112:113], v36, 1.0
	s_waitcnt lgkmcnt(1)
	v_lshl_or_b32 v0, v44, 9, v203
	global_load_dwordx4 v[24:27], v0, s[46:47]
	s_nop 0
	global_load_dwordx4 v[0:3], v0, s[46:47] offset:256
	s_waitcnt lgkmcnt(0)
	v_pk_fma_f32 v[50:51], v[112:113], v[32:33], v[50:51] op_sel_hi:[1,0,1]
	v_cvt_scalef32_pk_f32_fp4 v[112:113], v36, 1.0 op_sel:[1,0,0]
	v_pk_fma_f32 v[48:49], v[112:113], v[32:33], v[48:49] op_sel_hi:[1,0,1]
	v_cvt_scalef32_pk_f32_fp4 v[112:113], v36, 1.0 op_sel:[0,1,0]
	v_pk_fma_f32 v[66:67], v[112:113], v[32:33], v[66:67] op_sel_hi:[1,0,1]
	v_cvt_scalef32_pk_f32_fp4 v[112:113], v36, 1.0 op_sel:[1,1,0]
	v_pk_fma_f32 v[74:75], v[112:113], v[32:33], v[74:75] op_sel_hi:[1,0,1]
	v_cvt_scalef32_pk_f32_fp4 v[112:113], v37, 1.0
	v_pk_fma_f32 v[82:83], v[112:113], v[32:33], v[82:83] op_sel_hi:[1,0,1]
	v_cvt_scalef32_pk_f32_fp4 v[112:113], v37, 1.0 op_sel:[1,0,0]
	v_pk_fma_f32 v[90:91], v[112:113], v[32:33], v[90:91] op_sel_hi:[1,0,1]
	v_cvt_scalef32_pk_f32_fp4 v[112:113], v37, 1.0 op_sel:[0,1,0]
	v_cvt_scalef32_pk_f32_fp4 v[36:37], v37, 1.0 op_sel:[1,1,0]
	v_pk_fma_f32 v[108:109], v[36:37], v[32:33], v[108:109] op_sel_hi:[1,0,1]
	v_cvt_scalef32_pk_f32_fp4 v[36:37], v38, 1.0
	v_pk_fma_f32 v[68:69], v[36:37], v[32:33], v[68:69] op_sel_hi:[1,0,1]
	v_cvt_scalef32_pk_f32_fp4 v[36:37], v38, 1.0 op_sel:[1,0,0]
	v_pk_fma_f32 v[96:97], v[36:37], v[32:33], v[96:97] op_sel_hi:[1,0,1]
	v_cvt_scalef32_pk_f32_fp4 v[36:37], v38, 1.0 op_sel:[0,1,0]
	v_pk_fma_f32 v[98:99], v[36:37], v[32:33], v[98:99] op_sel_hi:[1,0,1]
	v_cvt_scalef32_pk_f32_fp4 v[36:37], v38, 1.0 op_sel:[1,1,0]
	v_pk_fma_f32 v[100:101], v[36:37], v[32:33], v[100:101] op_sel_hi:[1,0,1]
	v_cvt_scalef32_pk_f32_fp4 v[36:37], v39, 1.0
	v_pk_fma_f32 v[102:103], v[36:37], v[32:33], v[102:103] op_sel_hi:[1,0,1]
	v_cvt_scalef32_pk_f32_fp4 v[36:37], v39, 1.0 op_sel:[1,0,0]
	v_pk_fma_f32 v[104:105], v[36:37], v[32:33], v[104:105] op_sel_hi:[1,0,1]
	v_cvt_scalef32_pk_f32_fp4 v[36:37], v39, 1.0 op_sel:[0,1,0]
	v_pk_fma_f32 v[52:53], v[36:37], v[32:33], v[52:53] op_sel_hi:[1,0,1]
	v_cvt_scalef32_pk_f32_fp4 v[36:37], v39, 1.0 op_sel:[1,1,0]
	v_pk_fma_f32 v[110:111], v[36:37], v[32:33], v[110:111] op_sel_hi:[1,0,1]
	s_waitcnt vmcnt(8)
	v_cvt_scalef32_pk_f32_fp4 v[36:37], v16, 1.0
	v_pk_fma_f32 v[54:55], v[36:37], v[32:33], v[54:55] op_sel_hi:[1,0,1]
	v_cvt_scalef32_pk_f32_fp4 v[36:37], v16, 1.0 op_sel:[1,0,0]
	v_pk_fma_f32 v[56:57], v[36:37], v[32:33], v[56:57] op_sel_hi:[1,0,1]
	v_cvt_scalef32_pk_f32_fp4 v[36:37], v16, 1.0 op_sel:[0,1,0]
	v_pk_fma_f32 v[58:59], v[36:37], v[32:33], v[58:59] op_sel_hi:[1,0,1]
	v_cvt_scalef32_pk_f32_fp4 v[36:37], v16, 1.0 op_sel:[1,1,0]
	v_pk_fma_f32 v[60:61], v[36:37], v[32:33], v[60:61] op_sel_hi:[1,0,1]
	v_cvt_scalef32_pk_f32_fp4 v[36:37], v17, 1.0
	v_pk_fma_f32 v[62:63], v[36:37], v[32:33], v[62:63] op_sel_hi:[1,0,1]
	v_cvt_scalef32_pk_f32_fp4 v[36:37], v17, 1.0 op_sel:[1,0,0]
	v_pk_fma_f32 v[70:71], v[36:37], v[32:33], v[70:71] op_sel_hi:[1,0,1]
	v_cvt_scalef32_pk_f32_fp4 v[36:37], v17, 1.0 op_sel:[0,1,0]
	v_cvt_scalef32_pk_f32_fp4 v[16:17], v17, 1.0 op_sel:[1,1,0]
	v_pk_fma_f32 v[78:79], v[16:17], v[32:33], v[78:79] op_sel_hi:[1,0,1]
	v_cvt_scalef32_pk_f32_fp4 v[16:17], v18, 1.0
	v_pk_fma_f32 v[64:65], v[16:17], v[32:33], v[64:65] op_sel_hi:[1,0,1]
	v_cvt_scalef32_pk_f32_fp4 v[16:17], v18, 1.0 op_sel:[1,0,0]
	v_pk_fma_f32 v[72:73], v[16:17], v[32:33], v[72:73] op_sel_hi:[1,0,1]
	v_cvt_scalef32_pk_f32_fp4 v[16:17], v18, 1.0 op_sel:[0,1,0]
	v_pk_fma_f32 v[80:81], v[16:17], v[32:33], v[80:81] op_sel_hi:[1,0,1]
	v_cvt_scalef32_pk_f32_fp4 v[16:17], v18, 1.0 op_sel:[1,1,0]
	v_pk_fma_f32 v[84:85], v[16:17], v[32:33], v[84:85] op_sel_hi:[1,0,1]
	v_cvt_scalef32_pk_f32_fp4 v[16:17], v19, 1.0
	v_pk_fma_f32 v[86:87], v[16:17], v[32:33], v[86:87] op_sel_hi:[1,0,1]
	v_cvt_scalef32_pk_f32_fp4 v[16:17], v19, 1.0 op_sel:[1,0,0]
	v_pk_fma_f32 v[88:89], v[16:17], v[32:33], v[88:89] op_sel_hi:[1,0,1]
	v_cvt_scalef32_pk_f32_fp4 v[16:17], v19, 1.0 op_sel:[0,1,0]
	v_pk_fma_f32 v[92:93], v[16:17], v[32:33], v[92:93] op_sel_hi:[1,0,1]
	v_cvt_scalef32_pk_f32_fp4 v[16:17], v19, 1.0 op_sel:[1,1,0]
	v_pk_fma_f32 v[94:95], v[112:113], v[32:33], v[94:95] op_sel_hi:[1,0,1]
	v_pk_fma_f32 v[76:77], v[36:37], v[32:33], v[76:77] op_sel_hi:[1,0,1]
	v_pk_fma_f32 v[106:107], v[16:17], v[32:33], v[106:107] op_sel_hi:[1,0,1]
	v_lshl_or_b32 v16, v45, 9, v203
	global_load_dwordx4 v[36:39], v16, s[46:47]
	s_nop 0
	global_load_dwordx4 v[16:19], v16, s[46:47] offset:256
	s_waitcnt vmcnt(9)
	v_cvt_scalef32_pk_f32_fp4 v[44:45], v40, 1.0
	v_pk_fma_f32 v[44:45], v[44:45], v[32:33], v[50:51] op_sel:[0,1,0]
	v_cvt_scalef32_pk_f32_fp4 v[50:51], v40, 1.0 op_sel:[1,0,0]
	v_pk_fma_f32 v[48:49], v[50:51], v[32:33], v[48:49] op_sel:[0,1,0]
	v_cvt_scalef32_pk_f32_fp4 v[50:51], v40, 1.0 op_sel:[0,1,0]
	v_pk_fma_f32 v[50:51], v[50:51], v[32:33], v[66:67] op_sel:[0,1,0]
	v_cvt_scalef32_pk_f32_fp4 v[66:67], v40, 1.0 op_sel:[1,1,0]
	v_pk_fma_f32 v[66:67], v[66:67], v[32:33], v[74:75] op_sel:[0,1,0]
	v_cvt_scalef32_pk_f32_fp4 v[74:75], v41, 1.0
	v_pk_fma_f32 v[74:75], v[74:75], v[32:33], v[82:83] op_sel:[0,1,0]
	v_cvt_scalef32_pk_f32_fp4 v[82:83], v41, 1.0 op_sel:[1,0,0]
	v_pk_fma_f32 v[82:83], v[82:83], v[32:33], v[90:91] op_sel:[0,1,0]
	v_cvt_scalef32_pk_f32_fp4 v[90:91], v41, 1.0 op_sel:[0,1,0]
	v_cvt_scalef32_pk_f32_fp4 v[40:41], v41, 1.0 op_sel:[1,1,0]
	v_pk_fma_f32 v[90:91], v[90:91], v[32:33], v[94:95] op_sel:[0,1,0]
	v_pk_fma_f32 v[94:95], v[40:41], v[32:33], v[108:109] op_sel:[0,1,0]
	v_cvt_scalef32_pk_f32_fp4 v[40:41], v42, 1.0
	v_pk_fma_f32 v[68:69], v[40:41], v[32:33], v[68:69] op_sel:[0,1,0]
	v_cvt_scalef32_pk_f32_fp4 v[40:41], v42, 1.0 op_sel:[1,0,0]
	v_pk_fma_f32 v[96:97], v[40:41], v[32:33], v[96:97] op_sel:[0,1,0]
	v_cvt_scalef32_pk_f32_fp4 v[40:41], v42, 1.0 op_sel:[0,1,0]
	v_pk_fma_f32 v[98:99], v[40:41], v[32:33], v[98:99] op_sel:[0,1,0]
	v_cvt_scalef32_pk_f32_fp4 v[40:41], v42, 1.0 op_sel:[1,1,0]
	v_pk_fma_f32 v[100:101], v[40:41], v[32:33], v[100:101] op_sel:[0,1,0]
	v_cvt_scalef32_pk_f32_fp4 v[40:41], v43, 1.0
	v_pk_fma_f32 v[102:103], v[40:41], v[32:33], v[102:103] op_sel:[0,1,0]
	v_cvt_scalef32_pk_f32_fp4 v[40:41], v43, 1.0 op_sel:[1,0,0]
	v_pk_fma_f32 v[104:105], v[40:41], v[32:33], v[104:105] op_sel:[0,1,0]
	v_cvt_scalef32_pk_f32_fp4 v[40:41], v43, 1.0 op_sel:[0,1,0]
	v_pk_fma_f32 v[52:53], v[40:41], v[32:33], v[52:53] op_sel:[0,1,0]
	v_cvt_scalef32_pk_f32_fp4 v[40:41], v43, 1.0 op_sel:[1,1,0]
	v_pk_fma_f32 v[108:109], v[40:41], v[32:33], v[110:111] op_sel:[0,1,0]
	s_waitcnt vmcnt(8)
	v_cvt_scalef32_pk_f32_fp4 v[40:41], v20, 1.0
	v_pk_fma_f32 v[54:55], v[40:41], v[32:33], v[54:55] op_sel:[0,1,0]
	v_cvt_scalef32_pk_f32_fp4 v[40:41], v20, 1.0 op_sel:[1,0,0]
	v_pk_fma_f32 v[56:57], v[40:41], v[32:33], v[56:57] op_sel:[0,1,0]
	v_cvt_scalef32_pk_f32_fp4 v[40:41], v20, 1.0 op_sel:[0,1,0]
	v_pk_fma_f32 v[58:59], v[40:41], v[32:33], v[58:59] op_sel:[0,1,0]
	v_cvt_scalef32_pk_f32_fp4 v[40:41], v20, 1.0 op_sel:[1,1,0]
	v_pk_fma_f32 v[60:61], v[40:41], v[32:33], v[60:61] op_sel:[0,1,0]
	v_cvt_scalef32_pk_f32_fp4 v[40:41], v21, 1.0
	v_pk_fma_f32 v[62:63], v[40:41], v[32:33], v[62:63] op_sel:[0,1,0]
	v_cvt_scalef32_pk_f32_fp4 v[40:41], v21, 1.0 op_sel:[1,0,0]
	v_pk_fma_f32 v[70:71], v[40:41], v[32:33], v[70:71] op_sel:[0,1,0]
	v_cvt_scalef32_pk_f32_fp4 v[40:41], v21, 1.0 op_sel:[0,1,0]
	v_cvt_scalef32_pk_f32_fp4 v[20:21], v21, 1.0 op_sel:[1,1,0]
	v_pk_fma_f32 v[78:79], v[20:21], v[32:33], v[78:79] op_sel:[0,1,0]
	v_cvt_scalef32_pk_f32_fp4 v[20:21], v22, 1.0
	v_pk_fma_f32 v[64:65], v[20:21], v[32:33], v[64:65] op_sel:[0,1,0]
	v_cvt_scalef32_pk_f32_fp4 v[20:21], v22, 1.0 op_sel:[1,0,0]
	v_pk_fma_f32 v[72:73], v[20:21], v[32:33], v[72:73] op_sel:[0,1,0]
	v_cvt_scalef32_pk_f32_fp4 v[20:21], v22, 1.0 op_sel:[0,1,0]
	v_pk_fma_f32 v[80:81], v[20:21], v[32:33], v[80:81] op_sel:[0,1,0]
	v_cvt_scalef32_pk_f32_fp4 v[20:21], v22, 1.0 op_sel:[1,1,0]
	v_pk_fma_f32 v[84:85], v[20:21], v[32:33], v[84:85] op_sel:[0,1,0]
	v_cvt_scalef32_pk_f32_fp4 v[20:21], v23, 1.0
	v_pk_fma_f32 v[86:87], v[20:21], v[32:33], v[86:87] op_sel:[0,1,0]
	v_cvt_scalef32_pk_f32_fp4 v[20:21], v23, 1.0 op_sel:[1,0,0]
	v_pk_fma_f32 v[88:89], v[20:21], v[32:33], v[88:89] op_sel:[0,1,0]
	v_cvt_scalef32_pk_f32_fp4 v[20:21], v23, 1.0 op_sel:[0,1,0]
	v_pk_fma_f32 v[92:93], v[20:21], v[32:33], v[92:93] op_sel:[0,1,0]
	v_cvt_scalef32_pk_f32_fp4 v[20:21], v23, 1.0 op_sel:[1,1,0]
	v_pk_fma_f32 v[76:77], v[40:41], v[32:33], v[76:77] op_sel:[0,1,0]
	v_pk_fma_f32 v[32:33], v[20:21], v[32:33], v[106:107] op_sel:[0,1,0]
	v_lshl_or_b32 v20, v46, 9, v203
	global_load_dwordx4 v[40:43], v20, s[46:47]
	s_nop 0
	global_load_dwordx4 v[20:23], v20, s[46:47] offset:256
	s_waitcnt vmcnt(9)
	v_cvt_scalef32_pk_f32_fp4 v[106:107], v28, 1.0
	v_pk_fma_f32 v[44:45], v[106:107], v[34:35], v[44:45] op_sel_hi:[1,0,1]
	v_cvt_scalef32_pk_f32_fp4 v[106:107], v28, 1.0 op_sel:[1,0,0]
	v_pk_fma_f32 v[48:49], v[106:107], v[34:35], v[48:49] op_sel_hi:[1,0,1]
	v_cvt_scalef32_pk_f32_fp4 v[106:107], v28, 1.0 op_sel:[0,1,0]
	v_pk_fma_f32 v[50:51], v[106:107], v[34:35], v[50:51] op_sel_hi:[1,0,1]
	v_cvt_scalef32_pk_f32_fp4 v[106:107], v28, 1.0 op_sel:[1,1,0]
	v_pk_fma_f32 v[66:67], v[106:107], v[34:35], v[66:67] op_sel_hi:[1,0,1]
	v_cvt_scalef32_pk_f32_fp4 v[106:107], v29, 1.0
	v_pk_fma_f32 v[74:75], v[106:107], v[34:35], v[74:75] op_sel_hi:[1,0,1]
	v_cvt_scalef32_pk_f32_fp4 v[106:107], v29, 1.0 op_sel:[1,0,0]
	v_pk_fma_f32 v[82:83], v[106:107], v[34:35], v[82:83] op_sel_hi:[1,0,1]
	v_cvt_scalef32_pk_f32_fp4 v[106:107], v29, 1.0 op_sel:[0,1,0]
	v_cvt_scalef32_pk_f32_fp4 v[28:29], v29, 1.0 op_sel:[1,1,0]
	v_pk_fma_f32 v[94:95], v[28:29], v[34:35], v[94:95] op_sel_hi:[1,0,1]
	v_cvt_scalef32_pk_f32_fp4 v[28:29], v30, 1.0
	v_pk_fma_f32 v[68:69], v[28:29], v[34:35], v[68:69] op_sel_hi:[1,0,1]
	v_cvt_scalef32_pk_f32_fp4 v[28:29], v30, 1.0 op_sel:[1,0,0]
	v_pk_fma_f32 v[96:97], v[28:29], v[34:35], v[96:97] op_sel_hi:[1,0,1]
	v_cvt_scalef32_pk_f32_fp4 v[28:29], v30, 1.0 op_sel:[0,1,0]
	v_pk_fma_f32 v[98:99], v[28:29], v[34:35], v[98:99] op_sel_hi:[1,0,1]
	v_cvt_scalef32_pk_f32_fp4 v[28:29], v30, 1.0 op_sel:[1,1,0]
	v_pk_fma_f32 v[100:101], v[28:29], v[34:35], v[100:101] op_sel_hi:[1,0,1]
	v_cvt_scalef32_pk_f32_fp4 v[28:29], v31, 1.0
	v_pk_fma_f32 v[102:103], v[28:29], v[34:35], v[102:103] op_sel_hi:[1,0,1]
	v_cvt_scalef32_pk_f32_fp4 v[28:29], v31, 1.0 op_sel:[1,0,0]
	v_pk_fma_f32 v[104:105], v[28:29], v[34:35], v[104:105] op_sel_hi:[1,0,1]
	v_cvt_scalef32_pk_f32_fp4 v[28:29], v31, 1.0 op_sel:[0,1,0]
	v_pk_fma_f32 v[52:53], v[28:29], v[34:35], v[52:53] op_sel_hi:[1,0,1]
	v_cvt_scalef32_pk_f32_fp4 v[28:29], v31, 1.0 op_sel:[1,1,0]
	v_pk_fma_f32 v[90:91], v[106:107], v[34:35], v[90:91] op_sel_hi:[1,0,1]
	v_pk_fma_f32 v[106:107], v[28:29], v[34:35], v[108:109] op_sel_hi:[1,0,1]
	s_waitcnt vmcnt(8)
	v_cvt_scalef32_pk_f32_fp4 v[28:29], v8, 1.0
	v_pk_fma_f32 v[54:55], v[28:29], v[34:35], v[54:55] op_sel_hi:[1,0,1]
	v_cvt_scalef32_pk_f32_fp4 v[28:29], v8, 1.0 op_sel:[1,0,0]
	v_pk_fma_f32 v[56:57], v[28:29], v[34:35], v[56:57] op_sel_hi:[1,0,1]
	v_cvt_scalef32_pk_f32_fp4 v[28:29], v8, 1.0 op_sel:[0,1,0]
	v_pk_fma_f32 v[58:59], v[28:29], v[34:35], v[58:59] op_sel_hi:[1,0,1]
	v_cvt_scalef32_pk_f32_fp4 v[28:29], v8, 1.0 op_sel:[1,1,0]
	v_pk_fma_f32 v[60:61], v[28:29], v[34:35], v[60:61] op_sel_hi:[1,0,1]
	v_cvt_scalef32_pk_f32_fp4 v[28:29], v9, 1.0
	v_pk_fma_f32 v[62:63], v[28:29], v[34:35], v[62:63] op_sel_hi:[1,0,1]
	v_cvt_scalef32_pk_f32_fp4 v[28:29], v9, 1.0 op_sel:[1,0,0]
	v_pk_fma_f32 v[70:71], v[28:29], v[34:35], v[70:71] op_sel_hi:[1,0,1]
	v_cvt_scalef32_pk_f32_fp4 v[28:29], v9, 1.0 op_sel:[0,1,0]
	v_cvt_scalef32_pk_f32_fp4 v[8:9], v9, 1.0 op_sel:[1,1,0]
	v_pk_fma_f32 v[78:79], v[8:9], v[34:35], v[78:79] op_sel_hi:[1,0,1]
	v_cvt_scalef32_pk_f32_fp4 v[8:9], v10, 1.0
	v_pk_fma_f32 v[64:65], v[8:9], v[34:35], v[64:65] op_sel_hi:[1,0,1]
	v_cvt_scalef32_pk_f32_fp4 v[8:9], v10, 1.0 op_sel:[1,0,0]
	v_pk_fma_f32 v[72:73], v[8:9], v[34:35], v[72:73] op_sel_hi:[1,0,1]
	v_cvt_scalef32_pk_f32_fp4 v[8:9], v10, 1.0 op_sel:[0,1,0]
	v_pk_fma_f32 v[80:81], v[8:9], v[34:35], v[80:81] op_sel_hi:[1,0,1]
	v_cvt_scalef32_pk_f32_fp4 v[8:9], v10, 1.0 op_sel:[1,1,0]
	v_pk_fma_f32 v[84:85], v[8:9], v[34:35], v[84:85] op_sel_hi:[1,0,1]
	v_cvt_scalef32_pk_f32_fp4 v[8:9], v11, 1.0
	v_pk_fma_f32 v[86:87], v[8:9], v[34:35], v[86:87] op_sel_hi:[1,0,1]
	v_cvt_scalef32_pk_f32_fp4 v[8:9], v11, 1.0 op_sel:[1,0,0]
	v_pk_fma_f32 v[88:89], v[8:9], v[34:35], v[88:89] op_sel_hi:[1,0,1]
	v_cvt_scalef32_pk_f32_fp4 v[8:9], v11, 1.0 op_sel:[0,1,0]
	v_pk_fma_f32 v[92:93], v[8:9], v[34:35], v[92:93] op_sel_hi:[1,0,1]
	v_cvt_scalef32_pk_f32_fp4 v[8:9], v11, 1.0 op_sel:[1,1,0]
	v_pk_fma_f32 v[76:77], v[28:29], v[34:35], v[76:77] op_sel_hi:[1,0,1]
	v_pk_fma_f32 v[32:33], v[8:9], v[34:35], v[32:33] op_sel_hi:[1,0,1]
	v_lshl_or_b32 v8, v47, 9, v203
	global_load_dwordx4 v[28:31], v8, s[46:47]
	s_nop 0
	global_load_dwordx4 v[8:11], v8, s[46:47] offset:256
	v_mov_b32_e32 v34, v35
	s_waitcnt vmcnt(9)
	v_cvt_scalef32_pk_f32_fp4 v[46:47], v12, 1.0
	v_pk_fma_f32 v[44:45], v[46:47], v[34:35], v[44:45] op_sel_hi:[1,0,1]
	v_cvt_scalef32_pk_f32_fp4 v[46:47], v12, 1.0 op_sel:[1,0,0]
	v_pk_fma_f32 v[46:47], v[46:47], v[34:35], v[48:49] op_sel_hi:[1,0,1]
	v_cvt_scalef32_pk_f32_fp4 v[48:49], v12, 1.0 op_sel:[0,1,0]
	v_pk_fma_f32 v[48:49], v[48:49], v[34:35], v[50:51] op_sel_hi:[1,0,1]
	v_cvt_scalef32_pk_f32_fp4 v[50:51], v12, 1.0 op_sel:[1,1,0]
	v_pk_fma_f32 v[50:51], v[50:51], v[34:35], v[66:67] op_sel_hi:[1,0,1]
	v_cvt_scalef32_pk_f32_fp4 v[66:67], v13, 1.0
	v_pk_fma_f32 v[66:67], v[66:67], v[34:35], v[74:75] op_sel_hi:[1,0,1]
	v_cvt_scalef32_pk_f32_fp4 v[74:75], v13, 1.0 op_sel:[1,0,0]
	v_pk_fma_f32 v[74:75], v[74:75], v[34:35], v[82:83] op_sel_hi:[1,0,1]
	v_cvt_scalef32_pk_f32_fp4 v[82:83], v13, 1.0 op_sel:[0,1,0]
	v_cvt_scalef32_pk_f32_fp4 v[12:13], v13, 1.0 op_sel:[1,1,0]
	v_pk_fma_f32 v[12:13], v[12:13], v[34:35], v[94:95] op_sel_hi:[1,0,1]
	v_cvt_scalef32_pk_f32_fp4 v[94:95], v14, 1.0 op_sel:[0,1,0]
	v_pk_fma_f32 v[94:95], v[94:95], v[34:35], v[98:99] op_sel_hi:[1,0,1]
	v_cvt_scalef32_pk_f32_fp4 v[98:99], v15, 1.0
	v_pk_fma_f32 v[98:99], v[98:99], v[34:35], v[102:103] op_sel_hi:[1,0,1]
	v_cvt_scalef32_pk_f32_fp4 v[102:103], v15, 1.0 op_sel:[0,1,0]
	v_pk_fma_f32 v[52:53], v[102:103], v[34:35], v[52:53] op_sel_hi:[1,0,1]
	s_waitcnt vmcnt(8)
	v_cvt_scalef32_pk_f32_fp4 v[102:103], v4, 1.0
	v_pk_fma_f32 v[54:55], v[102:103], v[34:35], v[54:55] op_sel_hi:[1,0,1]
	v_cvt_scalef32_pk_f32_fp4 v[102:103], v4, 1.0 op_sel:[1,0,0]
	v_pk_fma_f32 v[56:57], v[102:103], v[34:35], v[56:57] op_sel_hi:[1,0,1]
	v_cvt_scalef32_pk_f32_fp4 v[102:103], v4, 1.0 op_sel:[0,1,0]
	v_pk_fma_f32 v[58:59], v[102:103], v[34:35], v[58:59] op_sel_hi:[1,0,1]
	v_cvt_scalef32_pk_f32_fp4 v[102:103], v4, 1.0 op_sel:[1,1,0]
	v_pk_fma_f32 v[60:61], v[102:103], v[34:35], v[60:61] op_sel_hi:[1,0,1]
	v_cvt_scalef32_pk_f32_fp4 v[102:103], v5, 1.0
	v_pk_fma_f32 v[62:63], v[102:103], v[34:35], v[62:63] op_sel_hi:[1,0,1]
	v_cvt_scalef32_pk_f32_fp4 v[102:103], v5, 1.0 op_sel:[1,0,0]
	v_pk_fma_f32 v[70:71], v[102:103], v[34:35], v[70:71] op_sel_hi:[1,0,1]
	v_cvt_scalef32_pk_f32_fp4 v[102:103], v5, 1.0 op_sel:[0,1,0]
	v_cvt_scalef32_pk_f32_fp4 v[4:5], v5, 1.0 op_sel:[1,1,0]
	v_pk_fma_f32 v[78:79], v[4:5], v[34:35], v[78:79] op_sel_hi:[1,0,1]
	v_cvt_scalef32_pk_f32_fp4 v[4:5], v6, 1.0
	v_pk_fma_f32 v[64:65], v[4:5], v[34:35], v[64:65] op_sel_hi:[1,0,1]
	v_cvt_scalef32_pk_f32_fp4 v[4:5], v6, 1.0 op_sel:[1,0,0]
	v_pk_fma_f32 v[72:73], v[4:5], v[34:35], v[72:73] op_sel_hi:[1,0,1]
	v_cvt_scalef32_pk_f32_fp4 v[4:5], v6, 1.0 op_sel:[0,1,0]
	v_pk_fma_f32 v[80:81], v[4:5], v[34:35], v[80:81] op_sel_hi:[1,0,1]
	v_cvt_scalef32_pk_f32_fp4 v[4:5], v6, 1.0 op_sel:[1,1,0]
	v_pk_fma_f32 v[82:83], v[82:83], v[34:35], v[90:91] op_sel_hi:[1,0,1]
	v_cvt_scalef32_pk_f32_fp4 v[90:91], v14, 1.0
	v_pk_fma_f32 v[84:85], v[4:5], v[34:35], v[84:85] op_sel_hi:[1,0,1]
	v_cvt_scalef32_pk_f32_fp4 v[4:5], v7, 1.0
	v_pk_fma_f32 v[68:69], v[90:91], v[34:35], v[68:69] op_sel_hi:[1,0,1]
	v_cvt_scalef32_pk_f32_fp4 v[90:91], v14, 1.0 op_sel:[1,0,0]
	v_pk_fma_f32 v[86:87], v[4:5], v[34:35], v[86:87] op_sel_hi:[1,0,1]
	v_cvt_scalef32_pk_f32_fp4 v[4:5], v7, 1.0 op_sel:[1,0,0]
	v_pk_fma_f32 v[90:91], v[90:91], v[34:35], v[96:97] op_sel_hi:[1,0,1]
	v_cvt_scalef32_pk_f32_fp4 v[96:97], v14, 1.0 op_sel:[1,1,0]
	v_pk_fma_f32 v[88:89], v[4:5], v[34:35], v[88:89] op_sel_hi:[1,0,1]
	v_cvt_scalef32_pk_f32_fp4 v[4:5], v7, 1.0 op_sel:[0,1,0]
	v_pk_fma_f32 v[96:97], v[96:97], v[34:35], v[100:101] op_sel_hi:[1,0,1]
	v_cvt_scalef32_pk_f32_fp4 v[100:101], v15, 1.0 op_sel:[1,0,0]
	v_cvt_scalef32_pk_f32_fp4 v[14:15], v15, 1.0 op_sel:[1,1,0]
	v_pk_fma_f32 v[92:93], v[4:5], v[34:35], v[92:93] op_sel_hi:[1,0,1]
	v_cvt_scalef32_pk_f32_fp4 v[4:5], v7, 1.0 op_sel:[1,1,0]
	v_pk_fma_f32 v[100:101], v[100:101], v[34:35], v[104:105] op_sel_hi:[1,0,1]
	v_pk_fma_f32 v[14:15], v[14:15], v[34:35], v[106:107] op_sel_hi:[1,0,1]
	v_pk_fma_f32 v[76:77], v[102:103], v[34:35], v[76:77] op_sel_hi:[1,0,1]
	v_pk_fma_f32 v[32:33], v[4:5], v[34:35], v[32:33] op_sel_hi:[1,0,1]
	ds_read_b128 v[4:7], v204 offset:4592
	s_waitcnt vmcnt(7)
	v_cvt_scalef32_pk_f32_fp4 v[34:35], v24, 1.0
	v_cvt_scalef32_pk_f32_fp4 v[102:103], v24, 1.0 op_sel:[1,0,0]
	v_cvt_scalef32_pk_f32_fp4 v[104:105], v24, 1.0 op_sel:[0,1,0]
	s_waitcnt lgkmcnt(0)
	v_pk_fma_f32 v[34:35], v[34:35], v[4:5], v[44:45] op_sel_hi:[1,0,1]
	v_pk_fma_f32 v[44:45], v[102:103], v[4:5], v[46:47] op_sel_hi:[1,0,1]
	v_pk_fma_f32 v[46:47], v[104:105], v[4:5], v[48:49] op_sel_hi:[1,0,1]
	v_cvt_scalef32_pk_f32_fp4 v[48:49], v24, 1.0 op_sel:[1,1,0]
	v_pk_fma_f32 v[48:49], v[48:49], v[4:5], v[50:51] op_sel_hi:[1,0,1]
	v_cvt_scalef32_pk_f32_fp4 v[50:51], v25, 1.0
	v_pk_fma_f32 v[50:51], v[50:51], v[4:5], v[66:67] op_sel_hi:[1,0,1]
	v_cvt_scalef32_pk_f32_fp4 v[66:67], v25, 1.0 op_sel:[1,0,0]
	v_pk_fma_f32 v[66:67], v[66:67], v[4:5], v[74:75] op_sel_hi:[1,0,1]
	v_cvt_scalef32_pk_f32_fp4 v[74:75], v25, 1.0 op_sel:[0,1,0]
	v_cvt_scalef32_pk_f32_fp4 v[24:25], v25, 1.0 op_sel:[1,1,0]
	v_pk_fma_f32 v[12:13], v[24:25], v[4:5], v[12:13] op_sel_hi:[1,0,1]
	v_cvt_scalef32_pk_f32_fp4 v[24:25], v26, 1.0
	v_pk_fma_f32 v[74:75], v[74:75], v[4:5], v[82:83] op_sel_hi:[1,0,1]
	v_pk_fma_f32 v[24:25], v[24:25], v[4:5], v[68:69] op_sel_hi:[1,0,1]
	v_cvt_scalef32_pk_f32_fp4 v[68:69], v26, 1.0 op_sel:[1,0,0]
	v_cvt_scalef32_pk_f32_fp4 v[82:83], v26, 1.0 op_sel:[0,1,0]
	v_pk_fma_f32 v[68:69], v[68:69], v[4:5], v[90:91] op_sel_hi:[1,0,1]
	v_pk_fma_f32 v[82:83], v[82:83], v[4:5], v[94:95] op_sel_hi:[1,0,1]
	v_cvt_scalef32_pk_f32_fp4 v[90:91], v26, 1.0 op_sel:[1,1,0]
	v_cvt_scalef32_pk_f32_fp4 v[94:95], v27, 1.0
	v_pk_fma_f32 v[90:91], v[90:91], v[4:5], v[96:97] op_sel_hi:[1,0,1]
	v_pk_fma_f32 v[94:95], v[94:95], v[4:5], v[98:99] op_sel_hi:[1,0,1]
	v_cvt_scalef32_pk_f32_fp4 v[96:97], v27, 1.0 op_sel:[1,0,0]
	v_cvt_scalef32_pk_f32_fp4 v[98:99], v27, 1.0 op_sel:[0,1,0]
	v_cvt_scalef32_pk_f32_fp4 v[26:27], v27, 1.0 op_sel:[1,1,0]
	v_pk_fma_f32 v[14:15], v[26:27], v[4:5], v[14:15] op_sel_hi:[1,0,1]
	s_waitcnt vmcnt(6)
	v_cvt_scalef32_pk_f32_fp4 v[26:27], v0, 1.0
	v_pk_fma_f32 v[26:27], v[26:27], v[4:5], v[54:55] op_sel_hi:[1,0,1]
	v_cvt_scalef32_pk_f32_fp4 v[54:55], v0, 1.0 op_sel:[1,0,0]
	v_pk_fma_f32 v[54:55], v[54:55], v[4:5], v[56:57] op_sel_hi:[1,0,1]
	v_cvt_scalef32_pk_f32_fp4 v[56:57], v0, 1.0 op_sel:[0,1,0]
	v_pk_fma_f32 v[56:57], v[56:57], v[4:5], v[58:59] op_sel_hi:[1,0,1]
	v_cvt_scalef32_pk_f32_fp4 v[58:59], v0, 1.0 op_sel:[1,1,0]
	v_pk_fma_f32 v[58:59], v[58:59], v[4:5], v[60:61] op_sel_hi:[1,0,1]
	v_cvt_scalef32_pk_f32_fp4 v[60:61], v1, 1.0
	v_pk_fma_f32 v[60:61], v[60:61], v[4:5], v[62:63] op_sel_hi:[1,0,1]
	v_cvt_scalef32_pk_f32_fp4 v[62:63], v1, 1.0 op_sel:[1,0,0]
	v_pk_fma_f32 v[62:63], v[62:63], v[4:5], v[70:71] op_sel_hi:[1,0,1]
	v_cvt_scalef32_pk_f32_fp4 v[70:71], v1, 1.0 op_sel:[0,1,0]
	v_pk_fma_f32 v[70:71], v[70:71], v[4:5], v[76:77] op_sel_hi:[1,0,1]
	v_cvt_scalef32_pk_f32_fp4 v[76:77], v2, 1.0
	v_pk_fma_f32 v[64:65], v[76:77], v[4:5], v[64:65] op_sel_hi:[1,0,1]
	v_cvt_scalef32_pk_f32_fp4 v[76:77], v2, 1.0 op_sel:[1,0,0]
	v_cvt_scalef32_pk_f32_fp4 v[0:1], v1, 1.0 op_sel:[1,1,0]
	v_pk_fma_f32 v[72:73], v[76:77], v[4:5], v[72:73] op_sel_hi:[1,0,1]
	v_cvt_scalef32_pk_f32_fp4 v[76:77], v2, 1.0 op_sel:[0,1,0]
	v_pk_fma_f32 v[0:1], v[0:1], v[4:5], v[78:79] op_sel_hi:[1,0,1]
	v_pk_fma_f32 v[76:77], v[76:77], v[4:5], v[80:81] op_sel_hi:[1,0,1]
	v_cvt_scalef32_pk_f32_fp4 v[78:79], v2, 1.0 op_sel:[1,1,0]
	v_cvt_scalef32_pk_f32_fp4 v[80:81], v3, 1.0
	v_pk_fma_f32 v[78:79], v[78:79], v[4:5], v[84:85] op_sel_hi:[1,0,1]
	v_pk_fma_f32 v[80:81], v[80:81], v[4:5], v[86:87] op_sel_hi:[1,0,1]
	v_cvt_scalef32_pk_f32_fp4 v[84:85], v3, 1.0 op_sel:[1,0,0]
	v_cvt_scalef32_pk_f32_fp4 v[86:87], v3, 1.0 op_sel:[0,1,0]
	v_cvt_scalef32_pk_f32_fp4 v[2:3], v3, 1.0 op_sel:[1,1,0]
	v_pk_fma_f32 v[96:97], v[96:97], v[4:5], v[100:101] op_sel_hi:[1,0,1]
	v_pk_fma_f32 v[52:53], v[98:99], v[4:5], v[52:53] op_sel_hi:[1,0,1]
	v_pk_fma_f32 v[84:85], v[84:85], v[4:5], v[88:89] op_sel_hi:[1,0,1]
	v_pk_fma_f32 v[86:87], v[86:87], v[4:5], v[92:93] op_sel_hi:[1,0,1]
	v_pk_fma_f32 v[2:3], v[2:3], v[4:5], v[32:33] op_sel_hi:[1,0,1]
	s_waitcnt vmcnt(5)
	v_cvt_scalef32_pk_f32_fp4 v[32:33], v36, 1.0
	v_pk_fma_f32 v[32:33], v[32:33], v[4:5], v[34:35] op_sel:[0,1,0]
	v_cvt_scalef32_pk_f32_fp4 v[34:35], v36, 1.0 op_sel:[1,0,0]
	v_pk_fma_f32 v[34:35], v[34:35], v[4:5], v[44:45] op_sel:[0,1,0]
	v_cvt_scalef32_pk_f32_fp4 v[44:45], v36, 1.0 op_sel:[0,1,0]
	v_pk_fma_f32 v[44:45], v[44:45], v[4:5], v[46:47] op_sel:[0,1,0]
	v_cvt_scalef32_pk_f32_fp4 v[46:47], v36, 1.0 op_sel:[1,1,0]
	v_pk_fma_f32 v[46:47], v[46:47], v[4:5], v[48:49] op_sel:[0,1,0]
	v_cvt_scalef32_pk_f32_fp4 v[48:49], v37, 1.0
	v_pk_fma_f32 v[48:49], v[48:49], v[4:5], v[50:51] op_sel:[0,1,0]
	v_cvt_scalef32_pk_f32_fp4 v[50:51], v37, 1.0 op_sel:[1,0,0]
	v_pk_fma_f32 v[50:51], v[50:51], v[4:5], v[66:67] op_sel:[0,1,0]
	v_cvt_scalef32_pk_f32_fp4 v[66:67], v37, 1.0 op_sel:[0,1,0]
	v_cvt_scalef32_pk_f32_fp4 v[36:37], v37, 1.0 op_sel:[1,1,0]
	v_pk_fma_f32 v[12:13], v[36:37], v[4:5], v[12:13] op_sel:[0,1,0]
	v_cvt_scalef32_pk_f32_fp4 v[36:37], v38, 1.0
	v_pk_fma_f32 v[24:25], v[36:37], v[4:5], v[24:25] op_sel:[0,1,0]
	v_cvt_scalef32_pk_f32_fp4 v[36:37], v38, 1.0 op_sel:[1,0,0]
	v_pk_fma_f32 v[66:67], v[66:67], v[4:5], v[74:75] op_sel:[0,1,0]
	v_pk_fma_f32 v[36:37], v[36:37], v[4:5], v[68:69] op_sel:[0,1,0]
	v_cvt_scalef32_pk_f32_fp4 v[68:69], v38, 1.0 op_sel:[0,1,0]
	v_cvt_scalef32_pk_f32_fp4 v[74:75], v38, 1.0 op_sel:[1,1,0]
	v_pk_fma_f32 v[68:69], v[68:69], v[4:5], v[82:83] op_sel:[0,1,0]
	v_pk_fma_f32 v[74:75], v[74:75], v[4:5], v[90:91] op_sel:[0,1,0]
	v_cvt_scalef32_pk_f32_fp4 v[82:83], v39, 1.0
	v_cvt_scalef32_pk_f32_fp4 v[88:89], v39, 1.0 op_sel:[1,0,0]
	v_cvt_scalef32_pk_f32_fp4 v[90:91], v39, 1.0 op_sel:[0,1,0]
	v_cvt_scalef32_pk_f32_fp4 v[38:39], v39, 1.0 op_sel:[1,1,0]
	v_pk_fma_f32 v[14:15], v[38:39], v[4:5], v[14:15] op_sel:[0,1,0]
	s_waitcnt vmcnt(4)
	v_cvt_scalef32_pk_f32_fp4 v[38:39], v16, 1.0
	v_pk_fma_f32 v[26:27], v[38:39], v[4:5], v[26:27] op_sel:[0,1,0]
	v_cvt_scalef32_pk_f32_fp4 v[38:39], v16, 1.0 op_sel:[1,0,0]
	v_pk_fma_f32 v[38:39], v[38:39], v[4:5], v[54:55] op_sel:[0,1,0]
	v_cvt_scalef32_pk_f32_fp4 v[54:55], v16, 1.0 op_sel:[0,1,0]
	v_pk_fma_f32 v[54:55], v[54:55], v[4:5], v[56:57] op_sel:[0,1,0]
	v_cvt_scalef32_pk_f32_fp4 v[56:57], v16, 1.0 op_sel:[1,1,0]
	v_pk_fma_f32 v[56:57], v[56:57], v[4:5], v[58:59] op_sel:[0,1,0]
	v_cvt_scalef32_pk_f32_fp4 v[58:59], v17, 1.0
	v_pk_fma_f32 v[58:59], v[58:59], v[4:5], v[60:61] op_sel:[0,1,0]
	v_cvt_scalef32_pk_f32_fp4 v[60:61], v17, 1.0 op_sel:[1,0,0]
	v_pk_fma_f32 v[60:61], v[60:61], v[4:5], v[62:63] op_sel:[0,1,0]
	v_cvt_scalef32_pk_f32_fp4 v[62:63], v17, 1.0 op_sel:[0,1,0]
	v_cvt_scalef32_pk_f32_fp4 v[16:17], v17, 1.0 op_sel:[1,1,0]
	v_pk_fma_f32 v[0:1], v[16:17], v[4:5], v[0:1] op_sel:[0,1,0]
	v_cvt_scalef32_pk_f32_fp4 v[16:17], v18, 1.0
	v_pk_fma_f32 v[62:63], v[62:63], v[4:5], v[70:71] op_sel:[0,1,0]
	v_pk_fma_f32 v[16:17], v[16:17], v[4:5], v[64:65] op_sel:[0,1,0]
	v_cvt_scalef32_pk_f32_fp4 v[64:65], v18, 1.0 op_sel:[1,0,0]
	v_cvt_scalef32_pk_f32_fp4 v[70:71], v18, 1.0 op_sel:[0,1,0]
	v_pk_fma_f32 v[64:65], v[64:65], v[4:5], v[72:73] op_sel:[0,1,0]
	v_pk_fma_f32 v[70:71], v[70:71], v[4:5], v[76:77] op_sel:[0,1,0]
	v_cvt_scalef32_pk_f32_fp4 v[72:73], v18, 1.0 op_sel:[1,1,0]
	v_cvt_scalef32_pk_f32_fp4 v[76:77], v19, 1.0
	v_pk_fma_f32 v[72:73], v[72:73], v[4:5], v[78:79] op_sel:[0,1,0]
	v_pk_fma_f32 v[76:77], v[76:77], v[4:5], v[80:81] op_sel:[0,1,0]
	v_cvt_scalef32_pk_f32_fp4 v[78:79], v19, 1.0 op_sel:[1,0,0]
	v_cvt_scalef32_pk_f32_fp4 v[80:81], v19, 1.0 op_sel:[0,1,0]
	v_cvt_scalef32_pk_f32_fp4 v[18:19], v19, 1.0 op_sel:[1,1,0]
	v_pk_fma_f32 v[82:83], v[82:83], v[4:5], v[94:95] op_sel:[0,1,0]
	v_pk_fma_f32 v[88:89], v[88:89], v[4:5], v[96:97] op_sel:[0,1,0]
	v_pk_fma_f32 v[52:53], v[90:91], v[4:5], v[52:53] op_sel:[0,1,0]
	v_pk_fma_f32 v[78:79], v[78:79], v[4:5], v[84:85] op_sel:[0,1,0]
	v_pk_fma_f32 v[80:81], v[80:81], v[4:5], v[86:87] op_sel:[0,1,0]
	v_pk_fma_f32 v[2:3], v[18:19], v[4:5], v[2:3] op_sel:[0,1,0]
	s_waitcnt vmcnt(3)
	v_cvt_scalef32_pk_f32_fp4 v[4:5], v40, 1.0
	v_pk_fma_f32 v[4:5], v[4:5], v[6:7], v[32:33] op_sel_hi:[1,0,1]
	v_cvt_scalef32_pk_f32_fp4 v[18:19], v40, 1.0 op_sel:[1,0,0]
	v_cvt_scalef32_pk_f32_fp4 v[32:33], v40, 1.0 op_sel:[0,1,0]
	v_pk_fma_f32 v[18:19], v[18:19], v[6:7], v[34:35] op_sel_hi:[1,0,1]
	v_pk_fma_f32 v[32:33], v[32:33], v[6:7], v[44:45] op_sel_hi:[1,0,1]
	v_cvt_scalef32_pk_f32_fp4 v[34:35], v40, 1.0 op_sel:[1,1,0]
	v_cvt_scalef32_pk_f32_fp4 v[44:45], v41, 1.0
	v_pk_fma_f32 v[34:35], v[34:35], v[6:7], v[46:47] op_sel_hi:[1,0,1]
	v_pk_fma_f32 v[44:45], v[44:45], v[6:7], v[48:49] op_sel_hi:[1,0,1]
	v_cvt_scalef32_pk_f32_fp4 v[46:47], v41, 1.0 op_sel:[1,0,0]
	v_cvt_scalef32_pk_f32_fp4 v[48:49], v41, 1.0 op_sel:[0,1,0]
	v_cvt_scalef32_pk_f32_fp4 v[40:41], v41, 1.0 op_sel:[1,1,0]
	v_pk_fma_f32 v[12:13], v[40:41], v[6:7], v[12:13] op_sel_hi:[1,0,1]
	v_cvt_scalef32_pk_f32_fp4 v[40:41], v42, 1.0
	v_pk_fma_f32 v[24:25], v[40:41], v[6:7], v[24:25] op_sel_hi:[1,0,1]
	v_cvt_scalef32_pk_f32_fp4 v[40:41], v42, 1.0 op_sel:[1,0,0]
	v_pk_fma_f32 v[46:47], v[46:47], v[6:7], v[50:51] op_sel_hi:[1,0,1]
	v_pk_fma_f32 v[36:37], v[40:41], v[6:7], v[36:37] op_sel_hi:[1,0,1]
	v_cvt_scalef32_pk_f32_fp4 v[40:41], v42, 1.0 op_sel:[0,1,0]
	v_cvt_scalef32_pk_f32_fp4 v[50:51], v42, 1.0 op_sel:[1,1,0]
	v_pk_fma_f32 v[48:49], v[48:49], v[6:7], v[66:67] op_sel_hi:[1,0,1]
	v_pk_fma_f32 v[40:41], v[40:41], v[6:7], v[68:69] op_sel_hi:[1,0,1]
	v_pk_fma_f32 v[50:51], v[50:51], v[6:7], v[74:75] op_sel_hi:[1,0,1]
	v_cvt_scalef32_pk_f32_fp4 v[66:67], v43, 1.0
	v_cvt_scalef32_pk_f32_fp4 v[68:69], v43, 1.0 op_sel:[1,0,0]
	v_cvt_scalef32_pk_f32_fp4 v[74:75], v43, 1.0 op_sel:[0,1,0]
	v_cvt_scalef32_pk_f32_fp4 v[42:43], v43, 1.0 op_sel:[1,1,0]
	v_pk_fma_f32 v[14:15], v[42:43], v[6:7], v[14:15] op_sel_hi:[1,0,1]
	s_waitcnt vmcnt(2)
	v_cvt_scalef32_pk_f32_fp4 v[42:43], v20, 1.0
	v_pk_fma_f32 v[26:27], v[42:43], v[6:7], v[26:27] op_sel_hi:[1,0,1]
	v_cvt_scalef32_pk_f32_fp4 v[42:43], v20, 1.0 op_sel:[1,0,0]
	v_pk_fma_f32 v[38:39], v[42:43], v[6:7], v[38:39] op_sel_hi:[1,0,1]
	v_cvt_scalef32_pk_f32_fp4 v[42:43], v20, 1.0 op_sel:[0,1,0]
	v_pk_fma_f32 v[42:43], v[42:43], v[6:7], v[54:55] op_sel_hi:[1,0,1]
	v_cvt_scalef32_pk_f32_fp4 v[54:55], v20, 1.0 op_sel:[1,1,0]
	v_pk_fma_f32 v[54:55], v[54:55], v[6:7], v[56:57] op_sel_hi:[1,0,1]
	v_cvt_scalef32_pk_f32_fp4 v[56:57], v21, 1.0
	v_pk_fma_f32 v[56:57], v[56:57], v[6:7], v[58:59] op_sel_hi:[1,0,1]
	v_cvt_scalef32_pk_f32_fp4 v[58:59], v21, 1.0 op_sel:[1,0,0]
	v_pk_fma_f32 v[58:59], v[58:59], v[6:7], v[60:61] op_sel_hi:[1,0,1]
	v_cvt_scalef32_pk_f32_fp4 v[60:61], v21, 1.0 op_sel:[0,1,0]
	v_cvt_scalef32_pk_f32_fp4 v[20:21], v21, 1.0 op_sel:[1,1,0]
	v_pk_fma_f32 v[0:1], v[20:21], v[6:7], v[0:1] op_sel_hi:[1,0,1]
	v_cvt_scalef32_pk_f32_fp4 v[20:21], v22, 1.0
	v_pk_fma_f32 v[16:17], v[20:21], v[6:7], v[16:17] op_sel_hi:[1,0,1]
	v_cvt_scalef32_pk_f32_fp4 v[20:21], v22, 1.0 op_sel:[1,0,0]
	v_pk_fma_f32 v[60:61], v[60:61], v[6:7], v[62:63] op_sel_hi:[1,0,1]
	v_pk_fma_f32 v[20:21], v[20:21], v[6:7], v[64:65] op_sel_hi:[1,0,1]
	v_cvt_scalef32_pk_f32_fp4 v[62:63], v22, 1.0 op_sel:[0,1,0]
	v_cvt_scalef32_pk_f32_fp4 v[64:65], v22, 1.0 op_sel:[1,1,0]
	v_pk_fma_f32 v[52:53], v[74:75], v[6:7], v[52:53] op_sel_hi:[1,0,1]
	v_pk_fma_f32 v[62:63], v[62:63], v[6:7], v[70:71] op_sel_hi:[1,0,1]
	v_pk_fma_f32 v[64:65], v[64:65], v[6:7], v[72:73] op_sel_hi:[1,0,1]
	v_cvt_scalef32_pk_f32_fp4 v[70:71], v23, 1.0
	v_cvt_scalef32_pk_f32_fp4 v[72:73], v23, 1.0 op_sel:[1,0,0]
	v_cvt_scalef32_pk_f32_fp4 v[74:75], v23, 1.0 op_sel:[0,1,0]
	v_cvt_scalef32_pk_f32_fp4 v[22:23], v23, 1.0 op_sel:[1,1,0]
	v_pk_fma_f32 v[66:67], v[66:67], v[6:7], v[82:83] op_sel_hi:[1,0,1]
	v_pk_fma_f32 v[68:69], v[68:69], v[6:7], v[88:89] op_sel_hi:[1,0,1]
	v_pk_fma_f32 v[70:71], v[70:71], v[6:7], v[76:77] op_sel_hi:[1,0,1]
	v_pk_fma_f32 v[72:73], v[72:73], v[6:7], v[78:79] op_sel_hi:[1,0,1]
	v_pk_fma_f32 v[74:75], v[74:75], v[6:7], v[80:81] op_sel_hi:[1,0,1]
	v_pk_fma_f32 v[2:3], v[22:23], v[6:7], v[2:3] op_sel_hi:[1,0,1]
	v_mov_b32_e32 v6, v7
	s_waitcnt vmcnt(1)
	v_cvt_scalef32_pk_f32_fp4 v[22:23], v28, 1.0
	v_pk_fma_f32 v[76:77], v[22:23], v[6:7], v[4:5] op_sel_hi:[1,0,1]
	v_cvt_scalef32_pk_f32_fp4 v[4:5], v28, 1.0 op_sel:[1,0,0]
	v_pk_fma_f32 v[78:79], v[4:5], v[6:7], v[18:19] op_sel_hi:[1,0,1]
	v_cvt_scalef32_pk_f32_fp4 v[4:5], v28, 1.0 op_sel:[0,1,0]
	v_pk_fma_f32 v[32:33], v[4:5], v[6:7], v[32:33] op_sel_hi:[1,0,1]
	v_cvt_scalef32_pk_f32_fp4 v[4:5], v28, 1.0 op_sel:[1,1,0]
	v_pk_fma_f32 v[34:35], v[4:5], v[6:7], v[34:35] op_sel_hi:[1,0,1]
	v_cvt_scalef32_pk_f32_fp4 v[4:5], v29, 1.0
	v_pk_fma_f32 v[44:45], v[4:5], v[6:7], v[44:45] op_sel_hi:[1,0,1]
	v_cvt_scalef32_pk_f32_fp4 v[4:5], v29, 1.0 op_sel:[1,0,0]
	v_pk_fma_f32 v[46:47], v[4:5], v[6:7], v[46:47] op_sel_hi:[1,0,1]
	v_cvt_scalef32_pk_f32_fp4 v[4:5], v29, 1.0 op_sel:[0,1,0]
	v_pk_fma_f32 v[48:49], v[4:5], v[6:7], v[48:49] op_sel_hi:[1,0,1]
	v_cvt_scalef32_pk_f32_fp4 v[4:5], v29, 1.0 op_sel:[1,1,0]
	v_pk_fma_f32 v[28:29], v[4:5], v[6:7], v[12:13] op_sel_hi:[1,0,1]
	v_cvt_scalef32_pk_f32_fp4 v[4:5], v30, 1.0
	v_pk_fma_f32 v[80:81], v[4:5], v[6:7], v[24:25] op_sel_hi:[1,0,1]
	v_cvt_scalef32_pk_f32_fp4 v[4:5], v30, 1.0 op_sel:[1,0,0]
	v_pk_fma_f32 v[36:37], v[4:5], v[6:7], v[36:37] op_sel_hi:[1,0,1]
	v_cvt_scalef32_pk_f32_fp4 v[4:5], v30, 1.0 op_sel:[0,1,0]
	v_pk_fma_f32 v[40:41], v[4:5], v[6:7], v[40:41] op_sel_hi:[1,0,1]
	v_cvt_scalef32_pk_f32_fp4 v[4:5], v30, 1.0 op_sel:[1,1,0]
	v_pk_fma_f32 v[82:83], v[4:5], v[6:7], v[50:51] op_sel_hi:[1,0,1]
	v_cvt_scalef32_pk_f32_fp4 v[4:5], v31, 1.0
	v_pk_fma_f32 v[84:85], v[4:5], v[6:7], v[66:67] op_sel_hi:[1,0,1]
	v_cvt_scalef32_pk_f32_fp4 v[4:5], v31, 1.0 op_sel:[1,0,0]
	v_pk_fma_f32 v[86:87], v[4:5], v[6:7], v[68:69] op_sel_hi:[1,0,1]
	v_cvt_scalef32_pk_f32_fp4 v[4:5], v31, 1.0 op_sel:[0,1,0]
	v_pk_fma_f32 v[88:89], v[4:5], v[6:7], v[52:53] op_sel_hi:[1,0,1]
	v_cvt_scalef32_pk_f32_fp4 v[4:5], v31, 1.0 op_sel:[1,1,0]
	v_pk_fma_f32 v[30:31], v[4:5], v[6:7], v[14:15] op_sel_hi:[1,0,1]
	s_waitcnt vmcnt(0)
	v_cvt_scalef32_pk_f32_fp4 v[4:5], v8, 1.0
	v_pk_fma_f32 v[26:27], v[4:5], v[6:7], v[26:27] op_sel_hi:[1,0,1]
	v_cvt_scalef32_pk_f32_fp4 v[4:5], v8, 1.0 op_sel:[1,0,0]
	v_pk_fma_f32 v[90:91], v[4:5], v[6:7], v[38:39] op_sel_hi:[1,0,1]
	v_cvt_scalef32_pk_f32_fp4 v[4:5], v8, 1.0 op_sel:[0,1,0]
	v_pk_fma_f32 v[92:93], v[4:5], v[6:7], v[42:43] op_sel_hi:[1,0,1]
	v_cvt_scalef32_pk_f32_fp4 v[4:5], v8, 1.0 op_sel:[1,1,0]
	v_pk_fma_f32 v[94:95], v[4:5], v[6:7], v[54:55] op_sel_hi:[1,0,1]
	v_cvt_scalef32_pk_f32_fp4 v[4:5], v9, 1.0
	v_pk_fma_f32 v[96:97], v[4:5], v[6:7], v[56:57] op_sel_hi:[1,0,1]
	v_cvt_scalef32_pk_f32_fp4 v[4:5], v9, 1.0 op_sel:[1,0,0]
	v_pk_fma_f32 v[98:99], v[4:5], v[6:7], v[58:59] op_sel_hi:[1,0,1]
	v_cvt_scalef32_pk_f32_fp4 v[4:5], v9, 1.0 op_sel:[0,1,0]
	v_pk_fma_f32 v[100:101], v[4:5], v[6:7], v[60:61] op_sel_hi:[1,0,1]
	v_cvt_scalef32_pk_f32_fp4 v[4:5], v9, 1.0 op_sel:[1,1,0]
	v_pk_fma_f32 v[102:103], v[4:5], v[6:7], v[0:1] op_sel_hi:[1,0,1]
	v_cvt_scalef32_pk_f32_fp4 v[0:1], v10, 1.0
	v_pk_fma_f32 v[104:105], v[0:1], v[6:7], v[16:17] op_sel_hi:[1,0,1]
	v_cvt_scalef32_pk_f32_fp4 v[0:1], v10, 1.0 op_sel:[1,0,0]
	v_pk_fma_f32 v[106:107], v[0:1], v[6:7], v[20:21] op_sel_hi:[1,0,1]
	v_cvt_scalef32_pk_f32_fp4 v[0:1], v10, 1.0 op_sel:[0,1,0]
	v_pk_fma_f32 v[108:109], v[0:1], v[6:7], v[62:63] op_sel_hi:[1,0,1]
	v_cvt_scalef32_pk_f32_fp4 v[0:1], v10, 1.0 op_sel:[1,1,0]
	v_pk_fma_f32 v[110:111], v[0:1], v[6:7], v[64:65] op_sel_hi:[1,0,1]
	v_cvt_scalef32_pk_f32_fp4 v[0:1], v11, 1.0
	v_pk_fma_f32 v[112:113], v[0:1], v[6:7], v[70:71] op_sel_hi:[1,0,1]
	v_cvt_scalef32_pk_f32_fp4 v[0:1], v11, 1.0 op_sel:[1,0,0]
	v_pk_fma_f32 v[114:115], v[0:1], v[6:7], v[72:73] op_sel_hi:[1,0,1]
	v_cvt_scalef32_pk_f32_fp4 v[0:1], v11, 1.0 op_sel:[0,1,0]
	v_pk_fma_f32 v[74:75], v[0:1], v[6:7], v[74:75] op_sel_hi:[1,0,1]
	v_cvt_scalef32_pk_f32_fp4 v[0:1], v11, 1.0 op_sel:[1,1,0]
	v_pk_fma_f32 v[116:117], v[0:1], v[6:7], v[2:3] op_sel_hi:[1,0,1]
	v_mbcnt_lo_u32_b32 v0, -1, 0
	v_mbcnt_hi_u32_b32 v0, -1, v0
	v_mbcnt_lo_u32_b32 v2, -1, 0
	v_mbcnt_hi_u32_b32 v2, -1, v2
	s_add_i32 s55, s55, s56
	v_ashrrev_i32_e32 v0, 4, v0
	v_add_u32_e32 v4, s64, v0
	v_ashrrev_i32_e32 v5, 31, v4
	v_lshlrev_b64 v[0:1], 11, v[4:5]
	v_lshlrev_b32_e32 v2, 5, v2
	v_lshl_add_u64 v[0:1], s[52:53], 0, v[0:1]
	v_and_b32_e32 v132, 0x1e0, v2
	v_lshl_add_u64 v[38:39], v[0:1], 0, v[132:133]
	global_load_dwordx4 v[0:3], v[38:39], off
	global_load_dwordx4 v[6:9], v[38:39], off offset:16
	global_load_dwordx4 v[10:13], v[38:39], off offset:512
	global_load_dwordx4 v[14:17], v[38:39], off offset:528
	global_load_dwordx4 v[18:21], v[38:39], off offset:1024
	global_load_dwordx4 v[22:25], v[38:39], off offset:1040
	global_load_dwordx4 v[66:69], v[38:39], off offset:1536
	global_load_dwordx4 v[70:73], v[38:39], off offset:1552
	v_lshlrev_b64 v[4:5], 12, v[4:5]
	v_lshl_add_u64 v[4:5], s[76:77], 0, v[4:5]
	s_add_i32 s57, s57, 1
	s_cmpk_gt_i32 s55, 0x1fff
	s_waitcnt vmcnt(7)
	v_lshlrev_b32_e32 v38, 16, v0
	v_and_b32_e32 v39, 0xffff0000, v0
	v_lshlrev_b32_e32 v0, 16, v1
	v_and_b32_e32 v1, 0xffff0000, v1
	v_lshlrev_b32_e32 v42, 16, v2
	v_and_b32_e32 v43, 0xffff0000, v2
	s_waitcnt vmcnt(5)
	v_lshlrev_b32_e32 v120, 16, v12
	v_and_b32_e32 v121, 0xffff0000, v12
	v_lshlrev_b32_e32 v12, 16, v13
	v_and_b32_e32 v13, 0xffff0000, v13
	v_pk_add_f32 v[62:63], v[78:79], v[0:1]
	s_waitcnt vmcnt(1)
	v_lshlrev_b32_e32 v0, 16, v66
	v_and_b32_e32 v1, 0xffff0000, v66
	v_lshlrev_b32_e32 v2, 16, v3
	v_and_b32_e32 v3, 0xffff0000, v3
	v_lshlrev_b32_e32 v124, 16, v16
	v_and_b32_e32 v125, 0xffff0000, v16
	v_lshlrev_b32_e32 v16, 16, v17
	v_and_b32_e32 v17, 0xffff0000, v17
	v_pk_add_f32 v[60:61], v[32:33], v[42:43]
	v_pk_add_f32 v[42:43], v[82:83], v[12:13]
	v_pk_add_f32 v[12:13], v[104:105], v[0:1]
	v_lshlrev_b32_e32 v0, 16, v67
	v_and_b32_e32 v1, 0xffff0000, v67
	v_lshlrev_b32_e32 v50, 16, v6
	v_and_b32_e32 v51, 0xffff0000, v6
	v_lshlrev_b32_e32 v52, 16, v8
	v_and_b32_e32 v53, 0xffff0000, v8
	v_lshlrev_b32_e32 v8, 16, v9
	v_and_b32_e32 v9, 0xffff0000, v9
	v_pk_add_f32 v[58:59], v[34:35], v[2:3]
	v_pk_add_f32 v[34:35], v[30:31], v[16:17]
	v_pk_add_f32 v[16:17], v[106:107], v[0:1]
	v_lshlrev_b32_e32 v0, 16, v68
	v_and_b32_e32 v1, 0xffff0000, v68
	v_lshlrev_b32_e32 v122, 16, v14
	v_and_b32_e32 v123, 0xffff0000, v14
	v_lshlrev_b32_e32 v14, 16, v15
	v_and_b32_e32 v15, 0xffff0000, v15
	v_pk_add_f32 v[56:57], v[44:45], v[50:51]
	v_pk_add_f32 v[50:51], v[28:29], v[8:9]
	v_pk_add_f32 v[8:9], v[108:109], v[0:1]
	v_lshlrev_b32_e32 v0, 16, v69
	v_and_b32_e32 v1, 0xffff0000, v69
	v_lshlrev_b32_e32 v6, 16, v7
	v_and_b32_e32 v7, 0xffff0000, v7
	v_pk_add_f32 v[64:65], v[76:77], v[38:39]
	v_pk_add_f32 v[38:39], v[86:87], v[14:15]
	v_pk_add_f32 v[14:15], v[110:111], v[0:1]
	s_waitcnt vmcnt(0)
	v_lshlrev_b32_e32 v0, 16, v70
	v_and_b32_e32 v1, 0xffff0000, v70
	v_lshlrev_b32_e32 v118, 16, v10
	v_and_b32_e32 v119, 0xffff0000, v10
	v_lshlrev_b32_e32 v10, 16, v11
	v_and_b32_e32 v11, 0xffff0000, v11
	v_pk_add_f32 v[54:55], v[46:47], v[6:7]
	v_pk_add_f32 v[6:7], v[112:113], v[0:1]
	v_lshlrev_b32_e32 v0, 16, v71
	v_and_b32_e32 v1, 0xffff0000, v71
	v_mov_b32_e32 v68, v9
	v_mov_b32_e32 v69, v15
	v_pk_add_f32 v[46:47], v[36:37], v[10:11]
	v_pk_add_f32 v[10:11], v[114:115], v[0:1]
	v_mov_b32_e32 v66, v8
	v_mov_b32_e32 v67, v14
	v_pk_mul_f32 v[68:69], v[68:69], v[68:69]
	v_pk_add_f32 v[44:45], v[40:41], v[120:121]
	v_pk_add_f32 v[40:41], v[84:85], v[122:123]
	v_pk_fma_f32 v[122:123], v[66:67], v[66:67], v[68:69]
	v_mov_b32_e32 v68, v7
	v_mov_b32_e32 v69, v11
	v_lshlrev_b32_e32 v130, 16, v22
	v_and_b32_e32 v131, 0xffff0000, v22
	v_mov_b32_e32 v66, v6
	v_mov_b32_e32 v67, v10
	v_pk_mul_f32 v[68:69], v[68:69], v[68:69]
	v_lshlrev_b32_e32 v138, 16, v24
	v_and_b32_e32 v139, 0xffff0000, v24
	v_lshlrev_b32_e32 v140, 16, v25
	v_and_b32_e32 v141, 0xffff0000, v25
	v_pk_add_f32 v[36:37], v[88:89], v[124:125]
	v_pk_add_f32 v[24:25], v[96:97], v[130:131]
	v_pk_fma_f32 v[124:125], v[66:67], v[66:67], v[68:69]
	v_mbcnt_lo_u32_b32 v130, -1, 0
	v_mbcnt_hi_u32_b32 v130, -1, v130
	global_load_dwordx4 v[66:69], v[134:135], off
	global_load_dwordx4 v[142:145], v[134:135], off offset:16
	global_load_dwordx4 v[146:149], v[134:135], off offset:32
	global_load_dwordx4 v[150:153], v[134:135], off offset:48
	global_load_dwordx4 v[154:157], v[134:135], off offset:1024
	global_load_dwordx4 v[158:161], v[134:135], off offset:1040
	global_load_dwordx4 v[162:165], v[134:135], off offset:1056
	global_load_dwordx4 v[166:169], v[134:135], off offset:1072
	global_load_dwordx4 v[170:173], v[134:135], off offset:2048
	global_load_dwordx4 v[174:177], v[134:135], off offset:2064
	global_load_dwordx4 v[178:181], v[134:135], off offset:2080
	global_load_dwordx4 v[182:185], v[134:135], off offset:2096
	global_load_dwordx4 v[186:189], v[134:135], off offset:3072
	global_load_dwordx4 v[190:193], v[134:135], off offset:3088
	global_load_dwordx4 v[194:197], v[134:135], off offset:3104
	global_load_dwordx4 v[198:201], v[134:135], off offset:3120
	v_lshlrev_b32_e32 v0, 16, v72
	v_and_b32_e32 v1, 0xffff0000, v72
	v_lshlrev_b32_e32 v2, 16, v73
	v_and_b32_e32 v3, 0xffff0000, v73
	v_pk_mul_f32 v[70:71], v[64:65], v[64:65]
	v_pk_mul_f32 v[72:73], v[62:63], v[62:63]
	v_pk_add_f32 v[0:1], v[74:75], v[0:1]
	v_pk_mul_f32 v[74:75], v[60:61], v[60:61]
	v_add_f32_e32 v72, v72, v73
	v_add_f32_e32 v70, v70, v71
	v_pk_mul_f32 v[76:77], v[58:59], v[58:59]
	v_add_f32_e32 v70, v70, v72
	v_add_f32_e32 v71, v74, v75
	v_pk_mul_f32 v[78:79], v[56:57], v[56:57]
	v_add_f32_e32 v70, v70, v71
	v_add_f32_e32 v71, v76, v77
	v_pk_add_f32 v[52:53], v[48:49], v[52:53]
	v_pk_add_f32 v[48:49], v[80:81], v[118:119]
	v_pk_mul_f32 v[80:81], v[54:55], v[54:55]
	v_add_f32_e32 v70, v70, v71
	v_add_f32_e32 v71, v78, v79
	v_pk_mul_f32 v[82:83], v[52:53], v[52:53]
	v_add_f32_e32 v70, v70, v71
	v_add_f32_e32 v71, v80, v81
	v_pk_mul_f32 v[84:85], v[50:51], v[50:51]
	v_add_f32_e32 v70, v70, v71
	v_add_f32_e32 v71, v82, v83
	v_pk_mul_f32 v[86:87], v[48:49], v[48:49]
	v_add_f32_e32 v70, v70, v71
	v_add_f32_e32 v71, v84, v85
	v_lshlrev_b32_e32 v126, 16, v18
	v_and_b32_e32 v127, 0xffff0000, v18
	v_lshlrev_b32_e32 v18, 16, v19
	v_and_b32_e32 v19, 0xffff0000, v19
	v_pk_mul_f32 v[88:89], v[46:47], v[46:47]
	v_add_f32_e32 v70, v70, v71
	v_add_f32_e32 v71, v86, v87
	v_lshlrev_b32_e32 v128, 16, v20
	v_and_b32_e32 v129, 0xffff0000, v20
	v_pk_add_f32 v[30:31], v[90:91], v[18:19]
	v_pk_mul_f32 v[90:91], v[44:45], v[44:45]
	v_add_f32_e32 v70, v70, v71
	v_add_f32_e32 v71, v88, v89
	v_lshlrev_b32_e32 v20, 16, v21
	v_and_b32_e32 v21, 0xffff0000, v21
	v_pk_add_f32 v[28:29], v[92:93], v[128:129]
	v_pk_mul_f32 v[92:93], v[42:43], v[42:43]
	v_add_f32_e32 v70, v70, v71
	v_add_f32_e32 v71, v90, v91
	v_pk_add_f32 v[32:33], v[26:27], v[126:127]
	v_pk_add_f32 v[26:27], v[94:95], v[20:21]
	v_pk_mul_f32 v[94:95], v[40:41], v[40:41]
	v_add_f32_e32 v70, v70, v71
	v_add_f32_e32 v71, v92, v93
	v_lshlrev_b32_e32 v22, 16, v23
	v_and_b32_e32 v23, 0xffff0000, v23
	v_pk_mul_f32 v[96:97], v[38:39], v[38:39]
	v_add_f32_e32 v70, v70, v71
	v_add_f32_e32 v71, v94, v95
	v_pk_add_f32 v[22:23], v[98:99], v[22:23]
	v_pk_mul_f32 v[98:99], v[36:37], v[36:37]
	v_add_f32_e32 v70, v70, v71
	v_add_f32_e32 v71, v96, v97
	v_pk_add_f32 v[18:19], v[100:101], v[138:139]
	v_pk_mul_f32 v[100:101], v[34:35], v[34:35]
	v_add_f32_e32 v70, v70, v71
	v_add_f32_e32 v71, v98, v99
	v_pk_add_f32 v[20:21], v[102:103], v[140:141]
	v_pk_mul_f32 v[102:103], v[32:33], v[32:33]
	v_add_f32_e32 v70, v70, v71
	v_add_f32_e32 v71, v100, v101
	v_pk_mul_f32 v[104:105], v[30:31], v[30:31]
	v_add_f32_e32 v70, v70, v71
	v_add_f32_e32 v71, v102, v103
	v_pk_mul_f32 v[106:107], v[28:29], v[28:29]
	v_add_f32_e32 v70, v70, v71
	v_add_f32_e32 v71, v104, v105
	v_pk_mul_f32 v[108:109], v[26:27], v[26:27]
	v_add_f32_e32 v70, v70, v71
	v_add_f32_e32 v71, v106, v107
	v_pk_mul_f32 v[110:111], v[24:25], v[24:25]
	v_add_f32_e32 v70, v70, v71
	v_add_f32_e32 v71, v108, v109
	v_pk_mul_f32 v[112:113], v[22:23], v[22:23]
	v_add_f32_e32 v70, v70, v71
	v_add_f32_e32 v71, v110, v111
	v_pk_mul_f32 v[114:115], v[18:19], v[18:19]
	v_add_f32_e32 v70, v70, v71
	v_add_f32_e32 v71, v112, v113
	v_pk_add_f32 v[2:3], v[116:117], v[2:3]
	v_pk_mul_f32 v[116:117], v[20:21], v[20:21]
	v_add_f32_e32 v70, v70, v71
	v_add_f32_e32 v71, v114, v115
	v_pk_mul_f32 v[118:119], v[12:13], v[12:13]
	v_add_f32_e32 v70, v70, v71
	v_add_f32_e32 v71, v116, v117
	v_pk_mul_f32 v[120:121], v[16:17], v[16:17]
	v_add_f32_e32 v70, v70, v71
	v_add_f32_e32 v71, v118, v119
	v_add_f32_e32 v70, v70, v71
	v_add_f32_e32 v71, v120, v121
	v_add_f32_e32 v70, v70, v71
	v_add_f32_e32 v70, v70, v122
	v_mov_b32_e32 v128, v1
	v_mov_b32_e32 v129, v3
	v_add_f32_e32 v70, v70, v123
	v_mov_b32_e32 v126, v0
	v_mov_b32_e32 v127, v2
	v_pk_mul_f32 v[128:129], v[128:129], v[128:129]
	v_add_f32_e32 v70, v70, v124
	v_pk_fma_f32 v[126:127], v[126:127], v[126:127], v[128:129]
	v_add_f32_e32 v70, v70, v125
	v_add_f32_e32 v70, v70, v126
	v_add_f32_e32 v70, v70, v127
	s_nop 1
	v_add_f32_dpp v70, v70, v70 quad_perm:[1,0,3,2] row_mask:0xf bank_mask:0xf bound_ctrl:1
	s_nop 1
	v_add_f32_dpp v70, v70, v70 quad_perm:[2,3,0,1] row_mask:0xf bank_mask:0xf bound_ctrl:1
	s_nop 1
	v_add_f32_dpp v70, v70, v70 row_half_mirror row_mask:0xf bank_mask:0xf bound_ctrl:1
	s_nop 1
	v_add_f32_dpp v70, v70, v70 row_mirror row_mask:0xf bank_mask:0xf bound_ctrl:1
	v_fmamk_f32 v70, v70, 0x3a800000, v211
	v_mul_f32_e32 v71, 0x4b800000, v70
	v_cmp_gt_f32_e32 vcc, s63, v70
	s_nop 1
	v_cndmask_b32_e32 v70, v70, v71, vcc
	v_rsq_f32_e32 v70, v70
	s_nop 0
	v_mul_f32_e32 v71, 0x45800000, v70
	v_cndmask_b32_e32 v70, v70, v71, vcc
	v_lshlrev_b32_e32 v71, 6, v130
	v_and_b32_e32 v132, 0x3c0, v71
	v_lshl_add_u64 v[72:73], v[4:5], 0, v[132:133]
	s_waitcnt vmcnt(0)
	v_pk_mul_f32 v[64:65], v[64:65], v[70:71] op_sel_hi:[1,0]
	v_pk_mul_f32 v[62:63], v[62:63], v[70:71] op_sel_hi:[1,0]
	v_pk_mul_f32 v[66:67], v[66:67], v[64:65]
	v_pk_mul_f32 v[68:69], v[68:69], v[62:63]
	global_store_dwordx4 v[72:73], v[66:69], off
	v_pk_mul_f32 v[60:61], v[60:61], v[70:71] op_sel_hi:[1,0]
	v_pk_mul_f32 v[58:59], v[58:59], v[70:71] op_sel_hi:[1,0]
	v_pk_mul_f32 v[142:143], v[142:143], v[60:61]
	v_pk_mul_f32 v[144:145], v[144:145], v[58:59]
	global_store_dwordx4 v[72:73], v[142:145], off offset:16
	v_pk_mul_f32 v[56:57], v[56:57], v[70:71] op_sel_hi:[1,0]
	v_pk_mul_f32 v[54:55], v[54:55], v[70:71] op_sel_hi:[1,0]
	v_pk_mul_f32 v[146:147], v[146:147], v[56:57]
	v_pk_mul_f32 v[148:149], v[148:149], v[54:55]
	global_store_dwordx4 v[72:73], v[146:149], off offset:32
	v_pk_mul_f32 v[52:53], v[52:53], v[70:71] op_sel_hi:[1,0]
	v_pk_mul_f32 v[50:51], v[50:51], v[70:71] op_sel_hi:[1,0]
	v_pk_mul_f32 v[150:151], v[150:151], v[52:53]
	v_pk_mul_f32 v[152:153], v[152:153], v[50:51]
	global_store_dwordx4 v[72:73], v[150:153], off offset:48
	v_pk_mul_f32 v[48:49], v[48:49], v[70:71] op_sel_hi:[1,0]
	v_pk_mul_f32 v[46:47], v[46:47], v[70:71] op_sel_hi:[1,0]
	v_pk_mul_f32 v[154:155], v[154:155], v[48:49]
	v_pk_mul_f32 v[156:157], v[156:157], v[46:47]
	global_store_dwordx4 v[72:73], v[154:157], off offset:1024
	v_pk_mul_f32 v[44:45], v[44:45], v[70:71] op_sel_hi:[1,0]
	v_pk_mul_f32 v[42:43], v[42:43], v[70:71] op_sel_hi:[1,0]
	v_pk_mul_f32 v[158:159], v[158:159], v[44:45]
	v_pk_mul_f32 v[160:161], v[160:161], v[42:43]
	global_store_dwordx4 v[72:73], v[158:161], off offset:1040
	v_pk_mul_f32 v[40:41], v[40:41], v[70:71] op_sel_hi:[1,0]
	v_pk_mul_f32 v[38:39], v[38:39], v[70:71] op_sel_hi:[1,0]
	v_pk_mul_f32 v[162:163], v[162:163], v[40:41]
	v_pk_mul_f32 v[164:165], v[164:165], v[38:39]
	global_store_dwordx4 v[72:73], v[162:165], off offset:1056
	v_pk_mul_f32 v[36:37], v[36:37], v[70:71] op_sel_hi:[1,0]
	v_pk_mul_f32 v[34:35], v[34:35], v[70:71] op_sel_hi:[1,0]
	v_pk_mul_f32 v[166:167], v[166:167], v[36:37]
	v_pk_mul_f32 v[168:169], v[168:169], v[34:35]
	global_store_dwordx4 v[72:73], v[166:169], off offset:1072
	v_pk_mul_f32 v[32:33], v[32:33], v[70:71] op_sel_hi:[1,0]
	v_pk_mul_f32 v[30:31], v[30:31], v[70:71] op_sel_hi:[1,0]
	v_pk_mul_f32 v[170:171], v[170:171], v[32:33]
	v_pk_mul_f32 v[172:173], v[172:173], v[30:31]
	global_store_dwordx4 v[72:73], v[170:173], off offset:2048
	v_pk_mul_f32 v[28:29], v[28:29], v[70:71] op_sel_hi:[1,0]
	v_pk_mul_f32 v[26:27], v[26:27], v[70:71] op_sel_hi:[1,0]
	v_pk_mul_f32 v[174:175], v[174:175], v[28:29]
	v_pk_mul_f32 v[176:177], v[176:177], v[26:27]
	global_store_dwordx4 v[72:73], v[174:177], off offset:2064
	v_pk_mul_f32 v[24:25], v[24:25], v[70:71] op_sel_hi:[1,0]
	v_pk_mul_f32 v[22:23], v[22:23], v[70:71] op_sel_hi:[1,0]
	v_pk_mul_f32 v[178:179], v[178:179], v[24:25]
	v_pk_mul_f32 v[180:181], v[180:181], v[22:23]
	global_store_dwordx4 v[72:73], v[178:181], off offset:2080
	v_pk_mul_f32 v[18:19], v[18:19], v[70:71] op_sel_hi:[1,0]
	v_pk_mul_f32 v[20:21], v[20:21], v[70:71] op_sel_hi:[1,0]
	v_pk_mul_f32 v[182:183], v[182:183], v[18:19]
	v_pk_mul_f32 v[184:185], v[184:185], v[20:21]
	global_store_dwordx4 v[72:73], v[182:185], off offset:2096
	v_pk_mul_f32 v[12:13], v[12:13], v[70:71] op_sel_hi:[1,0]
	v_pk_mul_f32 v[16:17], v[16:17], v[70:71] op_sel_hi:[1,0]
	v_pk_mul_f32 v[186:187], v[186:187], v[12:13]
	v_pk_mul_f32 v[188:189], v[188:189], v[16:17]
	global_store_dwordx4 v[72:73], v[186:189], off offset:3072
	v_pk_mul_f32 v[8:9], v[8:9], v[70:71] op_sel_hi:[1,0]
	v_pk_mul_f32 v[14:15], v[14:15], v[70:71] op_sel_hi:[1,0]
	v_pk_mul_f32 v[190:191], v[190:191], v[8:9]
	v_pk_mul_f32 v[192:193], v[192:193], v[14:15]
	global_store_dwordx4 v[72:73], v[190:193], off offset:3088
	v_pk_mul_f32 v[6:7], v[6:7], v[70:71] op_sel_hi:[1,0]
	v_pk_mul_f32 v[10:11], v[10:11], v[70:71] op_sel_hi:[1,0]
	v_pk_mul_f32 v[194:195], v[194:195], v[6:7]
	v_pk_mul_f32 v[196:197], v[196:197], v[10:11]
	global_store_dwordx4 v[72:73], v[194:197], off offset:3104
	v_pk_mul_f32 v[0:1], v[0:1], v[70:71] op_sel_hi:[1,0]
	v_pk_mul_f32 v[2:3], v[2:3], v[70:71] op_sel_hi:[1,0]
	v_pk_mul_f32 v[198:199], v[198:199], v[0:1]
	v_pk_mul_f32 v[200:201], v[200:201], v[2:3]
	global_store_dwordx4 v[72:73], v[198:201], off offset:3120
	s_cbranch_scc0 .LBB0_1752
